# residual/rmsnorm/modulate phases: hand-written fast paths with non-temporal (nt) policy on the once-read row loads and the residual-stream stores
# speedup vs baseline: 1.0088x; 1.0088x over previous
.LBB0_119:
	s_or_b64 exec, exec, s[2:3]
	v_mov_b32_e32 v2, 0x3e500000
	s_barrier
	global_load_dwordx2 v[52:53], v2, s[52:53]
	global_load_dwordx2 v[54:55], v2, s[52:53] offset:16
	global_load_dwordx2 v[0:1], v2, s[52:53] offset:48
	s_add_u32 s62, s52, 0x2c800000
	s_addc_u32 s63, s53, 0
	s_add_u32 s42, s52, 0x3e500000
	s_addc_u32 s43, s53, 0
	s_add_u32 s44, s52, 0x3e500010
	s_load_dwordx2 s[58:59], s[0:1], 0x160
	s_addc_u32 s45, s53, 0
	s_add_u32 s34, s52, 0x3e500030
	v_mov_b32_e32 v3, v189
	s_addc_u32 s35, s53, 0
	s_mov_b32 s0, s33
	v_ashrrev_i32_e32 v2, 6, v3
	s_add_u32 s40, s52, 0x3d800000
	v_lshl_add_u32 v87, s0, 3, v2
	s_movk_i32 s1, 0x4200
	s_addc_u32 s41, s53, 0
	v_cmp_gt_i32_e32 vcc, s1, v87
	v_mbcnt_lo_u32_b32 v190, -1, 0
	s_and_saveexec_b64 s[2:3], vcc
	s_cbranch_execz .LBB0_122
	s_cmpk_lg_i32 s94, 0x800
	s_cbranch_scc1 .Lrm0_orig
	s_waitcnt vmcnt(0) lgkmcnt(0)
	v_and_b32_e32 v125, 63, v189
	v_lshrrev_b32_e32 v128, 6, v189
	v_lshlrev_b32_e32 v122, 4, v125
	v_lshlrev_b32_e32 v124, 3, v125
	v_readfirstlane_b32 s5, v128
	v_add_u32_e32 v123, 0x1000, v122
	v_mov_b32_e32 v125, 0
	v_mov_b32_e32 v126, 0x3a000000
	v_mov_b32_e32 v127, 0x358637bd
	s_lshl_b32 s8, s33, 3
	s_add_u32 s5, s5, s8
	s_add_u32 s8, s52, 0x3e500000
	s_addc_u32 s9, s53, 0
	global_load_dwordx2 v[130:131], v125, s[8:9] offset:0
	global_load_dwordx2 v[132:133], v125, s[8:9] offset:16
	global_load_dwordx2 v[134:135], v125, s[8:9] offset:48
	s_waitcnt vmcnt(0)
	s_mov_b32 s0, 0
	s_lshr_b32 s4, s5, 9
.Lrm0_coef:
	v_readfirstlane_b32 s8, v134
	v_readfirstlane_b32 s9, v135
	s_nop 4
	global_load_dwordx4 v[0:3], v122, s[8:9] offset:0
	global_load_dwordx4 v[4:7], v122, s[8:9] offset:1024
	global_load_dwordx4 v[8:11], v122, s[8:9] offset:2048
	global_load_dwordx4 v[12:15], v122, s[8:9] offset:3072
	global_load_dwordx4 v[16:19], v123, s[8:9] offset:0
	global_load_dwordx4 v[20:23], v123, s[8:9] offset:1024
	global_load_dwordx4 v[24:27], v123, s[8:9] offset:2048
	global_load_dwordx4 v[28:31], v123, s[8:9] offset:3072
	s_mul_i32 s8, s4, 0xc000
	s_add_u32 s8, s8, 0x3d802000
	s_add_u32 s8, s52, s8
	s_addc_u32 s9, s53, 0
	global_load_dwordx4 v[68:71], v122, s[8:9] offset:0
	global_load_dwordx4 v[72:75], v122, s[8:9] offset:1024
	global_load_dwordx4 v[76:79], v122, s[8:9] offset:2048
	global_load_dwordx4 v[80:83], v122, s[8:9] offset:3072
	global_load_dwordx4 v[84:87], v123, s[8:9] offset:0
	global_load_dwordx4 v[88:91], v123, s[8:9] offset:1024
	global_load_dwordx4 v[92:95], v123, s[8:9] offset:2048
	global_load_dwordx4 v[96:99], v123, s[8:9] offset:3072
	s_waitcnt vmcnt(0)
	v_pk_add_f32 v[68:69], v[68:69], 1.0 op_sel_hi:[1,0]
	v_pk_add_f32 v[70:71], v[70:71], 1.0 op_sel_hi:[1,0]
	v_pk_add_f32 v[72:73], v[72:73], 1.0 op_sel_hi:[1,0]
	v_pk_add_f32 v[74:75], v[74:75], 1.0 op_sel_hi:[1,0]
	v_pk_add_f32 v[76:77], v[76:77], 1.0 op_sel_hi:[1,0]
	v_pk_add_f32 v[78:79], v[78:79], 1.0 op_sel_hi:[1,0]
	v_pk_add_f32 v[80:81], v[80:81], 1.0 op_sel_hi:[1,0]
	v_pk_add_f32 v[82:83], v[82:83], 1.0 op_sel_hi:[1,0]
	v_pk_add_f32 v[84:85], v[84:85], 1.0 op_sel_hi:[1,0]
	v_pk_add_f32 v[86:87], v[86:87], 1.0 op_sel_hi:[1,0]
	v_pk_add_f32 v[88:89], v[88:89], 1.0 op_sel_hi:[1,0]
	v_pk_add_f32 v[90:91], v[90:91], 1.0 op_sel_hi:[1,0]
	v_pk_add_f32 v[92:93], v[92:93], 1.0 op_sel_hi:[1,0]
	v_pk_add_f32 v[94:95], v[94:95], 1.0 op_sel_hi:[1,0]
	v_pk_add_f32 v[96:97], v[96:97], 1.0 op_sel_hi:[1,0]
	v_pk_add_f32 v[98:99], v[98:99], 1.0 op_sel_hi:[1,0]
	v_pk_mul_f32 v[32:33], v[0:1], v[68:69]
	v_pk_mul_f32 v[34:35], v[2:3], v[70:71]
	v_pk_mul_f32 v[36:37], v[4:5], v[72:73]
	v_pk_mul_f32 v[38:39], v[6:7], v[74:75]
	v_pk_mul_f32 v[40:41], v[8:9], v[76:77]
	v_pk_mul_f32 v[42:43], v[10:11], v[78:79]
	v_pk_mul_f32 v[44:45], v[12:13], v[80:81]
	v_pk_mul_f32 v[46:47], v[14:15], v[82:83]
	v_pk_mul_f32 v[48:49], v[16:17], v[84:85]
	v_pk_mul_f32 v[50:51], v[18:19], v[86:87]
	v_pk_mul_f32 v[56:57], v[20:21], v[88:89]
	v_pk_mul_f32 v[58:59], v[22:23], v[90:91]
	v_pk_mul_f32 v[60:61], v[24:25], v[92:93]
	v_pk_mul_f32 v[62:63], v[26:27], v[94:95]
	v_pk_mul_f32 v[64:65], v[28:29], v[96:97]
	v_pk_mul_f32 v[66:67], v[30:31], v[98:99]
	s_mul_i32 s8, s4, 0xc000
	s_add_u32 s8, s8, 0x3d800000
	s_add_u32 s8, s52, s8
	s_addc_u32 s9, s53, 0
	global_load_dwordx4 v[68:71], v122, s[8:9] offset:0
	global_load_dwordx4 v[72:75], v122, s[8:9] offset:1024
	global_load_dwordx4 v[76:79], v122, s[8:9] offset:2048
	global_load_dwordx4 v[80:83], v122, s[8:9] offset:3072
	global_load_dwordx4 v[84:87], v123, s[8:9] offset:0
	global_load_dwordx4 v[88:91], v123, s[8:9] offset:1024
	global_load_dwordx4 v[92:95], v123, s[8:9] offset:2048
	global_load_dwordx4 v[96:99], v123, s[8:9] offset:3072
	s_cmp_lt_u32 s0, 16
	s_cbranch_scc0 .Lrm0_ctxrow
	s_lshr_b32 s1, s5, 9
	s_lshl_b32 s1, s1, 13
	s_and_b32 s8, s5, 0x1ff
	s_add_u32 s1, s1, s8
	s_add_u32 s8, s0, 0
	s_lshl_b32 s8, s8, 9
	s_add_u32 s1, s1, s8
	s_lshl_b32 s8, s1, 13
	v_readfirstlane_b32 s6, v130
	v_readfirstlane_b32 s7, v131
	s_nop 3
	s_add_u32 s6, s6, s8
	s_addc_u32 s7, s7, 0
	s_nop 1
	global_load_dwordx4 v[0:3], v122, s[6:7] offset:0 nt
	global_load_dwordx4 v[4:7], v122, s[6:7] offset:1024 nt
	global_load_dwordx4 v[8:11], v122, s[6:7] offset:2048 nt
	global_load_dwordx4 v[12:15], v122, s[6:7] offset:3072 nt
	global_load_dwordx4 v[16:19], v123, s[6:7] offset:0 nt
	global_load_dwordx4 v[20:23], v123, s[6:7] offset:1024 nt
	global_load_dwordx4 v[24:27], v123, s[6:7] offset:2048 nt
	global_load_dwordx4 v[28:31], v123, s[6:7] offset:3072 nt
.Lrm0_loop:
	s_lshr_b32 s1, s5, 9
	s_lshl_b32 s1, s1, 13
	s_and_b32 s8, s5, 0x1ff
	s_add_u32 s1, s1, s8
	s_add_u32 s8, s0, 0
	s_lshl_b32 s8, s8, 9
	s_add_u32 s1, s1, s8
	s_lshl_b32 s8, s1, 13
	s_lshl_b32 s8, s1, 12
	s_add_u32 s9, s8, 0x2c800000
	s_add_u32 s10, s52, s9
	s_addc_u32 s11, s53, 0
	s_lshr_b32 s1, s5, 9
	s_lshl_b32 s1, s1, 13
	s_and_b32 s8, s5, 0x1ff
	s_add_u32 s1, s1, s8
	s_add_u32 s8, s0, 1
	s_lshl_b32 s8, s8, 9
	s_add_u32 s1, s1, s8
	s_lshl_b32 s8, s1, 13
	v_readfirstlane_b32 s6, v130
	v_readfirstlane_b32 s7, v131
	s_nop 3
	s_add_u32 s6, s6, s8
	s_addc_u32 s7, s7, 0
	s_nop 1
	global_load_dwordx4 v[136:139], v122, s[6:7] offset:0 nt
	global_load_dwordx4 v[140:143], v122, s[6:7] offset:1024 nt
	global_load_dwordx4 v[144:147], v122, s[6:7] offset:2048 nt
	global_load_dwordx4 v[148:151], v122, s[6:7] offset:3072 nt
	global_load_dwordx4 v[152:155], v123, s[6:7] offset:0 nt
	global_load_dwordx4 v[156:159], v123, s[6:7] offset:1024 nt
	global_load_dwordx4 v[160:163], v123, s[6:7] offset:2048 nt
	global_load_dwordx4 v[164:167], v123, s[6:7] offset:3072 nt
	s_waitcnt vmcnt(8)
	v_pk_mul_f32 v[108:109], v[0:1], v[0:1]
	v_pk_mul_f32 v[110:111], v[2:3], v[2:3]
	v_pk_fma_f32 v[108:109], v[4:5], v[4:5], v[108:109]
	v_pk_fma_f32 v[110:111], v[6:7], v[6:7], v[110:111]
	v_pk_fma_f32 v[108:109], v[8:9], v[8:9], v[108:109]
	v_pk_fma_f32 v[110:111], v[10:11], v[10:11], v[110:111]
	v_pk_fma_f32 v[108:109], v[12:13], v[12:13], v[108:109]
	v_pk_fma_f32 v[110:111], v[14:15], v[14:15], v[110:111]
	v_pk_fma_f32 v[108:109], v[16:17], v[16:17], v[108:109]
	v_pk_fma_f32 v[110:111], v[18:19], v[18:19], v[110:111]
	v_pk_fma_f32 v[108:109], v[20:21], v[20:21], v[108:109]
	v_pk_fma_f32 v[110:111], v[22:23], v[22:23], v[110:111]
	v_pk_fma_f32 v[108:109], v[24:25], v[24:25], v[108:109]
	v_pk_fma_f32 v[110:111], v[26:27], v[26:27], v[110:111]
	v_pk_fma_f32 v[108:109], v[28:29], v[28:29], v[108:109]
	v_pk_fma_f32 v[110:111], v[30:31], v[30:31], v[110:111]
	v_pk_add_f32 v[108:109], v[108:109], v[110:111]
	s_nop 0
	v_add_f32_e32 v128, v108, v109
	s_nop 1
	v_add_f32_dpp v128, v128, v128 quad_perm:[1,0,3,2] row_mask:0xf bank_mask:0xf
	s_nop 1
	v_add_f32_dpp v128, v128, v128 quad_perm:[2,3,0,1] row_mask:0xf bank_mask:0xf
	s_nop 1
	v_add_f32_dpp v128, v128, v128 row_half_mirror row_mask:0xf bank_mask:0xf
	s_nop 1
	v_add_f32_dpp v128, v128, v128 row_mirror row_mask:0xf bank_mask:0xf
	s_nop 1
	v_add_f32_dpp v128, v128, v128 row_bcast:15 row_mask:0xa bank_mask:0xf
	s_nop 1
	v_add_f32_dpp v128, v128, v128 row_bcast:31 row_mask:0xc bank_mask:0xf
	s_nop 1
	v_readlane_b32 s8, v128, 63
	s_nop 3
	v_mov_b32_e32 v112, s8
	v_fma_f32 v112, v112, v126, v127
	v_rsq_f32_e32 v112, v112
	s_nop 1
	v_pk_mul_f32 v[100:101], v[0:1], v[112:113] op_sel_hi:[1,0]
	v_pk_fma_f32 v[100:101], v[100:101], v[32:33], v[68:69]
	v_cvt_pk_bf16_f32 v114, v100, v101
	v_pk_mul_f32 v[102:103], v[2:3], v[112:113] op_sel_hi:[1,0]
	v_pk_fma_f32 v[102:103], v[102:103], v[34:35], v[70:71]
	v_cvt_pk_bf16_f32 v115, v102, v103
	global_store_dwordx2 v124, v[114:115], s[10:11] offset:0
	v_pk_mul_f32 v[104:105], v[4:5], v[112:113] op_sel_hi:[1,0]
	v_pk_fma_f32 v[104:105], v[104:105], v[36:37], v[72:73]
	v_cvt_pk_bf16_f32 v116, v104, v105
	v_pk_mul_f32 v[106:107], v[6:7], v[112:113] op_sel_hi:[1,0]
	v_pk_fma_f32 v[106:107], v[106:107], v[38:39], v[74:75]
	v_cvt_pk_bf16_f32 v117, v106, v107
	global_store_dwordx2 v124, v[116:117], s[10:11] offset:512
	v_pk_mul_f32 v[100:101], v[8:9], v[112:113] op_sel_hi:[1,0]
	v_pk_fma_f32 v[100:101], v[100:101], v[40:41], v[76:77]
	v_cvt_pk_bf16_f32 v118, v100, v101
	v_pk_mul_f32 v[102:103], v[10:11], v[112:113] op_sel_hi:[1,0]
	v_pk_fma_f32 v[102:103], v[102:103], v[42:43], v[78:79]
	v_cvt_pk_bf16_f32 v119, v102, v103
	global_store_dwordx2 v124, v[118:119], s[10:11] offset:1024
	v_pk_mul_f32 v[104:105], v[12:13], v[112:113] op_sel_hi:[1,0]
	v_pk_fma_f32 v[104:105], v[104:105], v[44:45], v[80:81]
	v_cvt_pk_bf16_f32 v120, v104, v105
	v_pk_mul_f32 v[106:107], v[14:15], v[112:113] op_sel_hi:[1,0]
	v_pk_fma_f32 v[106:107], v[106:107], v[46:47], v[82:83]
	v_cvt_pk_bf16_f32 v121, v106, v107
	global_store_dwordx2 v124, v[120:121], s[10:11] offset:1536
	v_pk_mul_f32 v[100:101], v[16:17], v[112:113] op_sel_hi:[1,0]
	v_pk_fma_f32 v[100:101], v[100:101], v[48:49], v[84:85]
	v_cvt_pk_bf16_f32 v114, v100, v101
	v_pk_mul_f32 v[102:103], v[18:19], v[112:113] op_sel_hi:[1,0]
	v_pk_fma_f32 v[102:103], v[102:103], v[50:51], v[86:87]
	v_cvt_pk_bf16_f32 v115, v102, v103
	global_store_dwordx2 v124, v[114:115], s[10:11] offset:2048
	v_pk_mul_f32 v[104:105], v[20:21], v[112:113] op_sel_hi:[1,0]
	v_pk_fma_f32 v[104:105], v[104:105], v[56:57], v[88:89]
	v_cvt_pk_bf16_f32 v116, v104, v105
	v_pk_mul_f32 v[106:107], v[22:23], v[112:113] op_sel_hi:[1,0]
	v_pk_fma_f32 v[106:107], v[106:107], v[58:59], v[90:91]
	v_cvt_pk_bf16_f32 v117, v106, v107
	global_store_dwordx2 v124, v[116:117], s[10:11] offset:2560
	v_pk_mul_f32 v[100:101], v[24:25], v[112:113] op_sel_hi:[1,0]
	v_pk_fma_f32 v[100:101], v[100:101], v[60:61], v[92:93]
	v_cvt_pk_bf16_f32 v118, v100, v101
	v_pk_mul_f32 v[102:103], v[26:27], v[112:113] op_sel_hi:[1,0]
	v_pk_fma_f32 v[102:103], v[102:103], v[62:63], v[94:95]
	v_cvt_pk_bf16_f32 v119, v102, v103
	global_store_dwordx2 v124, v[118:119], s[10:11] offset:3072
	v_pk_mul_f32 v[104:105], v[28:29], v[112:113] op_sel_hi:[1,0]
	v_pk_fma_f32 v[104:105], v[104:105], v[64:65], v[96:97]
	v_cvt_pk_bf16_f32 v120, v104, v105
	v_pk_mul_f32 v[106:107], v[30:31], v[112:113] op_sel_hi:[1,0]
	v_pk_fma_f32 v[106:107], v[106:107], v[66:67], v[98:99]
	v_cvt_pk_bf16_f32 v121, v106, v107
	global_store_dwordx2 v124, v[120:121], s[10:11] offset:3584
	s_lshr_b32 s1, s5, 9
	s_lshl_b32 s1, s1, 13
	s_and_b32 s8, s5, 0x1ff
	s_add_u32 s1, s1, s8
	s_add_u32 s8, s0, 1
	s_lshl_b32 s8, s8, 9
	s_add_u32 s1, s1, s8
	s_lshl_b32 s8, s1, 13
	s_lshl_b32 s8, s1, 12
	s_add_u32 s9, s8, 0x2c800000
	s_add_u32 s10, s52, s9
	s_addc_u32 s11, s53, 0
	s_cmp_lt_u32 s0, 14
	s_cbranch_scc0 .Lrm0_nopf_o
	s_lshr_b32 s1, s5, 9
	s_lshl_b32 s1, s1, 13
	s_and_b32 s8, s5, 0x1ff
	s_add_u32 s1, s1, s8
	s_add_u32 s8, s0, 2
	s_lshl_b32 s8, s8, 9
	s_add_u32 s1, s1, s8
	s_lshl_b32 s8, s1, 13
	v_readfirstlane_b32 s6, v130
	v_readfirstlane_b32 s7, v131
	s_nop 3
	s_add_u32 s6, s6, s8
	s_addc_u32 s7, s7, 0
	s_nop 1
	global_load_dwordx4 v[0:3], v122, s[6:7] offset:0 nt
	global_load_dwordx4 v[4:7], v122, s[6:7] offset:1024 nt
	global_load_dwordx4 v[8:11], v122, s[6:7] offset:2048 nt
	global_load_dwordx4 v[12:15], v122, s[6:7] offset:3072 nt
	global_load_dwordx4 v[16:19], v123, s[6:7] offset:0 nt
	global_load_dwordx4 v[20:23], v123, s[6:7] offset:1024 nt
	global_load_dwordx4 v[24:27], v123, s[6:7] offset:2048 nt
	global_load_dwordx4 v[28:31], v123, s[6:7] offset:3072 nt
	s_waitcnt vmcnt(8)
	s_branch .Lrm0_pfd_o

.Lrm0_pfd_o:
	v_pk_mul_f32 v[108:109], v[136:137], v[136:137]
	v_pk_mul_f32 v[110:111], v[138:139], v[138:139]
	v_pk_fma_f32 v[108:109], v[140:141], v[140:141], v[108:109]
	v_pk_fma_f32 v[110:111], v[142:143], v[142:143], v[110:111]
	v_pk_fma_f32 v[108:109], v[144:145], v[144:145], v[108:109]
	v_pk_fma_f32 v[110:111], v[146:147], v[146:147], v[110:111]
	v_pk_fma_f32 v[108:109], v[148:149], v[148:149], v[108:109]
	v_pk_fma_f32 v[110:111], v[150:151], v[150:151], v[110:111]
	v_pk_fma_f32 v[108:109], v[152:153], v[152:153], v[108:109]
	v_pk_fma_f32 v[110:111], v[154:155], v[154:155], v[110:111]
	v_pk_fma_f32 v[108:109], v[156:157], v[156:157], v[108:109]
	v_pk_fma_f32 v[110:111], v[158:159], v[158:159], v[110:111]
	v_pk_fma_f32 v[108:109], v[160:161], v[160:161], v[108:109]
	v_pk_fma_f32 v[110:111], v[162:163], v[162:163], v[110:111]
	v_pk_fma_f32 v[108:109], v[164:165], v[164:165], v[108:109]
	v_pk_fma_f32 v[110:111], v[166:167], v[166:167], v[110:111]
	v_pk_add_f32 v[108:109], v[108:109], v[110:111]
	s_nop 0
	v_add_f32_e32 v128, v108, v109
	s_nop 1
	v_add_f32_dpp v128, v128, v128 quad_perm:[1,0,3,2] row_mask:0xf bank_mask:0xf
	s_nop 1
	v_add_f32_dpp v128, v128, v128 quad_perm:[2,3,0,1] row_mask:0xf bank_mask:0xf
	s_nop 1
	v_add_f32_dpp v128, v128, v128 row_half_mirror row_mask:0xf bank_mask:0xf
	s_nop 1
	v_add_f32_dpp v128, v128, v128 row_mirror row_mask:0xf bank_mask:0xf
	s_nop 1
	v_add_f32_dpp v128, v128, v128 row_bcast:15 row_mask:0xa bank_mask:0xf
	s_nop 1
	v_add_f32_dpp v128, v128, v128 row_bcast:31 row_mask:0xc bank_mask:0xf
	s_nop 1
	v_readlane_b32 s8, v128, 63
	s_nop 3
	v_mov_b32_e32 v112, s8
	v_fma_f32 v112, v112, v126, v127
	v_rsq_f32_e32 v112, v112
	s_nop 1
	v_pk_mul_f32 v[100:101], v[136:137], v[112:113] op_sel_hi:[1,0]
	v_pk_fma_f32 v[100:101], v[100:101], v[32:33], v[68:69]
	v_cvt_pk_bf16_f32 v114, v100, v101
	v_pk_mul_f32 v[102:103], v[138:139], v[112:113] op_sel_hi:[1,0]
	v_pk_fma_f32 v[102:103], v[102:103], v[34:35], v[70:71]
	v_cvt_pk_bf16_f32 v115, v102, v103
	global_store_dwordx2 v124, v[114:115], s[10:11] offset:0
	v_pk_mul_f32 v[104:105], v[140:141], v[112:113] op_sel_hi:[1,0]
	v_pk_fma_f32 v[104:105], v[104:105], v[36:37], v[72:73]
	v_cvt_pk_bf16_f32 v116, v104, v105
	v_pk_mul_f32 v[106:107], v[142:143], v[112:113] op_sel_hi:[1,0]
	v_pk_fma_f32 v[106:107], v[106:107], v[38:39], v[74:75]
	v_cvt_pk_bf16_f32 v117, v106, v107
	global_store_dwordx2 v124, v[116:117], s[10:11] offset:512
	v_pk_mul_f32 v[100:101], v[144:145], v[112:113] op_sel_hi:[1,0]
	v_pk_fma_f32 v[100:101], v[100:101], v[40:41], v[76:77]
	v_cvt_pk_bf16_f32 v118, v100, v101
	v_pk_mul_f32 v[102:103], v[146:147], v[112:113] op_sel_hi:[1,0]
	v_pk_fma_f32 v[102:103], v[102:103], v[42:43], v[78:79]
	v_cvt_pk_bf16_f32 v119, v102, v103
	global_store_dwordx2 v124, v[118:119], s[10:11] offset:1024
	v_pk_mul_f32 v[104:105], v[148:149], v[112:113] op_sel_hi:[1,0]
	v_pk_fma_f32 v[104:105], v[104:105], v[44:45], v[80:81]
	v_cvt_pk_bf16_f32 v120, v104, v105
	v_pk_mul_f32 v[106:107], v[150:151], v[112:113] op_sel_hi:[1,0]
	v_pk_fma_f32 v[106:107], v[106:107], v[46:47], v[82:83]
	v_cvt_pk_bf16_f32 v121, v106, v107
	global_store_dwordx2 v124, v[120:121], s[10:11] offset:1536
	v_pk_mul_f32 v[100:101], v[152:153], v[112:113] op_sel_hi:[1,0]
	v_pk_fma_f32 v[100:101], v[100:101], v[48:49], v[84:85]
	v_cvt_pk_bf16_f32 v114, v100, v101
	v_pk_mul_f32 v[102:103], v[154:155], v[112:113] op_sel_hi:[1,0]
	v_pk_fma_f32 v[102:103], v[102:103], v[50:51], v[86:87]
	v_cvt_pk_bf16_f32 v115, v102, v103
	global_store_dwordx2 v124, v[114:115], s[10:11] offset:2048
	v_pk_mul_f32 v[104:105], v[156:157], v[112:113] op_sel_hi:[1,0]
	v_pk_fma_f32 v[104:105], v[104:105], v[56:57], v[88:89]
	v_cvt_pk_bf16_f32 v116, v104, v105
	v_pk_mul_f32 v[106:107], v[158:159], v[112:113] op_sel_hi:[1,0]
	v_pk_fma_f32 v[106:107], v[106:107], v[58:59], v[90:91]
	v_cvt_pk_bf16_f32 v117, v106, v107
	global_store_dwordx2 v124, v[116:117], s[10:11] offset:2560
	v_pk_mul_f32 v[100:101], v[160:161], v[112:113] op_sel_hi:[1,0]
	v_pk_fma_f32 v[100:101], v[100:101], v[60:61], v[92:93]
	v_cvt_pk_bf16_f32 v118, v100, v101
	v_pk_mul_f32 v[102:103], v[162:163], v[112:113] op_sel_hi:[1,0]
	v_pk_fma_f32 v[102:103], v[102:103], v[62:63], v[94:95]
	v_cvt_pk_bf16_f32 v119, v102, v103
	global_store_dwordx2 v124, v[118:119], s[10:11] offset:3072
	v_pk_mul_f32 v[104:105], v[164:165], v[112:113] op_sel_hi:[1,0]
	v_pk_fma_f32 v[104:105], v[104:105], v[64:65], v[96:97]
	v_cvt_pk_bf16_f32 v120, v104, v105
	v_pk_mul_f32 v[106:107], v[166:167], v[112:113] op_sel_hi:[1,0]
	v_pk_fma_f32 v[106:107], v[106:107], v[66:67], v[98:99]
	v_cvt_pk_bf16_f32 v121, v106, v107
	global_store_dwordx2 v124, v[120:121], s[10:11] offset:3584
	s_add_u32 s0, s0, 2
	s_cmp_lt_u32 s0, 16
	s_cbranch_scc1 .Lrm0_loop
	s_bitcmp1_b32 s5, 0
	s_cbranch_scc1 .Lrm0_done
	s_mov_b32 s4, 4
	s_branch .Lrm0_coef
.Lrm0_ctxrow:
	s_lshr_b32 s8, s5, 1
	s_lshl_b32 s8, s8, 13
	v_readfirstlane_b32 s6, v132
	v_readfirstlane_b32 s7, v133
	s_nop 3
	s_add_u32 s6, s6, s8
	s_addc_u32 s7, s7, 0
	s_nop 1
	global_load_dwordx4 v[0:3], v122, s[6:7] offset:0 nt
	global_load_dwordx4 v[4:7], v122, s[6:7] offset:1024 nt
	global_load_dwordx4 v[8:11], v122, s[6:7] offset:2048 nt
	global_load_dwordx4 v[12:15], v122, s[6:7] offset:3072 nt
	global_load_dwordx4 v[16:19], v123, s[6:7] offset:0 nt
	global_load_dwordx4 v[20:23], v123, s[6:7] offset:1024 nt
	global_load_dwordx4 v[24:27], v123, s[6:7] offset:2048 nt
	global_load_dwordx4 v[28:31], v123, s[6:7] offset:3072 nt
	s_lshr_b32 s8, s5, 1
	s_add_u32 s1, s8, 0x8000
	s_lshl_b32 s8, s8, 13
	s_lshl_b32 s8, s1, 12
	s_add_u32 s9, s8, 0x2c800000
	s_add_u32 s10, s52, s9
	s_addc_u32 s11, s53, 0
	s_waitcnt vmcnt(0)
	v_pk_mul_f32 v[108:109], v[0:1], v[0:1]
	v_pk_mul_f32 v[110:111], v[2:3], v[2:3]
	v_pk_fma_f32 v[108:109], v[4:5], v[4:5], v[108:109]
	v_pk_fma_f32 v[110:111], v[6:7], v[6:7], v[110:111]
	v_pk_fma_f32 v[108:109], v[8:9], v[8:9], v[108:109]
	v_pk_fma_f32 v[110:111], v[10:11], v[10:11], v[110:111]
	v_pk_fma_f32 v[108:109], v[12:13], v[12:13], v[108:109]
	v_pk_fma_f32 v[110:111], v[14:15], v[14:15], v[110:111]
	v_pk_fma_f32 v[108:109], v[16:17], v[16:17], v[108:109]
	v_pk_fma_f32 v[110:111], v[18:19], v[18:19], v[110:111]
	v_pk_fma_f32 v[108:109], v[20:21], v[20:21], v[108:109]
	v_pk_fma_f32 v[110:111], v[22:23], v[22:23], v[110:111]
	v_pk_fma_f32 v[108:109], v[24:25], v[24:25], v[108:109]
	v_pk_fma_f32 v[110:111], v[26:27], v[26:27], v[110:111]
	v_pk_fma_f32 v[108:109], v[28:29], v[28:29], v[108:109]
	v_pk_fma_f32 v[110:111], v[30:31], v[30:31], v[110:111]
	v_pk_add_f32 v[108:109], v[108:109], v[110:111]
	s_nop 0
	v_add_f32_e32 v128, v108, v109
	s_nop 1
	v_add_f32_dpp v128, v128, v128 quad_perm:[1,0,3,2] row_mask:0xf bank_mask:0xf
	s_nop 1
	v_add_f32_dpp v128, v128, v128 quad_perm:[2,3,0,1] row_mask:0xf bank_mask:0xf
	s_nop 1
	v_add_f32_dpp v128, v128, v128 row_half_mirror row_mask:0xf bank_mask:0xf
	s_nop 1
	v_add_f32_dpp v128, v128, v128 row_mirror row_mask:0xf bank_mask:0xf
	s_nop 1
	v_add_f32_dpp v128, v128, v128 row_bcast:15 row_mask:0xa bank_mask:0xf
	s_nop 1
	v_add_f32_dpp v128, v128, v128 row_bcast:31 row_mask:0xc bank_mask:0xf
	s_nop 1
	v_readlane_b32 s8, v128, 63
	s_nop 3
	v_mov_b32_e32 v112, s8
	v_fma_f32 v112, v112, v126, v127
	v_rsq_f32_e32 v112, v112
	s_nop 1
	v_pk_mul_f32 v[100:101], v[0:1], v[112:113] op_sel_hi:[1,0]
	v_pk_fma_f32 v[100:101], v[100:101], v[32:33], v[68:69]
	v_cvt_pk_bf16_f32 v114, v100, v101
	v_pk_mul_f32 v[102:103], v[2:3], v[112:113] op_sel_hi:[1,0]
	v_pk_fma_f32 v[102:103], v[102:103], v[34:35], v[70:71]
	v_cvt_pk_bf16_f32 v115, v102, v103
	global_store_dwordx2 v124, v[114:115], s[10:11] offset:0
	v_pk_mul_f32 v[104:105], v[4:5], v[112:113] op_sel_hi:[1,0]
	v_pk_fma_f32 v[104:105], v[104:105], v[36:37], v[72:73]
	v_cvt_pk_bf16_f32 v116, v104, v105
	v_pk_mul_f32 v[106:107], v[6:7], v[112:113] op_sel_hi:[1,0]
	v_pk_fma_f32 v[106:107], v[106:107], v[38:39], v[74:75]
	v_cvt_pk_bf16_f32 v117, v106, v107
	global_store_dwordx2 v124, v[116:117], s[10:11] offset:512
	v_pk_mul_f32 v[100:101], v[8:9], v[112:113] op_sel_hi:[1,0]
	v_pk_fma_f32 v[100:101], v[100:101], v[40:41], v[76:77]
	v_cvt_pk_bf16_f32 v118, v100, v101
	v_pk_mul_f32 v[102:103], v[10:11], v[112:113] op_sel_hi:[1,0]
	v_pk_fma_f32 v[102:103], v[102:103], v[42:43], v[78:79]
	v_cvt_pk_bf16_f32 v119, v102, v103
	global_store_dwordx2 v124, v[118:119], s[10:11] offset:1024
	v_pk_mul_f32 v[104:105], v[12:13], v[112:113] op_sel_hi:[1,0]
	v_pk_fma_f32 v[104:105], v[104:105], v[44:45], v[80:81]
	v_cvt_pk_bf16_f32 v120, v104, v105
	v_pk_mul_f32 v[106:107], v[14:15], v[112:113] op_sel_hi:[1,0]
	v_pk_fma_f32 v[106:107], v[106:107], v[46:47], v[82:83]
	v_cvt_pk_bf16_f32 v121, v106, v107
	global_store_dwordx2 v124, v[120:121], s[10:11] offset:1536
	v_pk_mul_f32 v[100:101], v[16:17], v[112:113] op_sel_hi:[1,0]
	v_pk_fma_f32 v[100:101], v[100:101], v[48:49], v[84:85]
	v_cvt_pk_bf16_f32 v114, v100, v101
	v_pk_mul_f32 v[102:103], v[18:19], v[112:113] op_sel_hi:[1,0]
	v_pk_fma_f32 v[102:103], v[102:103], v[50:51], v[86:87]
	v_cvt_pk_bf16_f32 v115, v102, v103
	global_store_dwordx2 v124, v[114:115], s[10:11] offset:2048
	v_pk_mul_f32 v[104:105], v[20:21], v[112:113] op_sel_hi:[1,0]
	v_pk_fma_f32 v[104:105], v[104:105], v[56:57], v[88:89]
	v_cvt_pk_bf16_f32 v116, v104, v105
	v_pk_mul_f32 v[106:107], v[22:23], v[112:113] op_sel_hi:[1,0]
	v_pk_fma_f32 v[106:107], v[106:107], v[58:59], v[90:91]
	v_cvt_pk_bf16_f32 v117, v106, v107
	global_store_dwordx2 v124, v[116:117], s[10:11] offset:2560
	v_pk_mul_f32 v[100:101], v[24:25], v[112:113] op_sel_hi:[1,0]
	v_pk_fma_f32 v[100:101], v[100:101], v[60:61], v[92:93]
	v_cvt_pk_bf16_f32 v118, v100, v101
	v_pk_mul_f32 v[102:103], v[26:27], v[112:113] op_sel_hi:[1,0]
	v_pk_fma_f32 v[102:103], v[102:103], v[62:63], v[94:95]
	v_cvt_pk_bf16_f32 v119, v102, v103
	global_store_dwordx2 v124, v[118:119], s[10:11] offset:3072
	v_pk_mul_f32 v[104:105], v[28:29], v[112:113] op_sel_hi:[1,0]
	v_pk_fma_f32 v[104:105], v[104:105], v[64:65], v[96:97]
	v_cvt_pk_bf16_f32 v120, v104, v105
	v_pk_mul_f32 v[106:107], v[30:31], v[112:113] op_sel_hi:[1,0]
	v_pk_fma_f32 v[106:107], v[106:107], v[66:67], v[98:99]
	v_cvt_pk_bf16_f32 v121, v106, v107
	global_store_dwordx2 v124, v[120:121], s[10:11] offset:3584

.Lrm0_orig:
	v_lshlrev_b32_e32 v3, 2, v3
	v_and_b32_e32 v4, 0xfc, v3
	v_mov_b32_e32 v57, 0
	v_or_b32_e32 v12, 0x400, v4
	v_lshlrev_b32_e32 v56, 2, v4
	v_or_b32_e32 v14, 0x500, v4
	s_waitcnt vmcnt(0)
	v_lshl_add_u64 v[58:59], v[0:1], 0, v[56:57]
	v_lshlrev_b32_e32 v56, 2, v12
	v_or_b32_e32 v16, 0x600, v4
	v_lshl_add_u64 v[60:61], v[0:1], 0, v[56:57]
	v_lshlrev_b32_e32 v56, 2, v14
	v_or_b32_e32 v18, 0x700, v4
	v_lshl_add_u64 v[62:63], v[0:1], 0, v[56:57]
	v_lshlrev_b32_e32 v56, 2, v16
	v_lshl_add_u64 v[64:65], v[0:1], 0, v[56:57]
	v_lshlrev_b32_e32 v56, 2, v18
	v_lshl_add_u64 v[66:67], v[0:1], 0, v[56:57]
	v_mbcnt_hi_u32_b32 v0, -1, v190
	v_and_b32_e32 v1, 64, v0
	v_add_u32_e32 v1, 64, v1
	v_xor_b32_e32 v3, 32, v0
	v_cmp_lt_i32_e32 vcc, v3, v1
	v_or_b32_e32 v6, 0x100, v4
	v_or_b32_e32 v8, 0x200, v4
	v_cndmask_b32_e32 v3, v0, v3, vcc
	v_lshlrev_b32_e32 v98, 2, v3
	v_xor_b32_e32 v3, 16, v0
	v_cmp_lt_i32_e32 vcc, v3, v1
	v_or_b32_e32 v10, 0x300, v4
	v_lshlrev_b32_e32 v56, 1, v4
	v_cndmask_b32_e32 v3, v0, v3, vcc
	v_lshlrev_b32_e32 v99, 2, v3
	v_xor_b32_e32 v3, 8, v0
	v_cmp_lt_i32_e32 vcc, v3, v1
	v_lshl_add_u64 v[68:69], s[62:63], 0, v[56:57]
	s_lshl_b32 s4, s54, 4
	v_cndmask_b32_e32 v3, v0, v3, vcc
	v_lshlrev_b32_e32 v100, 2, v3
	v_xor_b32_e32 v3, 4, v0
	v_cmp_lt_i32_e32 vcc, v3, v1
	s_mov_b64 s[6:7], 0
	s_movk_i32 s5, 0x4000
	v_cndmask_b32_e32 v3, v0, v3, vcc
	v_lshlrev_b32_e32 v101, 2, v3
	v_xor_b32_e32 v3, 2, v0
	v_cmp_lt_i32_e32 vcc, v3, v1
	v_lshlrev_b32_e32 v72, 2, v4
	s_movk_i32 s9, 0x1000
	v_cndmask_b32_e32 v3, v0, v3, vcc
	v_lshlrev_b32_e32 v102, 2, v3
	v_xor_b32_e32 v3, 1, v0
	v_cmp_lt_i32_e32 vcc, v3, v1
	s_movk_i32 s12, 0x2000
	s_movk_i32 s13, 0x3000
	v_cndmask_b32_e32 v0, v0, v3, vcc
	v_lshlrev_b32_e32 v103, 2, v0
	v_lshlrev_b32_e32 v0, 1, v2
	v_lshl_add_u32 v70, s0, 4, v0
	s_mov_b32 s8, 0x3a000000
	s_mov_b32 s14, 0x800000
	s_mov_b64 s[10:11], 0x2000
	v_lshlrev_b32_e32 v74, 2, v6
	v_lshlrev_b32_e32 v76, 2, v8
	v_lshlrev_b32_e32 v78, 2, v10
	v_lshlrev_b32_e32 v80, 2, v12
	v_lshlrev_b32_e32 v82, 2, v14
	v_lshlrev_b32_e32 v84, 2, v16
	v_lshlrev_b32_e32 v56, 2, v18
	s_movk_i32 s15, 0x41ff
	v_mov_b32_e32 v73, v57
	v_mov_b32_e32 v86, 0x358637bd
	v_mov_b32_e32 v75, v57
	v_mov_b32_e32 v77, v57
	v_mov_b32_e32 v79, v57
	v_mov_b32_e32 v81, v57
	v_mov_b32_e32 v83, v57
	v_mov_b32_e32 v85, v57

.LBB0_978:
	s_or_b64 exec, exec, s[0:1]
	v_mov_b32_e32 v77, 0
	s_waitcnt lgkmcnt(0)
	s_barrier
	global_load_dwordx2 v[78:79], v77, s[44:45]
	v_mov_b32_e32 v4, 0x3e500000
	global_load_dwordx2 v[80:81], v77, s[42:43]
	global_load_dwordx4 v[0:3], v4, s[52:53] offset:56
	s_add_u32 s50, s52, 0x3d000000
	s_addc_u32 s51, s53, 0
	s_add_u32 s0, s52, 0x3e500038
	s_addc_u32 s1, s53, 0
	v_writelane_b32 v252, s0, 7
	v_mov_b32_e32 v5, v189
	s_nop 0
	v_writelane_b32 v252, s1, 8
	s_mov_b32 s0, s33
	v_ashrrev_i32_e32 v4, 6, v5
	s_movk_i32 s1, 0x4200
	v_lshl_add_u32 v123, s0, 3, v4
	v_cmp_gt_i32_e32 vcc, s1, v123
	s_and_saveexec_b64 s[6:7], vcc
	s_cbranch_execz .LBB0_983
	s_cmpk_lg_i32 s94, 0x800
	s_cbranch_scc1 .Lrm1_orig
	s_waitcnt vmcnt(0) lgkmcnt(0)
	v_and_b32_e32 v174, 63, v189
	v_lshrrev_b32_e32 v177, 6, v189
	v_lshlrev_b32_e32 v76, 4, v174
	v_lshlrev_b32_e32 v173, 3, v174
	v_readfirstlane_b32 s3, v177
	v_add_u32_e32 v172, 0x1000, v76
	v_mov_b32_e32 v174, 0
	v_mov_b32_e32 v175, 0x3a000000
	v_mov_b32_e32 v176, 0x358637bd
	s_lshl_b32 s8, s33, 3
	s_add_u32 s3, s3, s8
	s_add_u32 s8, s52, 0x3e500000
	s_addc_u32 s9, s53, 0
	global_load_dwordx2 v[178:179], v174, s[8:9] offset:0
	global_load_dwordx2 v[180:181], v174, s[8:9] offset:16
	global_load_dwordx2 v[182:183], v174, s[8:9] offset:56
	global_load_dwordx2 v[184:185], v174, s[8:9] offset:64
	s_waitcnt vmcnt(0)
	s_mov_b32 s0, 0
	s_lshr_b32 s2, s3, 9
.Lrm1_coef:
	v_readfirstlane_b32 s8, v182
	v_readfirstlane_b32 s9, v183
	s_nop 4
	global_load_dwordx4 v[0:3], v76, s[8:9] offset:0
	global_load_dwordx4 v[4:7], v76, s[8:9] offset:1024
	global_load_dwordx4 v[8:11], v76, s[8:9] offset:2048
	global_load_dwordx4 v[12:15], v76, s[8:9] offset:3072
	global_load_dwordx4 v[16:19], v172, s[8:9] offset:0
	global_load_dwordx4 v[20:23], v172, s[8:9] offset:1024
	global_load_dwordx4 v[24:27], v172, s[8:9] offset:2048
	global_load_dwordx4 v[28:31], v172, s[8:9] offset:3072
	s_mul_i32 s8, s2, 0xc000
	s_add_u32 s8, s8, 0x3d804000
	s_add_u32 s8, s52, s8
	s_addc_u32 s9, s53, 0
	global_load_dwordx4 v[86:89], v76, s[8:9] offset:0
	global_load_dwordx4 v[90:93], v76, s[8:9] offset:1024
	global_load_dwordx4 v[94:97], v76, s[8:9] offset:2048
	global_load_dwordx4 v[98:101], v76, s[8:9] offset:3072
	global_load_dwordx4 v[102:105], v172, s[8:9] offset:0
	global_load_dwordx4 v[106:109], v172, s[8:9] offset:1024
	global_load_dwordx4 v[110:113], v172, s[8:9] offset:2048
	global_load_dwordx4 v[114:117], v172, s[8:9] offset:3072
	s_waitcnt vmcnt(0)
	v_pk_mul_f32 v[48:49], v[86:87], v[0:1]
	v_pk_mul_f32 v[50:51], v[88:89], v[2:3]
	v_pk_mul_f32 v[52:53], v[90:91], v[4:5]
	v_pk_mul_f32 v[54:55], v[92:93], v[6:7]
	v_pk_mul_f32 v[56:57], v[94:95], v[8:9]
	v_pk_mul_f32 v[58:59], v[96:97], v[10:11]
	v_pk_mul_f32 v[60:61], v[98:99], v[12:13]
	v_pk_mul_f32 v[62:63], v[100:101], v[14:15]
	v_pk_mul_f32 v[64:65], v[102:103], v[16:17]
	v_pk_mul_f32 v[66:67], v[104:105], v[18:19]
	v_pk_mul_f32 v[68:69], v[106:107], v[20:21]
	v_pk_mul_f32 v[70:71], v[108:109], v[22:23]
	v_pk_mul_f32 v[72:73], v[110:111], v[24:25]
	v_pk_mul_f32 v[74:75], v[112:113], v[26:27]
	v_pk_mul_f32 v[82:83], v[114:115], v[28:29]
	v_pk_mul_f32 v[84:85], v[116:117], v[30:31]
	v_readfirstlane_b32 s8, v184
	v_readfirstlane_b32 s9, v185
	s_nop 4
	global_load_dwordx4 v[0:3], v76, s[8:9] offset:0
	global_load_dwordx4 v[4:7], v76, s[8:9] offset:1024
	global_load_dwordx4 v[8:11], v76, s[8:9] offset:2048
	global_load_dwordx4 v[12:15], v76, s[8:9] offset:3072
	global_load_dwordx4 v[16:19], v172, s[8:9] offset:0
	global_load_dwordx4 v[20:23], v172, s[8:9] offset:1024
	global_load_dwordx4 v[24:27], v172, s[8:9] offset:2048
	global_load_dwordx4 v[28:31], v172, s[8:9] offset:3072
	s_mul_i32 s8, s2, 0xc000
	s_add_u32 s8, s8, 0x3d808000
	s_add_u32 s8, s52, s8
	s_addc_u32 s9, s53, 0
	global_load_dwordx4 v[118:121], v76, s[8:9] offset:0
	global_load_dwordx4 v[122:125], v76, s[8:9] offset:1024
	global_load_dwordx4 v[126:129], v76, s[8:9] offset:2048
	global_load_dwordx4 v[130:133], v76, s[8:9] offset:3072
	global_load_dwordx4 v[134:137], v172, s[8:9] offset:0
	global_load_dwordx4 v[138:141], v172, s[8:9] offset:1024
	global_load_dwordx4 v[142:145], v172, s[8:9] offset:2048
	global_load_dwordx4 v[146:149], v172, s[8:9] offset:3072
	s_waitcnt vmcnt(0)
	v_pk_add_f32 v[118:119], v[118:119], 1.0 op_sel_hi:[1,0]
	v_pk_add_f32 v[120:121], v[120:121], 1.0 op_sel_hi:[1,0]
	v_pk_add_f32 v[122:123], v[122:123], 1.0 op_sel_hi:[1,0]
	v_pk_add_f32 v[124:125], v[124:125], 1.0 op_sel_hi:[1,0]
	v_pk_add_f32 v[126:127], v[126:127], 1.0 op_sel_hi:[1,0]
	v_pk_add_f32 v[128:129], v[128:129], 1.0 op_sel_hi:[1,0]
	v_pk_add_f32 v[130:131], v[130:131], 1.0 op_sel_hi:[1,0]
	v_pk_add_f32 v[132:133], v[132:133], 1.0 op_sel_hi:[1,0]
	v_pk_add_f32 v[134:135], v[134:135], 1.0 op_sel_hi:[1,0]
	v_pk_add_f32 v[136:137], v[136:137], 1.0 op_sel_hi:[1,0]
	v_pk_add_f32 v[138:139], v[138:139], 1.0 op_sel_hi:[1,0]
	v_pk_add_f32 v[140:141], v[140:141], 1.0 op_sel_hi:[1,0]
	v_pk_add_f32 v[142:143], v[142:143], 1.0 op_sel_hi:[1,0]
	v_pk_add_f32 v[144:145], v[144:145], 1.0 op_sel_hi:[1,0]
	v_pk_add_f32 v[146:147], v[146:147], 1.0 op_sel_hi:[1,0]
	v_pk_add_f32 v[148:149], v[148:149], 1.0 op_sel_hi:[1,0]
	v_pk_mul_f32 v[86:87], v[0:1], v[118:119]
	v_pk_mul_f32 v[88:89], v[2:3], v[120:121]
	v_pk_mul_f32 v[90:91], v[4:5], v[122:123]
	v_pk_mul_f32 v[92:93], v[6:7], v[124:125]
	v_pk_mul_f32 v[94:95], v[8:9], v[126:127]
	v_pk_mul_f32 v[96:97], v[10:11], v[128:129]
	v_pk_mul_f32 v[98:99], v[12:13], v[130:131]
	v_pk_mul_f32 v[100:101], v[14:15], v[132:133]
	v_pk_mul_f32 v[102:103], v[16:17], v[134:135]
	v_pk_mul_f32 v[104:105], v[18:19], v[136:137]
	v_pk_mul_f32 v[106:107], v[20:21], v[138:139]
	v_pk_mul_f32 v[108:109], v[22:23], v[140:141]
	v_pk_mul_f32 v[110:111], v[24:25], v[142:143]
	v_pk_mul_f32 v[112:113], v[26:27], v[144:145]
	v_pk_mul_f32 v[114:115], v[28:29], v[146:147]
	v_pk_mul_f32 v[116:117], v[30:31], v[148:149]
	s_mul_i32 s8, s2, 0xc000
	s_add_u32 s8, s8, 0x3d806000
	s_add_u32 s8, s52, s8
	s_addc_u32 s9, s53, 0
	global_load_dwordx4 v[118:121], v76, s[8:9] offset:0
	global_load_dwordx4 v[122:125], v76, s[8:9] offset:1024
	global_load_dwordx4 v[126:129], v76, s[8:9] offset:2048
	global_load_dwordx4 v[130:133], v76, s[8:9] offset:3072
	global_load_dwordx4 v[134:137], v172, s[8:9] offset:0
	global_load_dwordx4 v[138:141], v172, s[8:9] offset:1024
	global_load_dwordx4 v[142:145], v172, s[8:9] offset:2048
	global_load_dwordx4 v[146:149], v172, s[8:9] offset:3072
	s_cmp_lt_u32 s0, 16
	s_cbranch_scc0 .Lrm1_ctxrow
	s_lshr_b32 s1, s3, 9
	s_lshl_b32 s1, s1, 13
	s_and_b32 s8, s3, 0x1ff
	s_add_u32 s1, s1, s8
	s_add_u32 s8, s0, 0
	s_lshl_b32 s8, s8, 9
	s_add_u32 s1, s1, s8
	s_lshl_b32 s8, s1, 13
	v_readfirstlane_b32 s4, v178
	v_readfirstlane_b32 s5, v179
	s_nop 3
	s_add_u32 s4, s4, s8
	s_addc_u32 s5, s5, 0
	s_nop 1
	global_load_dwordx4 v[0:3], v76, s[4:5] offset:0 nt
	global_load_dwordx4 v[4:7], v76, s[4:5] offset:1024 nt
	global_load_dwordx4 v[8:11], v76, s[4:5] offset:2048 nt
	global_load_dwordx4 v[12:15], v76, s[4:5] offset:3072 nt
	global_load_dwordx4 v[16:19], v172, s[4:5] offset:0 nt
	global_load_dwordx4 v[20:23], v172, s[4:5] offset:1024 nt
	global_load_dwordx4 v[24:27], v172, s[4:5] offset:2048 nt
	global_load_dwordx4 v[28:31], v172, s[4:5] offset:3072 nt
.Lrm1_loop:
	s_lshr_b32 s1, s3, 9
	s_lshl_b32 s1, s1, 13
	s_and_b32 s8, s3, 0x1ff
	s_add_u32 s1, s1, s8
	s_add_u32 s8, s0, 0
	s_lshl_b32 s8, s8, 9
	s_add_u32 s1, s1, s8
	s_lshl_b32 s8, s1, 13
	s_add_u32 s10, s58, s8
	s_addc_u32 s11, s59, 0
	s_lshl_b32 s8, s1, 12
	s_add_u32 s9, s8, 0xb800000
	s_add_u32 s12, s52, s9
	s_addc_u32 s13, s53, 0
	s_add_u32 s9, s8, 0x2c800000
	s_add_u32 s14, s52, s9
	s_addc_u32 s15, s53, 0
	global_load_dwordx2 v[32:33], v173, s[12:13] offset:0 nt
	global_load_dwordx2 v[34:35], v173, s[12:13] offset:512 nt
	global_load_dwordx2 v[36:37], v173, s[12:13] offset:1024 nt
	global_load_dwordx2 v[38:39], v173, s[12:13] offset:1536 nt
	global_load_dwordx2 v[40:41], v173, s[12:13] offset:2048 nt
	global_load_dwordx2 v[42:43], v173, s[12:13] offset:2560 nt
	global_load_dwordx2 v[44:45], v173, s[12:13] offset:3072 nt
	global_load_dwordx2 v[46:47], v173, s[12:13] offset:3584 nt
	s_lshr_b32 s1, s3, 9
	s_lshl_b32 s1, s1, 13
	s_and_b32 s8, s3, 0x1ff
	s_add_u32 s1, s1, s8
	s_add_u32 s8, s0, 1
	s_lshl_b32 s8, s8, 9
	s_add_u32 s1, s1, s8
	s_lshl_b32 s8, s1, 13
	v_readfirstlane_b32 s4, v178
	v_readfirstlane_b32 s5, v179
	s_nop 3
	s_add_u32 s4, s4, s8
	s_addc_u32 s5, s5, 0
	s_nop 1
	global_load_dwordx4 v[192:195], v76, s[4:5] offset:0 nt
	global_load_dwordx4 v[196:199], v76, s[4:5] offset:1024 nt
	global_load_dwordx4 v[200:203], v76, s[4:5] offset:2048 nt
	global_load_dwordx4 v[204:207], v76, s[4:5] offset:3072 nt
	global_load_dwordx4 v[208:211], v172, s[4:5] offset:0 nt
	global_load_dwordx4 v[216:219], v172, s[4:5] offset:1024 nt
	global_load_dwordx4 v[224:227], v172, s[4:5] offset:2048 nt
	global_load_dwordx4 v[236:239], v172, s[4:5] offset:3072 nt
	s_waitcnt vmcnt(8)
	v_lshlrev_b32_e32 v150, 16, v32
	v_and_b32_e32 v151, 0xffff0000, v32
	v_pk_mul_f32 v[158:159], v[150:151], v[150:151]
	v_lshlrev_b32_e32 v152, 16, v33
	v_and_b32_e32 v153, 0xffff0000, v33
	v_pk_mul_f32 v[160:161], v[152:153], v[152:153]
	v_lshlrev_b32_e32 v154, 16, v34
	v_and_b32_e32 v155, 0xffff0000, v34
	v_pk_fma_f32 v[158:159], v[154:155], v[154:155], v[158:159]
	v_lshlrev_b32_e32 v156, 16, v35
	v_and_b32_e32 v157, 0xffff0000, v35
	v_pk_fma_f32 v[160:161], v[156:157], v[156:157], v[160:161]
	v_lshlrev_b32_e32 v150, 16, v36
	v_and_b32_e32 v151, 0xffff0000, v36
	v_pk_fma_f32 v[158:159], v[150:151], v[150:151], v[158:159]
	v_lshlrev_b32_e32 v152, 16, v37
	v_and_b32_e32 v153, 0xffff0000, v37
	v_pk_fma_f32 v[160:161], v[152:153], v[152:153], v[160:161]
	v_lshlrev_b32_e32 v154, 16, v38
	v_and_b32_e32 v155, 0xffff0000, v38
	v_pk_fma_f32 v[158:159], v[154:155], v[154:155], v[158:159]
	v_lshlrev_b32_e32 v156, 16, v39
	v_and_b32_e32 v157, 0xffff0000, v39
	v_pk_fma_f32 v[160:161], v[156:157], v[156:157], v[160:161]
	v_lshlrev_b32_e32 v150, 16, v40
	v_and_b32_e32 v151, 0xffff0000, v40
	v_pk_fma_f32 v[158:159], v[150:151], v[150:151], v[158:159]
	v_lshlrev_b32_e32 v152, 16, v41
	v_and_b32_e32 v153, 0xffff0000, v41
	v_pk_fma_f32 v[160:161], v[152:153], v[152:153], v[160:161]
	v_lshlrev_b32_e32 v154, 16, v42
	v_and_b32_e32 v155, 0xffff0000, v42
	v_pk_fma_f32 v[158:159], v[154:155], v[154:155], v[158:159]
	v_lshlrev_b32_e32 v156, 16, v43
	v_and_b32_e32 v157, 0xffff0000, v43
	v_pk_fma_f32 v[160:161], v[156:157], v[156:157], v[160:161]
	v_lshlrev_b32_e32 v150, 16, v44
	v_and_b32_e32 v151, 0xffff0000, v44
	v_pk_fma_f32 v[158:159], v[150:151], v[150:151], v[158:159]
	v_lshlrev_b32_e32 v152, 16, v45
	v_and_b32_e32 v153, 0xffff0000, v45
	v_pk_fma_f32 v[160:161], v[152:153], v[152:153], v[160:161]
	v_lshlrev_b32_e32 v154, 16, v46
	v_and_b32_e32 v155, 0xffff0000, v46
	v_pk_fma_f32 v[158:159], v[154:155], v[154:155], v[158:159]
	v_lshlrev_b32_e32 v156, 16, v47
	v_and_b32_e32 v157, 0xffff0000, v47
	v_pk_fma_f32 v[160:161], v[156:157], v[156:157], v[160:161]
	v_pk_add_f32 v[158:159], v[158:159], v[160:161]
	s_nop 0
	v_add_f32_e32 v177, v158, v159
	s_nop 1
	v_add_f32_dpp v177, v177, v177 quad_perm:[1,0,3,2] row_mask:0xf bank_mask:0xf
	s_nop 1
	v_add_f32_dpp v177, v177, v177 quad_perm:[2,3,0,1] row_mask:0xf bank_mask:0xf
	s_nop 1
	v_add_f32_dpp v177, v177, v177 row_half_mirror row_mask:0xf bank_mask:0xf
	s_nop 1
	v_add_f32_dpp v177, v177, v177 row_mirror row_mask:0xf bank_mask:0xf
	s_nop 1
	v_add_f32_dpp v177, v177, v177 row_bcast:15 row_mask:0xa bank_mask:0xf
	s_nop 1
	v_add_f32_dpp v177, v177, v177 row_bcast:31 row_mask:0xc bank_mask:0xf
	s_nop 1
	v_readlane_b32 s8, v177, 63
	s_nop 3
	v_mov_b32_e32 v162, s8
	v_fma_f32 v162, v162, v175, v176
	v_rsq_f32_e32 v162, v162
	s_nop 1
	v_lshlrev_b32_e32 v150, 16, v32
	v_and_b32_e32 v151, 0xffff0000, v32
	v_pk_mul_f32 v[150:151], v[150:151], v[162:163] op_sel_hi:[1,0]
	v_pk_fma_f32 v[0:1], v[48:49], v[150:151], v[0:1]
	v_lshlrev_b32_e32 v152, 16, v33
	v_and_b32_e32 v153, 0xffff0000, v33
	v_pk_mul_f32 v[152:153], v[152:153], v[162:163] op_sel_hi:[1,0]
	v_pk_fma_f32 v[2:3], v[50:51], v[152:153], v[2:3]
	v_lshlrev_b32_e32 v154, 16, v34
	v_and_b32_e32 v155, 0xffff0000, v34
	v_pk_mul_f32 v[154:155], v[154:155], v[162:163] op_sel_hi:[1,0]
	v_pk_fma_f32 v[4:5], v[52:53], v[154:155], v[4:5]
	v_lshlrev_b32_e32 v156, 16, v35
	v_and_b32_e32 v157, 0xffff0000, v35
	v_pk_mul_f32 v[156:157], v[156:157], v[162:163] op_sel_hi:[1,0]
	v_pk_fma_f32 v[6:7], v[54:55], v[156:157], v[6:7]
	v_lshlrev_b32_e32 v150, 16, v36
	v_and_b32_e32 v151, 0xffff0000, v36
	v_pk_mul_f32 v[150:151], v[150:151], v[162:163] op_sel_hi:[1,0]
	v_pk_fma_f32 v[8:9], v[56:57], v[150:151], v[8:9]
	v_lshlrev_b32_e32 v152, 16, v37
	v_and_b32_e32 v153, 0xffff0000, v37
	v_pk_mul_f32 v[152:153], v[152:153], v[162:163] op_sel_hi:[1,0]
	v_pk_fma_f32 v[10:11], v[58:59], v[152:153], v[10:11]
	v_lshlrev_b32_e32 v154, 16, v38
	v_and_b32_e32 v155, 0xffff0000, v38
	v_pk_mul_f32 v[154:155], v[154:155], v[162:163] op_sel_hi:[1,0]
	v_pk_fma_f32 v[12:13], v[60:61], v[154:155], v[12:13]
	v_lshlrev_b32_e32 v156, 16, v39
	v_and_b32_e32 v157, 0xffff0000, v39
	v_pk_mul_f32 v[156:157], v[156:157], v[162:163] op_sel_hi:[1,0]
	v_pk_fma_f32 v[14:15], v[62:63], v[156:157], v[14:15]
	v_lshlrev_b32_e32 v150, 16, v40
	v_and_b32_e32 v151, 0xffff0000, v40
	v_pk_mul_f32 v[150:151], v[150:151], v[162:163] op_sel_hi:[1,0]
	v_pk_fma_f32 v[16:17], v[64:65], v[150:151], v[16:17]
	v_lshlrev_b32_e32 v152, 16, v41
	v_and_b32_e32 v153, 0xffff0000, v41
	v_pk_mul_f32 v[152:153], v[152:153], v[162:163] op_sel_hi:[1,0]
	v_pk_fma_f32 v[18:19], v[66:67], v[152:153], v[18:19]
	v_lshlrev_b32_e32 v154, 16, v42
	v_and_b32_e32 v155, 0xffff0000, v42
	v_pk_mul_f32 v[154:155], v[154:155], v[162:163] op_sel_hi:[1,0]
	v_pk_fma_f32 v[20:21], v[68:69], v[154:155], v[20:21]
	v_lshlrev_b32_e32 v156, 16, v43
	v_and_b32_e32 v157, 0xffff0000, v43
	v_pk_mul_f32 v[156:157], v[156:157], v[162:163] op_sel_hi:[1,0]
	v_pk_fma_f32 v[22:23], v[70:71], v[156:157], v[22:23]
	v_lshlrev_b32_e32 v150, 16, v44
	v_and_b32_e32 v151, 0xffff0000, v44
	v_pk_mul_f32 v[150:151], v[150:151], v[162:163] op_sel_hi:[1,0]
	v_pk_fma_f32 v[24:25], v[72:73], v[150:151], v[24:25]
	v_lshlrev_b32_e32 v152, 16, v45
	v_and_b32_e32 v153, 0xffff0000, v45
	v_pk_mul_f32 v[152:153], v[152:153], v[162:163] op_sel_hi:[1,0]
	v_pk_fma_f32 v[26:27], v[74:75], v[152:153], v[26:27]
	v_lshlrev_b32_e32 v154, 16, v46
	v_and_b32_e32 v155, 0xffff0000, v46
	v_pk_mul_f32 v[154:155], v[154:155], v[162:163] op_sel_hi:[1,0]
	v_pk_fma_f32 v[28:29], v[82:83], v[154:155], v[28:29]
	v_lshlrev_b32_e32 v156, 16, v47
	v_and_b32_e32 v157, 0xffff0000, v47
	v_pk_mul_f32 v[156:157], v[156:157], v[162:163] op_sel_hi:[1,0]
	v_pk_fma_f32 v[30:31], v[84:85], v[156:157], v[30:31]
	s_nop 0
	global_store_dwordx4 v76, v[0:3], s[10:11] offset:0 nt
	global_store_dwordx4 v76, v[4:7], s[10:11] offset:1024 nt
	global_store_dwordx4 v76, v[8:11], s[10:11] offset:2048 nt
	global_store_dwordx4 v76, v[12:15], s[10:11] offset:3072 nt
	global_store_dwordx4 v172, v[16:19], s[10:11] offset:0 nt
	global_store_dwordx4 v172, v[20:23], s[10:11] offset:1024 nt
	global_store_dwordx4 v172, v[24:27], s[10:11] offset:2048 nt
	global_store_dwordx4 v172, v[28:31], s[10:11] offset:3072 nt
	v_pk_mul_f32 v[158:159], v[0:1], v[0:1]
	v_pk_mul_f32 v[160:161], v[2:3], v[2:3]
	v_pk_fma_f32 v[158:159], v[4:5], v[4:5], v[158:159]
	v_pk_fma_f32 v[160:161], v[6:7], v[6:7], v[160:161]
	v_pk_fma_f32 v[158:159], v[8:9], v[8:9], v[158:159]
	v_pk_fma_f32 v[160:161], v[10:11], v[10:11], v[160:161]
	v_pk_fma_f32 v[158:159], v[12:13], v[12:13], v[158:159]
	v_pk_fma_f32 v[160:161], v[14:15], v[14:15], v[160:161]
	v_pk_fma_f32 v[158:159], v[16:17], v[16:17], v[158:159]
	v_pk_fma_f32 v[160:161], v[18:19], v[18:19], v[160:161]
	v_pk_fma_f32 v[158:159], v[20:21], v[20:21], v[158:159]
	v_pk_fma_f32 v[160:161], v[22:23], v[22:23], v[160:161]
	v_pk_fma_f32 v[158:159], v[24:25], v[24:25], v[158:159]
	v_pk_fma_f32 v[160:161], v[26:27], v[26:27], v[160:161]
	v_pk_fma_f32 v[158:159], v[28:29], v[28:29], v[158:159]
	v_pk_fma_f32 v[160:161], v[30:31], v[30:31], v[160:161]
	v_pk_add_f32 v[158:159], v[158:159], v[160:161]
	s_nop 0
	v_add_f32_e32 v177, v158, v159
	s_nop 1
	v_add_f32_dpp v177, v177, v177 quad_perm:[1,0,3,2] row_mask:0xf bank_mask:0xf
	s_nop 1
	v_add_f32_dpp v177, v177, v177 quad_perm:[2,3,0,1] row_mask:0xf bank_mask:0xf
	s_nop 1
	v_add_f32_dpp v177, v177, v177 row_half_mirror row_mask:0xf bank_mask:0xf
	s_nop 1
	v_add_f32_dpp v177, v177, v177 row_mirror row_mask:0xf bank_mask:0xf
	s_nop 1
	v_add_f32_dpp v177, v177, v177 row_bcast:15 row_mask:0xa bank_mask:0xf
	s_nop 1
	v_add_f32_dpp v177, v177, v177 row_bcast:31 row_mask:0xc bank_mask:0xf
	s_nop 1
	v_readlane_b32 s8, v177, 63
	s_nop 3
	v_mov_b32_e32 v162, s8
	v_fma_f32 v162, v162, v175, v176
	v_rsq_f32_e32 v162, v162
	s_nop 1
	v_pk_mul_f32 v[150:151], v[0:1], v[162:163] op_sel_hi:[1,0]
	v_pk_fma_f32 v[150:151], v[150:151], v[86:87], v[118:119]
	v_cvt_pk_bf16_f32 v164, v150, v151
	v_pk_mul_f32 v[152:153], v[2:3], v[162:163] op_sel_hi:[1,0]
	v_pk_fma_f32 v[152:153], v[152:153], v[88:89], v[120:121]
	v_cvt_pk_bf16_f32 v165, v152, v153
	global_store_dwordx2 v173, v[164:165], s[14:15] offset:0
	v_pk_mul_f32 v[154:155], v[4:5], v[162:163] op_sel_hi:[1,0]
	v_pk_fma_f32 v[154:155], v[154:155], v[90:91], v[122:123]
	v_cvt_pk_bf16_f32 v166, v154, v155
	v_pk_mul_f32 v[156:157], v[6:7], v[162:163] op_sel_hi:[1,0]
	v_pk_fma_f32 v[156:157], v[156:157], v[92:93], v[124:125]
	v_cvt_pk_bf16_f32 v167, v156, v157
	global_store_dwordx2 v173, v[166:167], s[14:15] offset:512
	v_pk_mul_f32 v[150:151], v[8:9], v[162:163] op_sel_hi:[1,0]
	v_pk_fma_f32 v[150:151], v[150:151], v[94:95], v[126:127]
	v_cvt_pk_bf16_f32 v168, v150, v151
	v_pk_mul_f32 v[152:153], v[10:11], v[162:163] op_sel_hi:[1,0]
	v_pk_fma_f32 v[152:153], v[152:153], v[96:97], v[128:129]
	v_cvt_pk_bf16_f32 v169, v152, v153
	global_store_dwordx2 v173, v[168:169], s[14:15] offset:1024
	v_pk_mul_f32 v[154:155], v[12:13], v[162:163] op_sel_hi:[1,0]
	v_pk_fma_f32 v[154:155], v[154:155], v[98:99], v[130:131]
	v_cvt_pk_bf16_f32 v170, v154, v155
	v_pk_mul_f32 v[156:157], v[14:15], v[162:163] op_sel_hi:[1,0]
	v_pk_fma_f32 v[156:157], v[156:157], v[100:101], v[132:133]
	v_cvt_pk_bf16_f32 v171, v156, v157
	global_store_dwordx2 v173, v[170:171], s[14:15] offset:1536
	v_pk_mul_f32 v[150:151], v[16:17], v[162:163] op_sel_hi:[1,0]
	v_pk_fma_f32 v[150:151], v[150:151], v[102:103], v[134:135]
	v_cvt_pk_bf16_f32 v164, v150, v151
	v_pk_mul_f32 v[152:153], v[18:19], v[162:163] op_sel_hi:[1,0]
	v_pk_fma_f32 v[152:153], v[152:153], v[104:105], v[136:137]
	v_cvt_pk_bf16_f32 v165, v152, v153
	global_store_dwordx2 v173, v[164:165], s[14:15] offset:2048
	v_pk_mul_f32 v[154:155], v[20:21], v[162:163] op_sel_hi:[1,0]
	v_pk_fma_f32 v[154:155], v[154:155], v[106:107], v[138:139]
	v_cvt_pk_bf16_f32 v166, v154, v155
	v_pk_mul_f32 v[156:157], v[22:23], v[162:163] op_sel_hi:[1,0]
	v_pk_fma_f32 v[156:157], v[156:157], v[108:109], v[140:141]
	v_cvt_pk_bf16_f32 v167, v156, v157
	global_store_dwordx2 v173, v[166:167], s[14:15] offset:2560
	v_pk_mul_f32 v[150:151], v[24:25], v[162:163] op_sel_hi:[1,0]
	v_pk_fma_f32 v[150:151], v[150:151], v[110:111], v[142:143]
	v_cvt_pk_bf16_f32 v168, v150, v151
	v_pk_mul_f32 v[152:153], v[26:27], v[162:163] op_sel_hi:[1,0]
	v_pk_fma_f32 v[152:153], v[152:153], v[112:113], v[144:145]
	v_cvt_pk_bf16_f32 v169, v152, v153
	global_store_dwordx2 v173, v[168:169], s[14:15] offset:3072
	v_pk_mul_f32 v[154:155], v[28:29], v[162:163] op_sel_hi:[1,0]
	v_pk_fma_f32 v[154:155], v[154:155], v[114:115], v[146:147]
	v_cvt_pk_bf16_f32 v170, v154, v155
	v_pk_mul_f32 v[156:157], v[30:31], v[162:163] op_sel_hi:[1,0]
	v_pk_fma_f32 v[156:157], v[156:157], v[116:117], v[148:149]
	v_cvt_pk_bf16_f32 v171, v156, v157
	global_store_dwordx2 v173, v[170:171], s[14:15] offset:3584
	s_lshr_b32 s1, s3, 9
	s_lshl_b32 s1, s1, 13
	s_and_b32 s8, s3, 0x1ff
	s_add_u32 s1, s1, s8
	s_add_u32 s8, s0, 1
	s_lshl_b32 s8, s8, 9
	s_add_u32 s1, s1, s8
	s_lshl_b32 s8, s1, 13
	s_add_u32 s10, s58, s8
	s_addc_u32 s11, s59, 0
	s_lshl_b32 s8, s1, 12
	s_add_u32 s9, s8, 0xb800000
	s_add_u32 s12, s52, s9
	s_addc_u32 s13, s53, 0
	s_add_u32 s9, s8, 0x2c800000
	s_add_u32 s14, s52, s9
	s_addc_u32 s15, s53, 0
	global_load_dwordx2 v[32:33], v173, s[12:13] offset:0 nt
	global_load_dwordx2 v[34:35], v173, s[12:13] offset:512 nt
	global_load_dwordx2 v[36:37], v173, s[12:13] offset:1024 nt
	global_load_dwordx2 v[38:39], v173, s[12:13] offset:1536 nt
	global_load_dwordx2 v[40:41], v173, s[12:13] offset:2048 nt
	global_load_dwordx2 v[42:43], v173, s[12:13] offset:2560 nt
	global_load_dwordx2 v[44:45], v173, s[12:13] offset:3072 nt
	global_load_dwordx2 v[46:47], v173, s[12:13] offset:3584 nt
	s_cmp_lt_u32 s0, 14
	s_cbranch_scc0 .Lrm1_nopf_o
	s_lshr_b32 s1, s3, 9
	s_lshl_b32 s1, s1, 13
	s_and_b32 s8, s3, 0x1ff
	s_add_u32 s1, s1, s8
	s_add_u32 s8, s0, 2
	s_lshl_b32 s8, s8, 9
	s_add_u32 s1, s1, s8
	s_lshl_b32 s8, s1, 13
	v_readfirstlane_b32 s4, v178
	v_readfirstlane_b32 s5, v179
	s_nop 3
	s_add_u32 s4, s4, s8
	s_addc_u32 s5, s5, 0
	s_nop 1
	global_load_dwordx4 v[0:3], v76, s[4:5] offset:0 nt
	global_load_dwordx4 v[4:7], v76, s[4:5] offset:1024 nt
	global_load_dwordx4 v[8:11], v76, s[4:5] offset:2048 nt
	global_load_dwordx4 v[12:15], v76, s[4:5] offset:3072 nt
	global_load_dwordx4 v[16:19], v172, s[4:5] offset:0 nt
	global_load_dwordx4 v[20:23], v172, s[4:5] offset:1024 nt
	global_load_dwordx4 v[24:27], v172, s[4:5] offset:2048 nt
	global_load_dwordx4 v[28:31], v172, s[4:5] offset:3072 nt
	s_waitcnt vmcnt(8)
	s_branch .Lrm1_pfd_o

.Lrm1_pfd_o:
	v_lshlrev_b32_e32 v150, 16, v32
	v_and_b32_e32 v151, 0xffff0000, v32
	v_pk_mul_f32 v[158:159], v[150:151], v[150:151]
	v_lshlrev_b32_e32 v152, 16, v33
	v_and_b32_e32 v153, 0xffff0000, v33
	v_pk_mul_f32 v[160:161], v[152:153], v[152:153]
	v_lshlrev_b32_e32 v154, 16, v34
	v_and_b32_e32 v155, 0xffff0000, v34
	v_pk_fma_f32 v[158:159], v[154:155], v[154:155], v[158:159]
	v_lshlrev_b32_e32 v156, 16, v35
	v_and_b32_e32 v157, 0xffff0000, v35
	v_pk_fma_f32 v[160:161], v[156:157], v[156:157], v[160:161]
	v_lshlrev_b32_e32 v150, 16, v36
	v_and_b32_e32 v151, 0xffff0000, v36
	v_pk_fma_f32 v[158:159], v[150:151], v[150:151], v[158:159]
	v_lshlrev_b32_e32 v152, 16, v37
	v_and_b32_e32 v153, 0xffff0000, v37
	v_pk_fma_f32 v[160:161], v[152:153], v[152:153], v[160:161]
	v_lshlrev_b32_e32 v154, 16, v38
	v_and_b32_e32 v155, 0xffff0000, v38
	v_pk_fma_f32 v[158:159], v[154:155], v[154:155], v[158:159]
	v_lshlrev_b32_e32 v156, 16, v39
	v_and_b32_e32 v157, 0xffff0000, v39
	v_pk_fma_f32 v[160:161], v[156:157], v[156:157], v[160:161]
	v_lshlrev_b32_e32 v150, 16, v40
	v_and_b32_e32 v151, 0xffff0000, v40
	v_pk_fma_f32 v[158:159], v[150:151], v[150:151], v[158:159]
	v_lshlrev_b32_e32 v152, 16, v41
	v_and_b32_e32 v153, 0xffff0000, v41
	v_pk_fma_f32 v[160:161], v[152:153], v[152:153], v[160:161]
	v_lshlrev_b32_e32 v154, 16, v42
	v_and_b32_e32 v155, 0xffff0000, v42
	v_pk_fma_f32 v[158:159], v[154:155], v[154:155], v[158:159]
	v_lshlrev_b32_e32 v156, 16, v43
	v_and_b32_e32 v157, 0xffff0000, v43
	v_pk_fma_f32 v[160:161], v[156:157], v[156:157], v[160:161]
	v_lshlrev_b32_e32 v150, 16, v44
	v_and_b32_e32 v151, 0xffff0000, v44
	v_pk_fma_f32 v[158:159], v[150:151], v[150:151], v[158:159]
	v_lshlrev_b32_e32 v152, 16, v45
	v_and_b32_e32 v153, 0xffff0000, v45
	v_pk_fma_f32 v[160:161], v[152:153], v[152:153], v[160:161]
	v_lshlrev_b32_e32 v154, 16, v46
	v_and_b32_e32 v155, 0xffff0000, v46
	v_pk_fma_f32 v[158:159], v[154:155], v[154:155], v[158:159]
	v_lshlrev_b32_e32 v156, 16, v47
	v_and_b32_e32 v157, 0xffff0000, v47
	v_pk_fma_f32 v[160:161], v[156:157], v[156:157], v[160:161]
	v_pk_add_f32 v[158:159], v[158:159], v[160:161]
	s_nop 0
	v_add_f32_e32 v177, v158, v159
	s_nop 1
	v_add_f32_dpp v177, v177, v177 quad_perm:[1,0,3,2] row_mask:0xf bank_mask:0xf
	s_nop 1
	v_add_f32_dpp v177, v177, v177 quad_perm:[2,3,0,1] row_mask:0xf bank_mask:0xf
	s_nop 1
	v_add_f32_dpp v177, v177, v177 row_half_mirror row_mask:0xf bank_mask:0xf
	s_nop 1
	v_add_f32_dpp v177, v177, v177 row_mirror row_mask:0xf bank_mask:0xf
	s_nop 1
	v_add_f32_dpp v177, v177, v177 row_bcast:15 row_mask:0xa bank_mask:0xf
	s_nop 1
	v_add_f32_dpp v177, v177, v177 row_bcast:31 row_mask:0xc bank_mask:0xf
	s_nop 1
	v_readlane_b32 s8, v177, 63
	s_nop 3
	v_mov_b32_e32 v162, s8
	v_fma_f32 v162, v162, v175, v176
	v_rsq_f32_e32 v162, v162
	s_nop 1
	v_lshlrev_b32_e32 v150, 16, v32
	v_and_b32_e32 v151, 0xffff0000, v32
	v_pk_mul_f32 v[150:151], v[150:151], v[162:163] op_sel_hi:[1,0]
	v_pk_fma_f32 v[192:193], v[48:49], v[150:151], v[192:193]
	v_lshlrev_b32_e32 v152, 16, v33
	v_and_b32_e32 v153, 0xffff0000, v33
	v_pk_mul_f32 v[152:153], v[152:153], v[162:163] op_sel_hi:[1,0]
	v_pk_fma_f32 v[194:195], v[50:51], v[152:153], v[194:195]
	v_lshlrev_b32_e32 v154, 16, v34
	v_and_b32_e32 v155, 0xffff0000, v34
	v_pk_mul_f32 v[154:155], v[154:155], v[162:163] op_sel_hi:[1,0]
	v_pk_fma_f32 v[196:197], v[52:53], v[154:155], v[196:197]
	v_lshlrev_b32_e32 v156, 16, v35
	v_and_b32_e32 v157, 0xffff0000, v35
	v_pk_mul_f32 v[156:157], v[156:157], v[162:163] op_sel_hi:[1,0]
	v_pk_fma_f32 v[198:199], v[54:55], v[156:157], v[198:199]
	v_lshlrev_b32_e32 v150, 16, v36
	v_and_b32_e32 v151, 0xffff0000, v36
	v_pk_mul_f32 v[150:151], v[150:151], v[162:163] op_sel_hi:[1,0]
	v_pk_fma_f32 v[200:201], v[56:57], v[150:151], v[200:201]
	v_lshlrev_b32_e32 v152, 16, v37
	v_and_b32_e32 v153, 0xffff0000, v37
	v_pk_mul_f32 v[152:153], v[152:153], v[162:163] op_sel_hi:[1,0]
	v_pk_fma_f32 v[202:203], v[58:59], v[152:153], v[202:203]
	v_lshlrev_b32_e32 v154, 16, v38
	v_and_b32_e32 v155, 0xffff0000, v38
	v_pk_mul_f32 v[154:155], v[154:155], v[162:163] op_sel_hi:[1,0]
	v_pk_fma_f32 v[204:205], v[60:61], v[154:155], v[204:205]
	v_lshlrev_b32_e32 v156, 16, v39
	v_and_b32_e32 v157, 0xffff0000, v39
	v_pk_mul_f32 v[156:157], v[156:157], v[162:163] op_sel_hi:[1,0]
	v_pk_fma_f32 v[206:207], v[62:63], v[156:157], v[206:207]
	v_lshlrev_b32_e32 v150, 16, v40
	v_and_b32_e32 v151, 0xffff0000, v40
	v_pk_mul_f32 v[150:151], v[150:151], v[162:163] op_sel_hi:[1,0]
	v_pk_fma_f32 v[208:209], v[64:65], v[150:151], v[208:209]
	v_lshlrev_b32_e32 v152, 16, v41
	v_and_b32_e32 v153, 0xffff0000, v41
	v_pk_mul_f32 v[152:153], v[152:153], v[162:163] op_sel_hi:[1,0]
	v_pk_fma_f32 v[210:211], v[66:67], v[152:153], v[210:211]
	v_lshlrev_b32_e32 v154, 16, v42
	v_and_b32_e32 v155, 0xffff0000, v42
	v_pk_mul_f32 v[154:155], v[154:155], v[162:163] op_sel_hi:[1,0]
	v_pk_fma_f32 v[216:217], v[68:69], v[154:155], v[216:217]
	v_lshlrev_b32_e32 v156, 16, v43
	v_and_b32_e32 v157, 0xffff0000, v43
	v_pk_mul_f32 v[156:157], v[156:157], v[162:163] op_sel_hi:[1,0]
	v_pk_fma_f32 v[218:219], v[70:71], v[156:157], v[218:219]
	v_lshlrev_b32_e32 v150, 16, v44
	v_and_b32_e32 v151, 0xffff0000, v44
	v_pk_mul_f32 v[150:151], v[150:151], v[162:163] op_sel_hi:[1,0]
	v_pk_fma_f32 v[224:225], v[72:73], v[150:151], v[224:225]
	v_lshlrev_b32_e32 v152, 16, v45
	v_and_b32_e32 v153, 0xffff0000, v45
	v_pk_mul_f32 v[152:153], v[152:153], v[162:163] op_sel_hi:[1,0]
	v_pk_fma_f32 v[226:227], v[74:75], v[152:153], v[226:227]
	v_lshlrev_b32_e32 v154, 16, v46
	v_and_b32_e32 v155, 0xffff0000, v46
	v_pk_mul_f32 v[154:155], v[154:155], v[162:163] op_sel_hi:[1,0]
	v_pk_fma_f32 v[236:237], v[82:83], v[154:155], v[236:237]
	v_lshlrev_b32_e32 v156, 16, v47
	v_and_b32_e32 v157, 0xffff0000, v47
	v_pk_mul_f32 v[156:157], v[156:157], v[162:163] op_sel_hi:[1,0]
	v_pk_fma_f32 v[238:239], v[84:85], v[156:157], v[238:239]
	s_nop 0
	global_store_dwordx4 v76, v[192:195], s[10:11] offset:0 nt
	global_store_dwordx4 v76, v[196:199], s[10:11] offset:1024 nt
	global_store_dwordx4 v76, v[200:203], s[10:11] offset:2048 nt
	global_store_dwordx4 v76, v[204:207], s[10:11] offset:3072 nt
	global_store_dwordx4 v172, v[208:211], s[10:11] offset:0 nt
	global_store_dwordx4 v172, v[216:219], s[10:11] offset:1024 nt
	global_store_dwordx4 v172, v[224:227], s[10:11] offset:2048 nt
	global_store_dwordx4 v172, v[236:239], s[10:11] offset:3072 nt
	v_pk_mul_f32 v[158:159], v[192:193], v[192:193]
	v_pk_mul_f32 v[160:161], v[194:195], v[194:195]
	v_pk_fma_f32 v[158:159], v[196:197], v[196:197], v[158:159]
	v_pk_fma_f32 v[160:161], v[198:199], v[198:199], v[160:161]
	v_pk_fma_f32 v[158:159], v[200:201], v[200:201], v[158:159]
	v_pk_fma_f32 v[160:161], v[202:203], v[202:203], v[160:161]
	v_pk_fma_f32 v[158:159], v[204:205], v[204:205], v[158:159]
	v_pk_fma_f32 v[160:161], v[206:207], v[206:207], v[160:161]
	v_pk_fma_f32 v[158:159], v[208:209], v[208:209], v[158:159]
	v_pk_fma_f32 v[160:161], v[210:211], v[210:211], v[160:161]
	v_pk_fma_f32 v[158:159], v[216:217], v[216:217], v[158:159]
	v_pk_fma_f32 v[160:161], v[218:219], v[218:219], v[160:161]
	v_pk_fma_f32 v[158:159], v[224:225], v[224:225], v[158:159]
	v_pk_fma_f32 v[160:161], v[226:227], v[226:227], v[160:161]
	v_pk_fma_f32 v[158:159], v[236:237], v[236:237], v[158:159]
	v_pk_fma_f32 v[160:161], v[238:239], v[238:239], v[160:161]
	v_pk_add_f32 v[158:159], v[158:159], v[160:161]
	s_nop 0
	v_add_f32_e32 v177, v158, v159
	s_nop 1
	v_add_f32_dpp v177, v177, v177 quad_perm:[1,0,3,2] row_mask:0xf bank_mask:0xf
	s_nop 1
	v_add_f32_dpp v177, v177, v177 quad_perm:[2,3,0,1] row_mask:0xf bank_mask:0xf
	s_nop 1
	v_add_f32_dpp v177, v177, v177 row_half_mirror row_mask:0xf bank_mask:0xf
	s_nop 1
	v_add_f32_dpp v177, v177, v177 row_mirror row_mask:0xf bank_mask:0xf
	s_nop 1
	v_add_f32_dpp v177, v177, v177 row_bcast:15 row_mask:0xa bank_mask:0xf
	s_nop 1
	v_add_f32_dpp v177, v177, v177 row_bcast:31 row_mask:0xc bank_mask:0xf
	s_nop 1
	v_readlane_b32 s8, v177, 63
	s_nop 3
	v_mov_b32_e32 v162, s8
	v_fma_f32 v162, v162, v175, v176
	v_rsq_f32_e32 v162, v162
	s_nop 1
	v_pk_mul_f32 v[150:151], v[192:193], v[162:163] op_sel_hi:[1,0]
	v_pk_fma_f32 v[150:151], v[150:151], v[86:87], v[118:119]
	v_cvt_pk_bf16_f32 v164, v150, v151
	v_pk_mul_f32 v[152:153], v[194:195], v[162:163] op_sel_hi:[1,0]
	v_pk_fma_f32 v[152:153], v[152:153], v[88:89], v[120:121]
	v_cvt_pk_bf16_f32 v165, v152, v153
	global_store_dwordx2 v173, v[164:165], s[14:15] offset:0
	v_pk_mul_f32 v[154:155], v[196:197], v[162:163] op_sel_hi:[1,0]
	v_pk_fma_f32 v[154:155], v[154:155], v[90:91], v[122:123]
	v_cvt_pk_bf16_f32 v166, v154, v155
	v_pk_mul_f32 v[156:157], v[198:199], v[162:163] op_sel_hi:[1,0]
	v_pk_fma_f32 v[156:157], v[156:157], v[92:93], v[124:125]
	v_cvt_pk_bf16_f32 v167, v156, v157
	global_store_dwordx2 v173, v[166:167], s[14:15] offset:512
	v_pk_mul_f32 v[150:151], v[200:201], v[162:163] op_sel_hi:[1,0]
	v_pk_fma_f32 v[150:151], v[150:151], v[94:95], v[126:127]
	v_cvt_pk_bf16_f32 v168, v150, v151
	v_pk_mul_f32 v[152:153], v[202:203], v[162:163] op_sel_hi:[1,0]
	v_pk_fma_f32 v[152:153], v[152:153], v[96:97], v[128:129]
	v_cvt_pk_bf16_f32 v169, v152, v153
	global_store_dwordx2 v173, v[168:169], s[14:15] offset:1024
	v_pk_mul_f32 v[154:155], v[204:205], v[162:163] op_sel_hi:[1,0]
	v_pk_fma_f32 v[154:155], v[154:155], v[98:99], v[130:131]
	v_cvt_pk_bf16_f32 v170, v154, v155
	v_pk_mul_f32 v[156:157], v[206:207], v[162:163] op_sel_hi:[1,0]
	v_pk_fma_f32 v[156:157], v[156:157], v[100:101], v[132:133]
	v_cvt_pk_bf16_f32 v171, v156, v157
	global_store_dwordx2 v173, v[170:171], s[14:15] offset:1536
	v_pk_mul_f32 v[150:151], v[208:209], v[162:163] op_sel_hi:[1,0]
	v_pk_fma_f32 v[150:151], v[150:151], v[102:103], v[134:135]
	v_cvt_pk_bf16_f32 v164, v150, v151
	v_pk_mul_f32 v[152:153], v[210:211], v[162:163] op_sel_hi:[1,0]
	v_pk_fma_f32 v[152:153], v[152:153], v[104:105], v[136:137]
	v_cvt_pk_bf16_f32 v165, v152, v153
	global_store_dwordx2 v173, v[164:165], s[14:15] offset:2048
	v_pk_mul_f32 v[154:155], v[216:217], v[162:163] op_sel_hi:[1,0]
	v_pk_fma_f32 v[154:155], v[154:155], v[106:107], v[138:139]
	v_cvt_pk_bf16_f32 v166, v154, v155
	v_pk_mul_f32 v[156:157], v[218:219], v[162:163] op_sel_hi:[1,0]
	v_pk_fma_f32 v[156:157], v[156:157], v[108:109], v[140:141]
	v_cvt_pk_bf16_f32 v167, v156, v157
	global_store_dwordx2 v173, v[166:167], s[14:15] offset:2560
	v_pk_mul_f32 v[150:151], v[224:225], v[162:163] op_sel_hi:[1,0]
	v_pk_fma_f32 v[150:151], v[150:151], v[110:111], v[142:143]
	v_cvt_pk_bf16_f32 v168, v150, v151
	v_pk_mul_f32 v[152:153], v[226:227], v[162:163] op_sel_hi:[1,0]
	v_pk_fma_f32 v[152:153], v[152:153], v[112:113], v[144:145]
	v_cvt_pk_bf16_f32 v169, v152, v153
	global_store_dwordx2 v173, v[168:169], s[14:15] offset:3072
	v_pk_mul_f32 v[154:155], v[236:237], v[162:163] op_sel_hi:[1,0]
	v_pk_fma_f32 v[154:155], v[154:155], v[114:115], v[146:147]
	v_cvt_pk_bf16_f32 v170, v154, v155
	v_pk_mul_f32 v[156:157], v[238:239], v[162:163] op_sel_hi:[1,0]
	v_pk_fma_f32 v[156:157], v[156:157], v[116:117], v[148:149]
	v_cvt_pk_bf16_f32 v171, v156, v157
	global_store_dwordx2 v173, v[170:171], s[14:15] offset:3584
	s_add_u32 s0, s0, 2
	s_cmp_lt_u32 s0, 16
	s_cbranch_scc1 .Lrm1_loop
	s_bitcmp1_b32 s3, 0
	s_cbranch_scc1 .Lrm1_done
	s_mov_b32 s2, 4
	s_branch .Lrm1_coef
.Lrm1_ctxrow:
	s_lshr_b32 s8, s3, 1
	s_lshl_b32 s8, s8, 13
	v_readfirstlane_b32 s4, v180
	v_readfirstlane_b32 s5, v181
	s_nop 3
	s_add_u32 s4, s4, s8
	s_addc_u32 s5, s5, 0
	s_nop 1
	global_load_dwordx4 v[0:3], v76, s[4:5] offset:0 nt
	global_load_dwordx4 v[4:7], v76, s[4:5] offset:1024 nt
	global_load_dwordx4 v[8:11], v76, s[4:5] offset:2048 nt
	global_load_dwordx4 v[12:15], v76, s[4:5] offset:3072 nt
	global_load_dwordx4 v[16:19], v172, s[4:5] offset:0 nt
	global_load_dwordx4 v[20:23], v172, s[4:5] offset:1024 nt
	global_load_dwordx4 v[24:27], v172, s[4:5] offset:2048 nt
	global_load_dwordx4 v[28:31], v172, s[4:5] offset:3072 nt
	s_lshr_b32 s8, s3, 1
	s_add_u32 s1, s8, 0x8000
	s_lshl_b32 s8, s8, 13
	s_add_u32 s9, s8, 0x3d000000
	s_add_u32 s10, s52, s9
	s_addc_u32 s11, s53, 0
	s_lshl_b32 s8, s1, 12
	s_add_u32 s9, s8, 0xb800000
	s_add_u32 s12, s52, s9
	s_addc_u32 s13, s53, 0
	s_add_u32 s9, s8, 0x2c800000
	s_add_u32 s14, s52, s9
	s_addc_u32 s15, s53, 0
	global_load_dwordx2 v[32:33], v173, s[12:13] offset:0 nt
	global_load_dwordx2 v[34:35], v173, s[12:13] offset:512 nt
	global_load_dwordx2 v[36:37], v173, s[12:13] offset:1024 nt
	global_load_dwordx2 v[38:39], v173, s[12:13] offset:1536 nt
	global_load_dwordx2 v[40:41], v173, s[12:13] offset:2048 nt
	global_load_dwordx2 v[42:43], v173, s[12:13] offset:2560 nt
	global_load_dwordx2 v[44:45], v173, s[12:13] offset:3072 nt
	global_load_dwordx2 v[46:47], v173, s[12:13] offset:3584 nt
	s_waitcnt vmcnt(0)
	v_lshlrev_b32_e32 v150, 16, v32
	v_and_b32_e32 v151, 0xffff0000, v32
	v_pk_mul_f32 v[158:159], v[150:151], v[150:151]
	v_lshlrev_b32_e32 v152, 16, v33
	v_and_b32_e32 v153, 0xffff0000, v33
	v_pk_mul_f32 v[160:161], v[152:153], v[152:153]
	v_lshlrev_b32_e32 v154, 16, v34
	v_and_b32_e32 v155, 0xffff0000, v34
	v_pk_fma_f32 v[158:159], v[154:155], v[154:155], v[158:159]
	v_lshlrev_b32_e32 v156, 16, v35
	v_and_b32_e32 v157, 0xffff0000, v35
	v_pk_fma_f32 v[160:161], v[156:157], v[156:157], v[160:161]
	v_lshlrev_b32_e32 v150, 16, v36
	v_and_b32_e32 v151, 0xffff0000, v36
	v_pk_fma_f32 v[158:159], v[150:151], v[150:151], v[158:159]
	v_lshlrev_b32_e32 v152, 16, v37
	v_and_b32_e32 v153, 0xffff0000, v37
	v_pk_fma_f32 v[160:161], v[152:153], v[152:153], v[160:161]
	v_lshlrev_b32_e32 v154, 16, v38
	v_and_b32_e32 v155, 0xffff0000, v38
	v_pk_fma_f32 v[158:159], v[154:155], v[154:155], v[158:159]
	v_lshlrev_b32_e32 v156, 16, v39
	v_and_b32_e32 v157, 0xffff0000, v39
	v_pk_fma_f32 v[160:161], v[156:157], v[156:157], v[160:161]
	v_lshlrev_b32_e32 v150, 16, v40
	v_and_b32_e32 v151, 0xffff0000, v40
	v_pk_fma_f32 v[158:159], v[150:151], v[150:151], v[158:159]
	v_lshlrev_b32_e32 v152, 16, v41
	v_and_b32_e32 v153, 0xffff0000, v41
	v_pk_fma_f32 v[160:161], v[152:153], v[152:153], v[160:161]
	v_lshlrev_b32_e32 v154, 16, v42
	v_and_b32_e32 v155, 0xffff0000, v42
	v_pk_fma_f32 v[158:159], v[154:155], v[154:155], v[158:159]
	v_lshlrev_b32_e32 v156, 16, v43
	v_and_b32_e32 v157, 0xffff0000, v43
	v_pk_fma_f32 v[160:161], v[156:157], v[156:157], v[160:161]
	v_lshlrev_b32_e32 v150, 16, v44
	v_and_b32_e32 v151, 0xffff0000, v44
	v_pk_fma_f32 v[158:159], v[150:151], v[150:151], v[158:159]
	v_lshlrev_b32_e32 v152, 16, v45
	v_and_b32_e32 v153, 0xffff0000, v45
	v_pk_fma_f32 v[160:161], v[152:153], v[152:153], v[160:161]
	v_lshlrev_b32_e32 v154, 16, v46
	v_and_b32_e32 v155, 0xffff0000, v46
	v_pk_fma_f32 v[158:159], v[154:155], v[154:155], v[158:159]
	v_lshlrev_b32_e32 v156, 16, v47
	v_and_b32_e32 v157, 0xffff0000, v47
	v_pk_fma_f32 v[160:161], v[156:157], v[156:157], v[160:161]
	v_pk_add_f32 v[158:159], v[158:159], v[160:161]
	s_nop 0
	v_add_f32_e32 v177, v158, v159
	s_nop 1
	v_add_f32_dpp v177, v177, v177 quad_perm:[1,0,3,2] row_mask:0xf bank_mask:0xf
	s_nop 1
	v_add_f32_dpp v177, v177, v177 quad_perm:[2,3,0,1] row_mask:0xf bank_mask:0xf
	s_nop 1
	v_add_f32_dpp v177, v177, v177 row_half_mirror row_mask:0xf bank_mask:0xf
	s_nop 1
	v_add_f32_dpp v177, v177, v177 row_mirror row_mask:0xf bank_mask:0xf
	s_nop 1
	v_add_f32_dpp v177, v177, v177 row_bcast:15 row_mask:0xa bank_mask:0xf
	s_nop 1
	v_add_f32_dpp v177, v177, v177 row_bcast:31 row_mask:0xc bank_mask:0xf
	s_nop 1
	v_readlane_b32 s8, v177, 63
	s_nop 3
	v_mov_b32_e32 v162, s8
	v_fma_f32 v162, v162, v175, v176
	v_rsq_f32_e32 v162, v162
	s_nop 1
	v_lshlrev_b32_e32 v150, 16, v32
	v_and_b32_e32 v151, 0xffff0000, v32
	v_pk_mul_f32 v[150:151], v[150:151], v[162:163] op_sel_hi:[1,0]
	v_pk_fma_f32 v[0:1], v[48:49], v[150:151], v[0:1]
	v_lshlrev_b32_e32 v152, 16, v33
	v_and_b32_e32 v153, 0xffff0000, v33
	v_pk_mul_f32 v[152:153], v[152:153], v[162:163] op_sel_hi:[1,0]
	v_pk_fma_f32 v[2:3], v[50:51], v[152:153], v[2:3]
	v_lshlrev_b32_e32 v154, 16, v34
	v_and_b32_e32 v155, 0xffff0000, v34
	v_pk_mul_f32 v[154:155], v[154:155], v[162:163] op_sel_hi:[1,0]
	v_pk_fma_f32 v[4:5], v[52:53], v[154:155], v[4:5]
	v_lshlrev_b32_e32 v156, 16, v35
	v_and_b32_e32 v157, 0xffff0000, v35
	v_pk_mul_f32 v[156:157], v[156:157], v[162:163] op_sel_hi:[1,0]
	v_pk_fma_f32 v[6:7], v[54:55], v[156:157], v[6:7]
	v_lshlrev_b32_e32 v150, 16, v36
	v_and_b32_e32 v151, 0xffff0000, v36
	v_pk_mul_f32 v[150:151], v[150:151], v[162:163] op_sel_hi:[1,0]
	v_pk_fma_f32 v[8:9], v[56:57], v[150:151], v[8:9]
	v_lshlrev_b32_e32 v152, 16, v37
	v_and_b32_e32 v153, 0xffff0000, v37
	v_pk_mul_f32 v[152:153], v[152:153], v[162:163] op_sel_hi:[1,0]
	v_pk_fma_f32 v[10:11], v[58:59], v[152:153], v[10:11]
	v_lshlrev_b32_e32 v154, 16, v38
	v_and_b32_e32 v155, 0xffff0000, v38
	v_pk_mul_f32 v[154:155], v[154:155], v[162:163] op_sel_hi:[1,0]
	v_pk_fma_f32 v[12:13], v[60:61], v[154:155], v[12:13]
	v_lshlrev_b32_e32 v156, 16, v39
	v_and_b32_e32 v157, 0xffff0000, v39
	v_pk_mul_f32 v[156:157], v[156:157], v[162:163] op_sel_hi:[1,0]
	v_pk_fma_f32 v[14:15], v[62:63], v[156:157], v[14:15]
	v_lshlrev_b32_e32 v150, 16, v40
	v_and_b32_e32 v151, 0xffff0000, v40
	v_pk_mul_f32 v[150:151], v[150:151], v[162:163] op_sel_hi:[1,0]
	v_pk_fma_f32 v[16:17], v[64:65], v[150:151], v[16:17]
	v_lshlrev_b32_e32 v152, 16, v41
	v_and_b32_e32 v153, 0xffff0000, v41
	v_pk_mul_f32 v[152:153], v[152:153], v[162:163] op_sel_hi:[1,0]
	v_pk_fma_f32 v[18:19], v[66:67], v[152:153], v[18:19]
	v_lshlrev_b32_e32 v154, 16, v42
	v_and_b32_e32 v155, 0xffff0000, v42
	v_pk_mul_f32 v[154:155], v[154:155], v[162:163] op_sel_hi:[1,0]
	v_pk_fma_f32 v[20:21], v[68:69], v[154:155], v[20:21]
	v_lshlrev_b32_e32 v156, 16, v43
	v_and_b32_e32 v157, 0xffff0000, v43
	v_pk_mul_f32 v[156:157], v[156:157], v[162:163] op_sel_hi:[1,0]
	v_pk_fma_f32 v[22:23], v[70:71], v[156:157], v[22:23]
	v_lshlrev_b32_e32 v150, 16, v44
	v_and_b32_e32 v151, 0xffff0000, v44
	v_pk_mul_f32 v[150:151], v[150:151], v[162:163] op_sel_hi:[1,0]
	v_pk_fma_f32 v[24:25], v[72:73], v[150:151], v[24:25]
	v_lshlrev_b32_e32 v152, 16, v45
	v_and_b32_e32 v153, 0xffff0000, v45
	v_pk_mul_f32 v[152:153], v[152:153], v[162:163] op_sel_hi:[1,0]
	v_pk_fma_f32 v[26:27], v[74:75], v[152:153], v[26:27]
	v_lshlrev_b32_e32 v154, 16, v46
	v_and_b32_e32 v155, 0xffff0000, v46
	v_pk_mul_f32 v[154:155], v[154:155], v[162:163] op_sel_hi:[1,0]
	v_pk_fma_f32 v[28:29], v[82:83], v[154:155], v[28:29]
	v_lshlrev_b32_e32 v156, 16, v47
	v_and_b32_e32 v157, 0xffff0000, v47
	v_pk_mul_f32 v[156:157], v[156:157], v[162:163] op_sel_hi:[1,0]
	v_pk_fma_f32 v[30:31], v[84:85], v[156:157], v[30:31]
	s_nop 0
	global_store_dwordx4 v76, v[0:3], s[10:11] offset:0 nt
	global_store_dwordx4 v76, v[4:7], s[10:11] offset:1024 nt
	global_store_dwordx4 v76, v[8:11], s[10:11] offset:2048 nt
	global_store_dwordx4 v76, v[12:15], s[10:11] offset:3072 nt
	global_store_dwordx4 v172, v[16:19], s[10:11] offset:0 nt
	global_store_dwordx4 v172, v[20:23], s[10:11] offset:1024 nt
	global_store_dwordx4 v172, v[24:27], s[10:11] offset:2048 nt
	global_store_dwordx4 v172, v[28:31], s[10:11] offset:3072 nt
	v_pk_mul_f32 v[158:159], v[0:1], v[0:1]
	v_pk_mul_f32 v[160:161], v[2:3], v[2:3]
	v_pk_fma_f32 v[158:159], v[4:5], v[4:5], v[158:159]
	v_pk_fma_f32 v[160:161], v[6:7], v[6:7], v[160:161]
	v_pk_fma_f32 v[158:159], v[8:9], v[8:9], v[158:159]
	v_pk_fma_f32 v[160:161], v[10:11], v[10:11], v[160:161]
	v_pk_fma_f32 v[158:159], v[12:13], v[12:13], v[158:159]
	v_pk_fma_f32 v[160:161], v[14:15], v[14:15], v[160:161]
	v_pk_fma_f32 v[158:159], v[16:17], v[16:17], v[158:159]
	v_pk_fma_f32 v[160:161], v[18:19], v[18:19], v[160:161]
	v_pk_fma_f32 v[158:159], v[20:21], v[20:21], v[158:159]
	v_pk_fma_f32 v[160:161], v[22:23], v[22:23], v[160:161]
	v_pk_fma_f32 v[158:159], v[24:25], v[24:25], v[158:159]
	v_pk_fma_f32 v[160:161], v[26:27], v[26:27], v[160:161]
	v_pk_fma_f32 v[158:159], v[28:29], v[28:29], v[158:159]
	v_pk_fma_f32 v[160:161], v[30:31], v[30:31], v[160:161]
	v_pk_add_f32 v[158:159], v[158:159], v[160:161]
	s_nop 0
	v_add_f32_e32 v177, v158, v159
	s_nop 1
	v_add_f32_dpp v177, v177, v177 quad_perm:[1,0,3,2] row_mask:0xf bank_mask:0xf
	s_nop 1
	v_add_f32_dpp v177, v177, v177 quad_perm:[2,3,0,1] row_mask:0xf bank_mask:0xf
	s_nop 1
	v_add_f32_dpp v177, v177, v177 row_half_mirror row_mask:0xf bank_mask:0xf
	s_nop 1
	v_add_f32_dpp v177, v177, v177 row_mirror row_mask:0xf bank_mask:0xf
	s_nop 1
	v_add_f32_dpp v177, v177, v177 row_bcast:15 row_mask:0xa bank_mask:0xf
	s_nop 1
	v_add_f32_dpp v177, v177, v177 row_bcast:31 row_mask:0xc bank_mask:0xf
	s_nop 1
	v_readlane_b32 s8, v177, 63
	s_nop 3
	v_mov_b32_e32 v162, s8
	v_fma_f32 v162, v162, v175, v176
	v_rsq_f32_e32 v162, v162
	s_nop 1
	v_pk_mul_f32 v[150:151], v[0:1], v[162:163] op_sel_hi:[1,0]
	v_pk_fma_f32 v[150:151], v[150:151], v[86:87], v[118:119]
	v_cvt_pk_bf16_f32 v164, v150, v151
	v_pk_mul_f32 v[152:153], v[2:3], v[162:163] op_sel_hi:[1,0]
	v_pk_fma_f32 v[152:153], v[152:153], v[88:89], v[120:121]
	v_cvt_pk_bf16_f32 v165, v152, v153
	global_store_dwordx2 v173, v[164:165], s[14:15] offset:0
	v_pk_mul_f32 v[154:155], v[4:5], v[162:163] op_sel_hi:[1,0]
	v_pk_fma_f32 v[154:155], v[154:155], v[90:91], v[122:123]
	v_cvt_pk_bf16_f32 v166, v154, v155
	v_pk_mul_f32 v[156:157], v[6:7], v[162:163] op_sel_hi:[1,0]
	v_pk_fma_f32 v[156:157], v[156:157], v[92:93], v[124:125]
	v_cvt_pk_bf16_f32 v167, v156, v157
	global_store_dwordx2 v173, v[166:167], s[14:15] offset:512
	v_pk_mul_f32 v[150:151], v[8:9], v[162:163] op_sel_hi:[1,0]
	v_pk_fma_f32 v[150:151], v[150:151], v[94:95], v[126:127]
	v_cvt_pk_bf16_f32 v168, v150, v151
	v_pk_mul_f32 v[152:153], v[10:11], v[162:163] op_sel_hi:[1,0]
	v_pk_fma_f32 v[152:153], v[152:153], v[96:97], v[128:129]
	v_cvt_pk_bf16_f32 v169, v152, v153
	global_store_dwordx2 v173, v[168:169], s[14:15] offset:1024
	v_pk_mul_f32 v[154:155], v[12:13], v[162:163] op_sel_hi:[1,0]
	v_pk_fma_f32 v[154:155], v[154:155], v[98:99], v[130:131]
	v_cvt_pk_bf16_f32 v170, v154, v155
	v_pk_mul_f32 v[156:157], v[14:15], v[162:163] op_sel_hi:[1,0]
	v_pk_fma_f32 v[156:157], v[156:157], v[100:101], v[132:133]
	v_cvt_pk_bf16_f32 v171, v156, v157
	global_store_dwordx2 v173, v[170:171], s[14:15] offset:1536
	v_pk_mul_f32 v[150:151], v[16:17], v[162:163] op_sel_hi:[1,0]
	v_pk_fma_f32 v[150:151], v[150:151], v[102:103], v[134:135]
	v_cvt_pk_bf16_f32 v164, v150, v151
	v_pk_mul_f32 v[152:153], v[18:19], v[162:163] op_sel_hi:[1,0]
	v_pk_fma_f32 v[152:153], v[152:153], v[104:105], v[136:137]
	v_cvt_pk_bf16_f32 v165, v152, v153
	global_store_dwordx2 v173, v[164:165], s[14:15] offset:2048
	v_pk_mul_f32 v[154:155], v[20:21], v[162:163] op_sel_hi:[1,0]
	v_pk_fma_f32 v[154:155], v[154:155], v[106:107], v[138:139]
	v_cvt_pk_bf16_f32 v166, v154, v155
	v_pk_mul_f32 v[156:157], v[22:23], v[162:163] op_sel_hi:[1,0]
	v_pk_fma_f32 v[156:157], v[156:157], v[108:109], v[140:141]
	v_cvt_pk_bf16_f32 v167, v156, v157
	global_store_dwordx2 v173, v[166:167], s[14:15] offset:2560
	v_pk_mul_f32 v[150:151], v[24:25], v[162:163] op_sel_hi:[1,0]
	v_pk_fma_f32 v[150:151], v[150:151], v[110:111], v[142:143]
	v_cvt_pk_bf16_f32 v168, v150, v151
	v_pk_mul_f32 v[152:153], v[26:27], v[162:163] op_sel_hi:[1,0]
	v_pk_fma_f32 v[152:153], v[152:153], v[112:113], v[144:145]
	v_cvt_pk_bf16_f32 v169, v152, v153
	global_store_dwordx2 v173, v[168:169], s[14:15] offset:3072
	v_pk_mul_f32 v[154:155], v[28:29], v[162:163] op_sel_hi:[1,0]
	v_pk_fma_f32 v[154:155], v[154:155], v[114:115], v[146:147]
	v_cvt_pk_bf16_f32 v170, v154, v155
	v_pk_mul_f32 v[156:157], v[30:31], v[162:163] op_sel_hi:[1,0]
	v_pk_fma_f32 v[156:157], v[156:157], v[116:117], v[148:149]
	v_cvt_pk_bf16_f32 v171, v156, v157
	global_store_dwordx2 v173, v[170:171], s[14:15] offset:3584

.Lrm1_orig:
	v_lshlrev_b32_e32 v5, 2, v5
	v_and_b32_e32 v6, 0xfc, v5
	v_or_b32_e32 v16, 0x400, v6
	v_or_b32_e32 v20, 0x500, v6
	v_or_b32_e32 v24, 0x600, v6
	v_or_b32_e32 v28, 0x700, v6
	v_lshlrev_b32_e32 v8, 2, v6
	v_mov_b32_e32 v9, v77
	v_lshlrev_b32_e32 v18, 2, v16
	v_mov_b32_e32 v19, v77
	v_lshlrev_b32_e32 v22, 2, v20
	v_mov_b32_e32 v23, v77
	v_lshlrev_b32_e32 v26, 2, v24
	v_mov_b32_e32 v27, v77
	v_lshlrev_b32_e32 v30, 2, v28
	v_mov_b32_e32 v31, v77
	s_waitcnt vmcnt(0)
	v_lshl_add_u64 v[84:85], v[0:1], 0, v[8:9]
	v_lshl_add_u64 v[86:87], v[0:1], 0, v[18:19]
	v_lshl_add_u64 v[88:89], v[0:1], 0, v[22:23]
	v_lshl_add_u64 v[90:91], v[0:1], 0, v[26:27]
	v_lshl_add_u64 v[92:93], v[0:1], 0, v[30:31]
	v_mbcnt_hi_u32_b32 v0, -1, v190
	v_and_b32_e32 v1, 64, v0
	v_lshl_add_u64 v[94:95], v[2:3], 0, v[8:9]
	v_lshl_add_u64 v[96:97], v[2:3], 0, v[18:19]
	v_lshl_add_u64 v[98:99], v[2:3], 0, v[22:23]
	v_lshl_add_u64 v[100:101], v[2:3], 0, v[26:27]
	v_lshl_add_u64 v[102:103], v[2:3], 0, v[30:31]
	v_add_u32_e32 v1, 64, v1
	v_xor_b32_e32 v2, 32, v0
	v_cmp_lt_i32_e32 vcc, v2, v1
	s_add_u32 s8, s52, 0x3d804000
	s_addc_u32 s9, s53, 0
	v_cndmask_b32_e32 v2, v0, v2, vcc
	v_lshlrev_b32_e32 v183, 2, v2
	v_xor_b32_e32 v2, 16, v0
	v_cmp_lt_i32_e32 vcc, v2, v1
	v_lshlrev_b32_e32 v76, 1, v6
	s_cmp_lg_u64 s[58:59], 0
	v_cndmask_b32_e32 v2, v0, v2, vcc
	v_lshlrev_b32_e32 v184, 2, v2
	v_xor_b32_e32 v2, 8, v0
	v_cmp_lt_i32_e32 vcc, v2, v1
	v_or_b32_e32 v10, 0x100, v6
	v_or_b32_e32 v12, 0x200, v6
	v_cndmask_b32_e32 v2, v0, v2, vcc
	v_lshlrev_b32_e32 v185, 2, v2
	v_xor_b32_e32 v2, 4, v0
	v_cmp_lt_i32_e32 vcc, v2, v1
	v_or_b32_e32 v14, 0x300, v6
	v_lshl_add_u64 v[82:83], s[60:61], 0, v[76:77]
	v_cndmask_b32_e32 v2, v0, v2, vcc
	v_lshlrev_b32_e32 v186, 2, v2
	v_xor_b32_e32 v2, 2, v0
	v_cmp_lt_i32_e32 vcc, v2, v1
	s_mov_b64 s[10:11], 0
	s_cselect_b64 s[12:13], -1, 0
	v_cndmask_b32_e32 v2, v0, v2, vcc
	v_lshlrev_b32_e32 v187, 2, v2
	v_xor_b32_e32 v2, 1, v0
	v_cmp_lt_i32_e32 vcc, v2, v1
	v_lshl_add_u64 v[104:105], s[62:63], 0, v[76:77]
	s_lshl_b32 s4, s54, 4
	v_cndmask_b32_e32 v0, v0, v2, vcc
	v_lshlrev_b32_e32 v188, 2, v0
	v_lshlrev_b32_e32 v0, 1, v4
	v_lshl_add_u32 v106, s0, 4, v0
	s_movk_i32 s5, 0x4000
	s_movk_i32 s15, 0x3000
	s_movk_i32 s20, 0x1000
	s_movk_i32 s21, 0x2000
	s_mov_b32 s14, 0x3a000000
	s_mov_b32 s22, 0x800000
	v_lshlrev_b32_e32 v108, 2, v16
	v_lshlrev_b32_e32 v110, 2, v20
	v_lshlrev_b32_e32 v112, 2, v24
	v_lshlrev_b32_e32 v114, 2, v28
	s_mov_b64 s[16:17], 0x6000
	s_mov_b64 s[18:19], 0x8000
	v_lshlrev_b32_e32 v76, 2, v6
	v_lshlrev_b32_e32 v116, 2, v10
	v_lshlrev_b32_e32 v118, 2, v12
	v_lshlrev_b32_e32 v120, 2, v14
	s_movk_i32 s23, 0x41ff
	v_mov_b32_e32 v122, 0x358637bd
	s_branch .LBB0_981

.LBB0_1199:
	s_or_b64 exec, exec, s[0:1]
	v_mov_b32_e32 v4, 0x3e500000
	s_waitcnt lgkmcnt(0)
	s_barrier
	v_mov_b32_e32 v81, 0
	global_load_dwordx2 v[0:1], v4, s[52:53] offset:72
	global_load_dwordx2 v[2:3], v81, s[34:35]
	s_add_u32 s0, s52, 0x3e500048
	s_addc_u32 s1, s53, 0
	v_writelane_b32 v252, s0, 9
	v_mov_b32_e32 v5, v189
	s_add_u32 s72, s52, 0x3d83c000
	v_writelane_b32 v252, s1, 10
	s_mov_b32 s0, s33
	v_ashrrev_i32_e32 v4, 6, v5
	s_movk_i32 s1, 0x4200
	v_lshl_add_u32 v129, s0, 3, v4
	s_addc_u32 s73, s53, 0
	v_cmp_gt_i32_e32 vcc, s1, v129
	s_and_saveexec_b64 s[2:3], vcc
	s_cbranch_execz .LBB0_1204
	s_cmpk_lg_i32 s94, 0x800
	s_cbranch_scc1 .Lrm2_orig
	s_waitcnt vmcnt(0) lgkmcnt(0)
	v_and_b32_e32 v170, 63, v189
	v_lshrrev_b32_e32 v173, 6, v189
	v_lshlrev_b32_e32 v80, 4, v170
	v_lshlrev_b32_e32 v169, 3, v170
	v_readfirstlane_b32 s5, v173
	v_add_u32_e32 v168, 0x1000, v80
	v_mov_b32_e32 v170, 0
	v_mov_b32_e32 v171, 0x3a000000
	v_mov_b32_e32 v172, 0x358637bd
	s_lshl_b32 s8, s33, 3
	s_add_u32 s5, s5, s8
	s_add_u32 s8, s52, 0x3e500000
	s_addc_u32 s9, s53, 0
	global_load_dwordx2 v[174:175], v170, s[8:9] offset:72
	global_load_dwordx2 v[176:177], v170, s[8:9] offset:48
	s_waitcnt vmcnt(0)
	v_mov_b32_e32 v173, 0x2000
	v_add_co_u32_e32 v176, vcc, v176, v173
	s_nop 1
	v_addc_co_u32_e32 v177, vcc, 0, v177, vcc
	s_mov_b32 s0, 0
	s_lshr_b32 s4, s5, 9
.Lrm2_coef:
	v_readfirstlane_b32 s8, v174
	v_readfirstlane_b32 s9, v175
	s_nop 4
	global_load_dwordx4 v[0:3], v80, s[8:9] offset:0
	global_load_dwordx4 v[4:7], v80, s[8:9] offset:1024
	global_load_dwordx4 v[8:11], v80, s[8:9] offset:2048
	global_load_dwordx4 v[12:15], v80, s[8:9] offset:3072
	global_load_dwordx4 v[16:19], v168, s[8:9] offset:0
	global_load_dwordx4 v[20:23], v168, s[8:9] offset:1024
	global_load_dwordx4 v[24:27], v168, s[8:9] offset:2048
	global_load_dwordx4 v[28:31], v168, s[8:9] offset:3072
	s_mul_i32 s8, s4, 0xc000
	s_add_u32 s8, s8, 0x3d80a000
	s_add_u32 s8, s52, s8
	s_addc_u32 s9, s53, 0
	global_load_dwordx4 v[82:85], v80, s[8:9] offset:0
	global_load_dwordx4 v[86:89], v80, s[8:9] offset:1024
	global_load_dwordx4 v[90:93], v80, s[8:9] offset:2048
	global_load_dwordx4 v[94:97], v80, s[8:9] offset:3072
	global_load_dwordx4 v[98:101], v168, s[8:9] offset:0
	global_load_dwordx4 v[102:105], v168, s[8:9] offset:1024
	global_load_dwordx4 v[106:109], v168, s[8:9] offset:2048
	global_load_dwordx4 v[110:113], v168, s[8:9] offset:3072
	s_waitcnt vmcnt(0)
	v_pk_mul_f32 v[48:49], v[82:83], v[0:1]
	v_pk_mul_f32 v[50:51], v[84:85], v[2:3]
	v_pk_mul_f32 v[52:53], v[86:87], v[4:5]
	v_pk_mul_f32 v[54:55], v[88:89], v[6:7]
	v_pk_mul_f32 v[56:57], v[90:91], v[8:9]
	v_pk_mul_f32 v[58:59], v[92:93], v[10:11]
	v_pk_mul_f32 v[60:61], v[94:95], v[12:13]
	v_pk_mul_f32 v[62:63], v[96:97], v[14:15]
	v_pk_mul_f32 v[64:65], v[98:99], v[16:17]
	v_pk_mul_f32 v[66:67], v[100:101], v[18:19]
	v_pk_mul_f32 v[68:69], v[102:103], v[20:21]
	v_pk_mul_f32 v[70:71], v[104:105], v[22:23]
	v_pk_mul_f32 v[72:73], v[106:107], v[24:25]
	v_pk_mul_f32 v[74:75], v[108:109], v[26:27]
	v_pk_mul_f32 v[76:77], v[110:111], v[28:29]
	v_pk_mul_f32 v[78:79], v[112:113], v[30:31]
	v_readfirstlane_b32 s8, v176
	v_readfirstlane_b32 s9, v177
	s_nop 4
	global_load_dwordx4 v[0:3], v80, s[8:9] offset:0
	global_load_dwordx4 v[4:7], v80, s[8:9] offset:1024
	global_load_dwordx4 v[8:11], v80, s[8:9] offset:2048
	global_load_dwordx4 v[12:15], v80, s[8:9] offset:3072
	global_load_dwordx4 v[16:19], v168, s[8:9] offset:0
	global_load_dwordx4 v[20:23], v168, s[8:9] offset:1024
	global_load_dwordx4 v[24:27], v168, s[8:9] offset:2048
	global_load_dwordx4 v[28:31], v168, s[8:9] offset:3072
	s_mul_i32 s8, s4, 0xc000
	s_add_u32 s8, s8, 0x3d83e000
	s_add_u32 s8, s52, s8
	s_addc_u32 s9, s53, 0
	global_load_dwordx4 v[114:117], v80, s[8:9] offset:0
	global_load_dwordx4 v[118:121], v80, s[8:9] offset:1024
	global_load_dwordx4 v[122:125], v80, s[8:9] offset:2048
	global_load_dwordx4 v[126:129], v80, s[8:9] offset:3072
	global_load_dwordx4 v[130:133], v168, s[8:9] offset:0
	global_load_dwordx4 v[134:137], v168, s[8:9] offset:1024
	global_load_dwordx4 v[138:141], v168, s[8:9] offset:2048
	global_load_dwordx4 v[142:145], v168, s[8:9] offset:3072
	s_waitcnt vmcnt(0)
	v_pk_add_f32 v[114:115], v[114:115], 1.0 op_sel_hi:[1,0]
	v_pk_add_f32 v[116:117], v[116:117], 1.0 op_sel_hi:[1,0]
	v_pk_add_f32 v[118:119], v[118:119], 1.0 op_sel_hi:[1,0]
	v_pk_add_f32 v[120:121], v[120:121], 1.0 op_sel_hi:[1,0]
	v_pk_add_f32 v[122:123], v[122:123], 1.0 op_sel_hi:[1,0]
	v_pk_add_f32 v[124:125], v[124:125], 1.0 op_sel_hi:[1,0]
	v_pk_add_f32 v[126:127], v[126:127], 1.0 op_sel_hi:[1,0]
	v_pk_add_f32 v[128:129], v[128:129], 1.0 op_sel_hi:[1,0]
	v_pk_add_f32 v[130:131], v[130:131], 1.0 op_sel_hi:[1,0]
	v_pk_add_f32 v[132:133], v[132:133], 1.0 op_sel_hi:[1,0]
	v_pk_add_f32 v[134:135], v[134:135], 1.0 op_sel_hi:[1,0]
	v_pk_add_f32 v[136:137], v[136:137], 1.0 op_sel_hi:[1,0]
	v_pk_add_f32 v[138:139], v[138:139], 1.0 op_sel_hi:[1,0]
	v_pk_add_f32 v[140:141], v[140:141], 1.0 op_sel_hi:[1,0]
	v_pk_add_f32 v[142:143], v[142:143], 1.0 op_sel_hi:[1,0]
	v_pk_add_f32 v[144:145], v[144:145], 1.0 op_sel_hi:[1,0]
	v_pk_mul_f32 v[82:83], v[0:1], v[114:115]
	v_pk_mul_f32 v[84:85], v[2:3], v[116:117]
	v_pk_mul_f32 v[86:87], v[4:5], v[118:119]
	v_pk_mul_f32 v[88:89], v[6:7], v[120:121]
	v_pk_mul_f32 v[90:91], v[8:9], v[122:123]
	v_pk_mul_f32 v[92:93], v[10:11], v[124:125]
	v_pk_mul_f32 v[94:95], v[12:13], v[126:127]
	v_pk_mul_f32 v[96:97], v[14:15], v[128:129]
	v_pk_mul_f32 v[98:99], v[16:17], v[130:131]
	v_pk_mul_f32 v[100:101], v[18:19], v[132:133]
	v_pk_mul_f32 v[102:103], v[20:21], v[134:135]
	v_pk_mul_f32 v[104:105], v[22:23], v[136:137]
	v_pk_mul_f32 v[106:107], v[24:25], v[138:139]
	v_pk_mul_f32 v[108:109], v[26:27], v[140:141]
	v_pk_mul_f32 v[110:111], v[28:29], v[142:143]
	v_pk_mul_f32 v[112:113], v[30:31], v[144:145]
	s_mul_i32 s8, s4, 0xc000
	s_add_u32 s8, s8, 0x3d83c000
	s_add_u32 s8, s52, s8
	s_addc_u32 s9, s53, 0
	global_load_dwordx4 v[114:117], v80, s[8:9] offset:0
	global_load_dwordx4 v[118:121], v80, s[8:9] offset:1024
	global_load_dwordx4 v[122:125], v80, s[8:9] offset:2048
	global_load_dwordx4 v[126:129], v80, s[8:9] offset:3072
	global_load_dwordx4 v[130:133], v168, s[8:9] offset:0
	global_load_dwordx4 v[134:137], v168, s[8:9] offset:1024
	global_load_dwordx4 v[138:141], v168, s[8:9] offset:2048
	global_load_dwordx4 v[142:145], v168, s[8:9] offset:3072
	s_cmp_lt_u32 s0, 16
	s_cbranch_scc0 .Lrm2_ctxrow
	s_lshr_b32 s1, s5, 9
	s_lshl_b32 s1, s1, 13
	s_and_b32 s8, s5, 0x1ff
	s_add_u32 s1, s1, s8
	s_add_u32 s8, s0, 0
	s_lshl_b32 s8, s8, 9
	s_add_u32 s1, s1, s8
	s_lshl_b32 s8, s1, 13
	s_add_u32 s6, s58, s8
	s_addc_u32 s7, s59, 0
	global_load_dwordx4 v[0:3], v80, s[6:7] offset:0 nt
	global_load_dwordx4 v[4:7], v80, s[6:7] offset:1024 nt
	global_load_dwordx4 v[8:11], v80, s[6:7] offset:2048 nt
	global_load_dwordx4 v[12:15], v80, s[6:7] offset:3072 nt
	global_load_dwordx4 v[16:19], v168, s[6:7] offset:0 nt
	global_load_dwordx4 v[20:23], v168, s[6:7] offset:1024 nt
	global_load_dwordx4 v[24:27], v168, s[6:7] offset:2048 nt
	global_load_dwordx4 v[28:31], v168, s[6:7] offset:3072 nt
.Lrm2_loop:
	s_lshr_b32 s1, s5, 9
	s_lshl_b32 s1, s1, 13
	s_and_b32 s8, s5, 0x1ff
	s_add_u32 s1, s1, s8
	s_add_u32 s8, s0, 0
	s_lshl_b32 s8, s8, 9
	s_add_u32 s1, s1, s8
	s_lshl_b32 s8, s1, 13
	s_add_u32 s10, s58, s8
	s_addc_u32 s11, s59, 0
	s_lshl_b32 s8, s1, 12
	s_add_u32 s9, s8, 0x34c00000
	s_add_u32 s12, s52, s9
	s_addc_u32 s13, s53, 0
	s_add_u32 s9, s8, 0x2c800000
	s_add_u32 s14, s52, s9
	s_addc_u32 s15, s53, 0
	global_load_dwordx2 v[32:33], v169, s[12:13] offset:0 nt
	global_load_dwordx2 v[34:35], v169, s[12:13] offset:512 nt
	global_load_dwordx2 v[36:37], v169, s[12:13] offset:1024 nt
	global_load_dwordx2 v[38:39], v169, s[12:13] offset:1536 nt
	global_load_dwordx2 v[40:41], v169, s[12:13] offset:2048 nt
	global_load_dwordx2 v[42:43], v169, s[12:13] offset:2560 nt
	global_load_dwordx2 v[44:45], v169, s[12:13] offset:3072 nt
	global_load_dwordx2 v[46:47], v169, s[12:13] offset:3584 nt
	s_lshr_b32 s1, s5, 9
	s_lshl_b32 s1, s1, 13
	s_and_b32 s8, s5, 0x1ff
	s_add_u32 s1, s1, s8
	s_add_u32 s8, s0, 1
	s_lshl_b32 s8, s8, 9
	s_add_u32 s1, s1, s8
	s_lshl_b32 s8, s1, 13
	s_add_u32 s6, s58, s8
	s_addc_u32 s7, s59, 0
	global_load_dwordx4 v[178:181], v80, s[6:7] offset:0 nt
	global_load_dwordx4 v[182:185], v80, s[6:7] offset:1024 nt
	global_load_dwordx4 v[194:197], v80, s[6:7] offset:2048 nt
	global_load_dwordx4 v[198:201], v80, s[6:7] offset:3072 nt
	global_load_dwordx4 v[202:205], v168, s[6:7] offset:0 nt
	global_load_dwordx4 v[206:209], v168, s[6:7] offset:1024 nt
	global_load_dwordx4 v[210:213], v168, s[6:7] offset:2048 nt
	global_load_dwordx4 v[218:221], v168, s[6:7] offset:3072 nt
	s_waitcnt vmcnt(8)
	v_lshlrev_b32_e32 v146, 16, v32
	v_and_b32_e32 v147, 0xffff0000, v32
	v_pk_mul_f32 v[154:155], v[146:147], v[146:147]
	v_lshlrev_b32_e32 v148, 16, v33
	v_and_b32_e32 v149, 0xffff0000, v33
	v_pk_mul_f32 v[156:157], v[148:149], v[148:149]
	v_lshlrev_b32_e32 v150, 16, v34
	v_and_b32_e32 v151, 0xffff0000, v34
	v_pk_fma_f32 v[154:155], v[150:151], v[150:151], v[154:155]
	v_lshlrev_b32_e32 v152, 16, v35
	v_and_b32_e32 v153, 0xffff0000, v35
	v_pk_fma_f32 v[156:157], v[152:153], v[152:153], v[156:157]
	v_lshlrev_b32_e32 v146, 16, v36
	v_and_b32_e32 v147, 0xffff0000, v36
	v_pk_fma_f32 v[154:155], v[146:147], v[146:147], v[154:155]
	v_lshlrev_b32_e32 v148, 16, v37
	v_and_b32_e32 v149, 0xffff0000, v37
	v_pk_fma_f32 v[156:157], v[148:149], v[148:149], v[156:157]
	v_lshlrev_b32_e32 v150, 16, v38
	v_and_b32_e32 v151, 0xffff0000, v38
	v_pk_fma_f32 v[154:155], v[150:151], v[150:151], v[154:155]
	v_lshlrev_b32_e32 v152, 16, v39
	v_and_b32_e32 v153, 0xffff0000, v39
	v_pk_fma_f32 v[156:157], v[152:153], v[152:153], v[156:157]
	v_lshlrev_b32_e32 v146, 16, v40
	v_and_b32_e32 v147, 0xffff0000, v40
	v_pk_fma_f32 v[154:155], v[146:147], v[146:147], v[154:155]
	v_lshlrev_b32_e32 v148, 16, v41
	v_and_b32_e32 v149, 0xffff0000, v41
	v_pk_fma_f32 v[156:157], v[148:149], v[148:149], v[156:157]
	v_lshlrev_b32_e32 v150, 16, v42
	v_and_b32_e32 v151, 0xffff0000, v42
	v_pk_fma_f32 v[154:155], v[150:151], v[150:151], v[154:155]
	v_lshlrev_b32_e32 v152, 16, v43
	v_and_b32_e32 v153, 0xffff0000, v43
	v_pk_fma_f32 v[156:157], v[152:153], v[152:153], v[156:157]
	v_lshlrev_b32_e32 v146, 16, v44
	v_and_b32_e32 v147, 0xffff0000, v44
	v_pk_fma_f32 v[154:155], v[146:147], v[146:147], v[154:155]
	v_lshlrev_b32_e32 v148, 16, v45
	v_and_b32_e32 v149, 0xffff0000, v45
	v_pk_fma_f32 v[156:157], v[148:149], v[148:149], v[156:157]
	v_lshlrev_b32_e32 v150, 16, v46
	v_and_b32_e32 v151, 0xffff0000, v46
	v_pk_fma_f32 v[154:155], v[150:151], v[150:151], v[154:155]
	v_lshlrev_b32_e32 v152, 16, v47
	v_and_b32_e32 v153, 0xffff0000, v47
	v_pk_fma_f32 v[156:157], v[152:153], v[152:153], v[156:157]
	v_pk_add_f32 v[154:155], v[154:155], v[156:157]
	s_nop 0
	v_add_f32_e32 v173, v154, v155
	s_nop 1
	v_add_f32_dpp v173, v173, v173 quad_perm:[1,0,3,2] row_mask:0xf bank_mask:0xf
	s_nop 1
	v_add_f32_dpp v173, v173, v173 quad_perm:[2,3,0,1] row_mask:0xf bank_mask:0xf
	s_nop 1
	v_add_f32_dpp v173, v173, v173 row_half_mirror row_mask:0xf bank_mask:0xf
	s_nop 1
	v_add_f32_dpp v173, v173, v173 row_mirror row_mask:0xf bank_mask:0xf
	s_nop 1
	v_add_f32_dpp v173, v173, v173 row_bcast:15 row_mask:0xa bank_mask:0xf
	s_nop 1
	v_add_f32_dpp v173, v173, v173 row_bcast:31 row_mask:0xc bank_mask:0xf
	s_nop 1
	v_readlane_b32 s8, v173, 63
	s_nop 3
	v_mov_b32_e32 v158, s8
	v_fma_f32 v158, v158, v171, v172
	v_rsq_f32_e32 v158, v158
	s_nop 1
	v_lshlrev_b32_e32 v146, 16, v32
	v_and_b32_e32 v147, 0xffff0000, v32
	v_pk_mul_f32 v[146:147], v[146:147], v[158:159] op_sel_hi:[1,0]
	v_pk_fma_f32 v[0:1], v[48:49], v[146:147], v[0:1]
	v_lshlrev_b32_e32 v148, 16, v33
	v_and_b32_e32 v149, 0xffff0000, v33
	v_pk_mul_f32 v[148:149], v[148:149], v[158:159] op_sel_hi:[1,0]
	v_pk_fma_f32 v[2:3], v[50:51], v[148:149], v[2:3]
	v_lshlrev_b32_e32 v150, 16, v34
	v_and_b32_e32 v151, 0xffff0000, v34
	v_pk_mul_f32 v[150:151], v[150:151], v[158:159] op_sel_hi:[1,0]
	v_pk_fma_f32 v[4:5], v[52:53], v[150:151], v[4:5]
	v_lshlrev_b32_e32 v152, 16, v35
	v_and_b32_e32 v153, 0xffff0000, v35
	v_pk_mul_f32 v[152:153], v[152:153], v[158:159] op_sel_hi:[1,0]
	v_pk_fma_f32 v[6:7], v[54:55], v[152:153], v[6:7]
	v_lshlrev_b32_e32 v146, 16, v36
	v_and_b32_e32 v147, 0xffff0000, v36
	v_pk_mul_f32 v[146:147], v[146:147], v[158:159] op_sel_hi:[1,0]
	v_pk_fma_f32 v[8:9], v[56:57], v[146:147], v[8:9]
	v_lshlrev_b32_e32 v148, 16, v37
	v_and_b32_e32 v149, 0xffff0000, v37
	v_pk_mul_f32 v[148:149], v[148:149], v[158:159] op_sel_hi:[1,0]
	v_pk_fma_f32 v[10:11], v[58:59], v[148:149], v[10:11]
	v_lshlrev_b32_e32 v150, 16, v38
	v_and_b32_e32 v151, 0xffff0000, v38
	v_pk_mul_f32 v[150:151], v[150:151], v[158:159] op_sel_hi:[1,0]
	v_pk_fma_f32 v[12:13], v[60:61], v[150:151], v[12:13]
	v_lshlrev_b32_e32 v152, 16, v39
	v_and_b32_e32 v153, 0xffff0000, v39
	v_pk_mul_f32 v[152:153], v[152:153], v[158:159] op_sel_hi:[1,0]
	v_pk_fma_f32 v[14:15], v[62:63], v[152:153], v[14:15]
	v_lshlrev_b32_e32 v146, 16, v40
	v_and_b32_e32 v147, 0xffff0000, v40
	v_pk_mul_f32 v[146:147], v[146:147], v[158:159] op_sel_hi:[1,0]
	v_pk_fma_f32 v[16:17], v[64:65], v[146:147], v[16:17]
	v_lshlrev_b32_e32 v148, 16, v41
	v_and_b32_e32 v149, 0xffff0000, v41
	v_pk_mul_f32 v[148:149], v[148:149], v[158:159] op_sel_hi:[1,0]
	v_pk_fma_f32 v[18:19], v[66:67], v[148:149], v[18:19]
	v_lshlrev_b32_e32 v150, 16, v42
	v_and_b32_e32 v151, 0xffff0000, v42
	v_pk_mul_f32 v[150:151], v[150:151], v[158:159] op_sel_hi:[1,0]
	v_pk_fma_f32 v[20:21], v[68:69], v[150:151], v[20:21]
	v_lshlrev_b32_e32 v152, 16, v43
	v_and_b32_e32 v153, 0xffff0000, v43
	v_pk_mul_f32 v[152:153], v[152:153], v[158:159] op_sel_hi:[1,0]
	v_pk_fma_f32 v[22:23], v[70:71], v[152:153], v[22:23]
	v_lshlrev_b32_e32 v146, 16, v44
	v_and_b32_e32 v147, 0xffff0000, v44
	v_pk_mul_f32 v[146:147], v[146:147], v[158:159] op_sel_hi:[1,0]
	v_pk_fma_f32 v[24:25], v[72:73], v[146:147], v[24:25]
	v_lshlrev_b32_e32 v148, 16, v45
	v_and_b32_e32 v149, 0xffff0000, v45
	v_pk_mul_f32 v[148:149], v[148:149], v[158:159] op_sel_hi:[1,0]
	v_pk_fma_f32 v[26:27], v[74:75], v[148:149], v[26:27]
	v_lshlrev_b32_e32 v150, 16, v46
	v_and_b32_e32 v151, 0xffff0000, v46
	v_pk_mul_f32 v[150:151], v[150:151], v[158:159] op_sel_hi:[1,0]
	v_pk_fma_f32 v[28:29], v[76:77], v[150:151], v[28:29]
	v_lshlrev_b32_e32 v152, 16, v47
	v_and_b32_e32 v153, 0xffff0000, v47
	v_pk_mul_f32 v[152:153], v[152:153], v[158:159] op_sel_hi:[1,0]
	v_pk_fma_f32 v[30:31], v[78:79], v[152:153], v[30:31]
	s_nop 0
	global_store_dwordx4 v80, v[0:3], s[10:11] offset:0 nt
	global_store_dwordx4 v80, v[4:7], s[10:11] offset:1024 nt
	global_store_dwordx4 v80, v[8:11], s[10:11] offset:2048 nt
	global_store_dwordx4 v80, v[12:15], s[10:11] offset:3072 nt
	global_store_dwordx4 v168, v[16:19], s[10:11] offset:0 nt
	global_store_dwordx4 v168, v[20:23], s[10:11] offset:1024 nt
	global_store_dwordx4 v168, v[24:27], s[10:11] offset:2048 nt
	global_store_dwordx4 v168, v[28:31], s[10:11] offset:3072 nt
	v_pk_mul_f32 v[154:155], v[0:1], v[0:1]
	v_pk_mul_f32 v[156:157], v[2:3], v[2:3]
	v_pk_fma_f32 v[154:155], v[4:5], v[4:5], v[154:155]
	v_pk_fma_f32 v[156:157], v[6:7], v[6:7], v[156:157]
	v_pk_fma_f32 v[154:155], v[8:9], v[8:9], v[154:155]
	v_pk_fma_f32 v[156:157], v[10:11], v[10:11], v[156:157]
	v_pk_fma_f32 v[154:155], v[12:13], v[12:13], v[154:155]
	v_pk_fma_f32 v[156:157], v[14:15], v[14:15], v[156:157]
	v_pk_fma_f32 v[154:155], v[16:17], v[16:17], v[154:155]
	v_pk_fma_f32 v[156:157], v[18:19], v[18:19], v[156:157]
	v_pk_fma_f32 v[154:155], v[20:21], v[20:21], v[154:155]
	v_pk_fma_f32 v[156:157], v[22:23], v[22:23], v[156:157]
	v_pk_fma_f32 v[154:155], v[24:25], v[24:25], v[154:155]
	v_pk_fma_f32 v[156:157], v[26:27], v[26:27], v[156:157]
	v_pk_fma_f32 v[154:155], v[28:29], v[28:29], v[154:155]
	v_pk_fma_f32 v[156:157], v[30:31], v[30:31], v[156:157]
	v_pk_add_f32 v[154:155], v[154:155], v[156:157]
	s_nop 0
	v_add_f32_e32 v173, v154, v155
	s_nop 1
	v_add_f32_dpp v173, v173, v173 quad_perm:[1,0,3,2] row_mask:0xf bank_mask:0xf
	s_nop 1
	v_add_f32_dpp v173, v173, v173 quad_perm:[2,3,0,1] row_mask:0xf bank_mask:0xf
	s_nop 1
	v_add_f32_dpp v173, v173, v173 row_half_mirror row_mask:0xf bank_mask:0xf
	s_nop 1
	v_add_f32_dpp v173, v173, v173 row_mirror row_mask:0xf bank_mask:0xf
	s_nop 1
	v_add_f32_dpp v173, v173, v173 row_bcast:15 row_mask:0xa bank_mask:0xf
	s_nop 1
	v_add_f32_dpp v173, v173, v173 row_bcast:31 row_mask:0xc bank_mask:0xf
	s_nop 1
	v_readlane_b32 s8, v173, 63
	s_nop 3
	v_mov_b32_e32 v158, s8
	v_fma_f32 v158, v158, v171, v172
	v_rsq_f32_e32 v158, v158
	s_nop 1
	v_pk_mul_f32 v[146:147], v[0:1], v[158:159] op_sel_hi:[1,0]
	v_pk_fma_f32 v[146:147], v[146:147], v[82:83], v[114:115]
	v_cvt_pk_bf16_f32 v160, v146, v147
	v_pk_mul_f32 v[148:149], v[2:3], v[158:159] op_sel_hi:[1,0]
	v_pk_fma_f32 v[148:149], v[148:149], v[84:85], v[116:117]
	v_cvt_pk_bf16_f32 v161, v148, v149
	global_store_dwordx2 v169, v[160:161], s[14:15] offset:0
	v_pk_mul_f32 v[150:151], v[4:5], v[158:159] op_sel_hi:[1,0]
	v_pk_fma_f32 v[150:151], v[150:151], v[86:87], v[118:119]
	v_cvt_pk_bf16_f32 v162, v150, v151
	v_pk_mul_f32 v[152:153], v[6:7], v[158:159] op_sel_hi:[1,0]
	v_pk_fma_f32 v[152:153], v[152:153], v[88:89], v[120:121]
	v_cvt_pk_bf16_f32 v163, v152, v153
	global_store_dwordx2 v169, v[162:163], s[14:15] offset:512
	v_pk_mul_f32 v[146:147], v[8:9], v[158:159] op_sel_hi:[1,0]
	v_pk_fma_f32 v[146:147], v[146:147], v[90:91], v[122:123]
	v_cvt_pk_bf16_f32 v164, v146, v147
	v_pk_mul_f32 v[148:149], v[10:11], v[158:159] op_sel_hi:[1,0]
	v_pk_fma_f32 v[148:149], v[148:149], v[92:93], v[124:125]
	v_cvt_pk_bf16_f32 v165, v148, v149
	global_store_dwordx2 v169, v[164:165], s[14:15] offset:1024
	v_pk_mul_f32 v[150:151], v[12:13], v[158:159] op_sel_hi:[1,0]
	v_pk_fma_f32 v[150:151], v[150:151], v[94:95], v[126:127]
	v_cvt_pk_bf16_f32 v166, v150, v151
	v_pk_mul_f32 v[152:153], v[14:15], v[158:159] op_sel_hi:[1,0]
	v_pk_fma_f32 v[152:153], v[152:153], v[96:97], v[128:129]
	v_cvt_pk_bf16_f32 v167, v152, v153
	global_store_dwordx2 v169, v[166:167], s[14:15] offset:1536
	v_pk_mul_f32 v[146:147], v[16:17], v[158:159] op_sel_hi:[1,0]
	v_pk_fma_f32 v[146:147], v[146:147], v[98:99], v[130:131]
	v_cvt_pk_bf16_f32 v160, v146, v147
	v_pk_mul_f32 v[148:149], v[18:19], v[158:159] op_sel_hi:[1,0]
	v_pk_fma_f32 v[148:149], v[148:149], v[100:101], v[132:133]
	v_cvt_pk_bf16_f32 v161, v148, v149
	global_store_dwordx2 v169, v[160:161], s[14:15] offset:2048
	v_pk_mul_f32 v[150:151], v[20:21], v[158:159] op_sel_hi:[1,0]
	v_pk_fma_f32 v[150:151], v[150:151], v[102:103], v[134:135]
	v_cvt_pk_bf16_f32 v162, v150, v151
	v_pk_mul_f32 v[152:153], v[22:23], v[158:159] op_sel_hi:[1,0]
	v_pk_fma_f32 v[152:153], v[152:153], v[104:105], v[136:137]
	v_cvt_pk_bf16_f32 v163, v152, v153
	global_store_dwordx2 v169, v[162:163], s[14:15] offset:2560
	v_pk_mul_f32 v[146:147], v[24:25], v[158:159] op_sel_hi:[1,0]
	v_pk_fma_f32 v[146:147], v[146:147], v[106:107], v[138:139]
	v_cvt_pk_bf16_f32 v164, v146, v147
	v_pk_mul_f32 v[148:149], v[26:27], v[158:159] op_sel_hi:[1,0]
	v_pk_fma_f32 v[148:149], v[148:149], v[108:109], v[140:141]
	v_cvt_pk_bf16_f32 v165, v148, v149
	global_store_dwordx2 v169, v[164:165], s[14:15] offset:3072
	v_pk_mul_f32 v[150:151], v[28:29], v[158:159] op_sel_hi:[1,0]
	v_pk_fma_f32 v[150:151], v[150:151], v[110:111], v[142:143]
	v_cvt_pk_bf16_f32 v166, v150, v151
	v_pk_mul_f32 v[152:153], v[30:31], v[158:159] op_sel_hi:[1,0]
	v_pk_fma_f32 v[152:153], v[152:153], v[112:113], v[144:145]
	v_cvt_pk_bf16_f32 v167, v152, v153
	global_store_dwordx2 v169, v[166:167], s[14:15] offset:3584
	s_lshr_b32 s1, s5, 9
	s_lshl_b32 s1, s1, 13
	s_and_b32 s8, s5, 0x1ff
	s_add_u32 s1, s1, s8
	s_add_u32 s8, s0, 1
	s_lshl_b32 s8, s8, 9
	s_add_u32 s1, s1, s8
	s_lshl_b32 s8, s1, 13
	s_add_u32 s10, s58, s8
	s_addc_u32 s11, s59, 0
	s_lshl_b32 s8, s1, 12
	s_add_u32 s9, s8, 0x34c00000
	s_add_u32 s12, s52, s9
	s_addc_u32 s13, s53, 0
	s_add_u32 s9, s8, 0x2c800000
	s_add_u32 s14, s52, s9
	s_addc_u32 s15, s53, 0
	global_load_dwordx2 v[32:33], v169, s[12:13] offset:0 nt
	global_load_dwordx2 v[34:35], v169, s[12:13] offset:512 nt
	global_load_dwordx2 v[36:37], v169, s[12:13] offset:1024 nt
	global_load_dwordx2 v[38:39], v169, s[12:13] offset:1536 nt
	global_load_dwordx2 v[40:41], v169, s[12:13] offset:2048 nt
	global_load_dwordx2 v[42:43], v169, s[12:13] offset:2560 nt
	global_load_dwordx2 v[44:45], v169, s[12:13] offset:3072 nt
	global_load_dwordx2 v[46:47], v169, s[12:13] offset:3584 nt
	s_cmp_lt_u32 s0, 14
	s_cbranch_scc0 .Lrm2_nopf_o
	s_lshr_b32 s1, s5, 9
	s_lshl_b32 s1, s1, 13
	s_and_b32 s8, s5, 0x1ff
	s_add_u32 s1, s1, s8
	s_add_u32 s8, s0, 2
	s_lshl_b32 s8, s8, 9
	s_add_u32 s1, s1, s8
	s_lshl_b32 s8, s1, 13
	s_add_u32 s6, s58, s8
	s_addc_u32 s7, s59, 0
	global_load_dwordx4 v[0:3], v80, s[6:7] offset:0 nt
	global_load_dwordx4 v[4:7], v80, s[6:7] offset:1024 nt
	global_load_dwordx4 v[8:11], v80, s[6:7] offset:2048 nt
	global_load_dwordx4 v[12:15], v80, s[6:7] offset:3072 nt
	global_load_dwordx4 v[16:19], v168, s[6:7] offset:0 nt
	global_load_dwordx4 v[20:23], v168, s[6:7] offset:1024 nt
	global_load_dwordx4 v[24:27], v168, s[6:7] offset:2048 nt
	global_load_dwordx4 v[28:31], v168, s[6:7] offset:3072 nt
	s_waitcnt vmcnt(8)
	s_branch .Lrm2_pfd_o

.Lrm2_pfd_o:
	v_lshlrev_b32_e32 v146, 16, v32
	v_and_b32_e32 v147, 0xffff0000, v32
	v_pk_mul_f32 v[154:155], v[146:147], v[146:147]
	v_lshlrev_b32_e32 v148, 16, v33
	v_and_b32_e32 v149, 0xffff0000, v33
	v_pk_mul_f32 v[156:157], v[148:149], v[148:149]
	v_lshlrev_b32_e32 v150, 16, v34
	v_and_b32_e32 v151, 0xffff0000, v34
	v_pk_fma_f32 v[154:155], v[150:151], v[150:151], v[154:155]
	v_lshlrev_b32_e32 v152, 16, v35
	v_and_b32_e32 v153, 0xffff0000, v35
	v_pk_fma_f32 v[156:157], v[152:153], v[152:153], v[156:157]
	v_lshlrev_b32_e32 v146, 16, v36
	v_and_b32_e32 v147, 0xffff0000, v36
	v_pk_fma_f32 v[154:155], v[146:147], v[146:147], v[154:155]
	v_lshlrev_b32_e32 v148, 16, v37
	v_and_b32_e32 v149, 0xffff0000, v37
	v_pk_fma_f32 v[156:157], v[148:149], v[148:149], v[156:157]
	v_lshlrev_b32_e32 v150, 16, v38
	v_and_b32_e32 v151, 0xffff0000, v38
	v_pk_fma_f32 v[154:155], v[150:151], v[150:151], v[154:155]
	v_lshlrev_b32_e32 v152, 16, v39
	v_and_b32_e32 v153, 0xffff0000, v39
	v_pk_fma_f32 v[156:157], v[152:153], v[152:153], v[156:157]
	v_lshlrev_b32_e32 v146, 16, v40
	v_and_b32_e32 v147, 0xffff0000, v40
	v_pk_fma_f32 v[154:155], v[146:147], v[146:147], v[154:155]
	v_lshlrev_b32_e32 v148, 16, v41
	v_and_b32_e32 v149, 0xffff0000, v41
	v_pk_fma_f32 v[156:157], v[148:149], v[148:149], v[156:157]
	v_lshlrev_b32_e32 v150, 16, v42
	v_and_b32_e32 v151, 0xffff0000, v42
	v_pk_fma_f32 v[154:155], v[150:151], v[150:151], v[154:155]
	v_lshlrev_b32_e32 v152, 16, v43
	v_and_b32_e32 v153, 0xffff0000, v43
	v_pk_fma_f32 v[156:157], v[152:153], v[152:153], v[156:157]
	v_lshlrev_b32_e32 v146, 16, v44
	v_and_b32_e32 v147, 0xffff0000, v44
	v_pk_fma_f32 v[154:155], v[146:147], v[146:147], v[154:155]
	v_lshlrev_b32_e32 v148, 16, v45
	v_and_b32_e32 v149, 0xffff0000, v45
	v_pk_fma_f32 v[156:157], v[148:149], v[148:149], v[156:157]
	v_lshlrev_b32_e32 v150, 16, v46
	v_and_b32_e32 v151, 0xffff0000, v46
	v_pk_fma_f32 v[154:155], v[150:151], v[150:151], v[154:155]
	v_lshlrev_b32_e32 v152, 16, v47
	v_and_b32_e32 v153, 0xffff0000, v47
	v_pk_fma_f32 v[156:157], v[152:153], v[152:153], v[156:157]
	v_pk_add_f32 v[154:155], v[154:155], v[156:157]
	s_nop 0
	v_add_f32_e32 v173, v154, v155
	s_nop 1
	v_add_f32_dpp v173, v173, v173 quad_perm:[1,0,3,2] row_mask:0xf bank_mask:0xf
	s_nop 1
	v_add_f32_dpp v173, v173, v173 quad_perm:[2,3,0,1] row_mask:0xf bank_mask:0xf
	s_nop 1
	v_add_f32_dpp v173, v173, v173 row_half_mirror row_mask:0xf bank_mask:0xf
	s_nop 1
	v_add_f32_dpp v173, v173, v173 row_mirror row_mask:0xf bank_mask:0xf
	s_nop 1
	v_add_f32_dpp v173, v173, v173 row_bcast:15 row_mask:0xa bank_mask:0xf
	s_nop 1
	v_add_f32_dpp v173, v173, v173 row_bcast:31 row_mask:0xc bank_mask:0xf
	s_nop 1
	v_readlane_b32 s8, v173, 63
	s_nop 3
	v_mov_b32_e32 v158, s8
	v_fma_f32 v158, v158, v171, v172
	v_rsq_f32_e32 v158, v158
	s_nop 1
	v_lshlrev_b32_e32 v146, 16, v32
	v_and_b32_e32 v147, 0xffff0000, v32
	v_pk_mul_f32 v[146:147], v[146:147], v[158:159] op_sel_hi:[1,0]
	v_pk_fma_f32 v[178:179], v[48:49], v[146:147], v[178:179]
	v_lshlrev_b32_e32 v148, 16, v33
	v_and_b32_e32 v149, 0xffff0000, v33
	v_pk_mul_f32 v[148:149], v[148:149], v[158:159] op_sel_hi:[1,0]
	v_pk_fma_f32 v[180:181], v[50:51], v[148:149], v[180:181]
	v_lshlrev_b32_e32 v150, 16, v34
	v_and_b32_e32 v151, 0xffff0000, v34
	v_pk_mul_f32 v[150:151], v[150:151], v[158:159] op_sel_hi:[1,0]
	v_pk_fma_f32 v[182:183], v[52:53], v[150:151], v[182:183]
	v_lshlrev_b32_e32 v152, 16, v35
	v_and_b32_e32 v153, 0xffff0000, v35
	v_pk_mul_f32 v[152:153], v[152:153], v[158:159] op_sel_hi:[1,0]
	v_pk_fma_f32 v[184:185], v[54:55], v[152:153], v[184:185]
	v_lshlrev_b32_e32 v146, 16, v36
	v_and_b32_e32 v147, 0xffff0000, v36
	v_pk_mul_f32 v[146:147], v[146:147], v[158:159] op_sel_hi:[1,0]
	v_pk_fma_f32 v[194:195], v[56:57], v[146:147], v[194:195]
	v_lshlrev_b32_e32 v148, 16, v37
	v_and_b32_e32 v149, 0xffff0000, v37
	v_pk_mul_f32 v[148:149], v[148:149], v[158:159] op_sel_hi:[1,0]
	v_pk_fma_f32 v[196:197], v[58:59], v[148:149], v[196:197]
	v_lshlrev_b32_e32 v150, 16, v38
	v_and_b32_e32 v151, 0xffff0000, v38
	v_pk_mul_f32 v[150:151], v[150:151], v[158:159] op_sel_hi:[1,0]
	v_pk_fma_f32 v[198:199], v[60:61], v[150:151], v[198:199]
	v_lshlrev_b32_e32 v152, 16, v39
	v_and_b32_e32 v153, 0xffff0000, v39
	v_pk_mul_f32 v[152:153], v[152:153], v[158:159] op_sel_hi:[1,0]
	v_pk_fma_f32 v[200:201], v[62:63], v[152:153], v[200:201]
	v_lshlrev_b32_e32 v146, 16, v40
	v_and_b32_e32 v147, 0xffff0000, v40
	v_pk_mul_f32 v[146:147], v[146:147], v[158:159] op_sel_hi:[1,0]
	v_pk_fma_f32 v[202:203], v[64:65], v[146:147], v[202:203]
	v_lshlrev_b32_e32 v148, 16, v41
	v_and_b32_e32 v149, 0xffff0000, v41
	v_pk_mul_f32 v[148:149], v[148:149], v[158:159] op_sel_hi:[1,0]
	v_pk_fma_f32 v[204:205], v[66:67], v[148:149], v[204:205]
	v_lshlrev_b32_e32 v150, 16, v42
	v_and_b32_e32 v151, 0xffff0000, v42
	v_pk_mul_f32 v[150:151], v[150:151], v[158:159] op_sel_hi:[1,0]
	v_pk_fma_f32 v[206:207], v[68:69], v[150:151], v[206:207]
	v_lshlrev_b32_e32 v152, 16, v43
	v_and_b32_e32 v153, 0xffff0000, v43
	v_pk_mul_f32 v[152:153], v[152:153], v[158:159] op_sel_hi:[1,0]
	v_pk_fma_f32 v[208:209], v[70:71], v[152:153], v[208:209]
	v_lshlrev_b32_e32 v146, 16, v44
	v_and_b32_e32 v147, 0xffff0000, v44
	v_pk_mul_f32 v[146:147], v[146:147], v[158:159] op_sel_hi:[1,0]
	v_pk_fma_f32 v[210:211], v[72:73], v[146:147], v[210:211]
	v_lshlrev_b32_e32 v148, 16, v45
	v_and_b32_e32 v149, 0xffff0000, v45
	v_pk_mul_f32 v[148:149], v[148:149], v[158:159] op_sel_hi:[1,0]
	v_pk_fma_f32 v[212:213], v[74:75], v[148:149], v[212:213]
	v_lshlrev_b32_e32 v150, 16, v46
	v_and_b32_e32 v151, 0xffff0000, v46
	v_pk_mul_f32 v[150:151], v[150:151], v[158:159] op_sel_hi:[1,0]
	v_pk_fma_f32 v[218:219], v[76:77], v[150:151], v[218:219]
	v_lshlrev_b32_e32 v152, 16, v47
	v_and_b32_e32 v153, 0xffff0000, v47
	v_pk_mul_f32 v[152:153], v[152:153], v[158:159] op_sel_hi:[1,0]
	v_pk_fma_f32 v[220:221], v[78:79], v[152:153], v[220:221]
	s_nop 0
	global_store_dwordx4 v80, v[178:181], s[10:11] offset:0 nt
	global_store_dwordx4 v80, v[182:185], s[10:11] offset:1024 nt
	global_store_dwordx4 v80, v[194:197], s[10:11] offset:2048 nt
	global_store_dwordx4 v80, v[198:201], s[10:11] offset:3072 nt
	global_store_dwordx4 v168, v[202:205], s[10:11] offset:0 nt
	global_store_dwordx4 v168, v[206:209], s[10:11] offset:1024 nt
	global_store_dwordx4 v168, v[210:213], s[10:11] offset:2048 nt
	global_store_dwordx4 v168, v[218:221], s[10:11] offset:3072 nt
	v_pk_mul_f32 v[154:155], v[178:179], v[178:179]
	v_pk_mul_f32 v[156:157], v[180:181], v[180:181]
	v_pk_fma_f32 v[154:155], v[182:183], v[182:183], v[154:155]
	v_pk_fma_f32 v[156:157], v[184:185], v[184:185], v[156:157]
	v_pk_fma_f32 v[154:155], v[194:195], v[194:195], v[154:155]
	v_pk_fma_f32 v[156:157], v[196:197], v[196:197], v[156:157]
	v_pk_fma_f32 v[154:155], v[198:199], v[198:199], v[154:155]
	v_pk_fma_f32 v[156:157], v[200:201], v[200:201], v[156:157]
	v_pk_fma_f32 v[154:155], v[202:203], v[202:203], v[154:155]
	v_pk_fma_f32 v[156:157], v[204:205], v[204:205], v[156:157]
	v_pk_fma_f32 v[154:155], v[206:207], v[206:207], v[154:155]
	v_pk_fma_f32 v[156:157], v[208:209], v[208:209], v[156:157]
	v_pk_fma_f32 v[154:155], v[210:211], v[210:211], v[154:155]
	v_pk_fma_f32 v[156:157], v[212:213], v[212:213], v[156:157]
	v_pk_fma_f32 v[154:155], v[218:219], v[218:219], v[154:155]
	v_pk_fma_f32 v[156:157], v[220:221], v[220:221], v[156:157]
	v_pk_add_f32 v[154:155], v[154:155], v[156:157]
	s_nop 0
	v_add_f32_e32 v173, v154, v155
	s_nop 1
	v_add_f32_dpp v173, v173, v173 quad_perm:[1,0,3,2] row_mask:0xf bank_mask:0xf
	s_nop 1
	v_add_f32_dpp v173, v173, v173 quad_perm:[2,3,0,1] row_mask:0xf bank_mask:0xf
	s_nop 1
	v_add_f32_dpp v173, v173, v173 row_half_mirror row_mask:0xf bank_mask:0xf
	s_nop 1
	v_add_f32_dpp v173, v173, v173 row_mirror row_mask:0xf bank_mask:0xf
	s_nop 1
	v_add_f32_dpp v173, v173, v173 row_bcast:15 row_mask:0xa bank_mask:0xf
	s_nop 1
	v_add_f32_dpp v173, v173, v173 row_bcast:31 row_mask:0xc bank_mask:0xf
	s_nop 1
	v_readlane_b32 s8, v173, 63
	s_nop 3
	v_mov_b32_e32 v158, s8
	v_fma_f32 v158, v158, v171, v172
	v_rsq_f32_e32 v158, v158
	s_nop 1
	v_pk_mul_f32 v[146:147], v[178:179], v[158:159] op_sel_hi:[1,0]
	v_pk_fma_f32 v[146:147], v[146:147], v[82:83], v[114:115]
	v_cvt_pk_bf16_f32 v160, v146, v147
	v_pk_mul_f32 v[148:149], v[180:181], v[158:159] op_sel_hi:[1,0]
	v_pk_fma_f32 v[148:149], v[148:149], v[84:85], v[116:117]
	v_cvt_pk_bf16_f32 v161, v148, v149
	global_store_dwordx2 v169, v[160:161], s[14:15] offset:0
	v_pk_mul_f32 v[150:151], v[182:183], v[158:159] op_sel_hi:[1,0]
	v_pk_fma_f32 v[150:151], v[150:151], v[86:87], v[118:119]
	v_cvt_pk_bf16_f32 v162, v150, v151
	v_pk_mul_f32 v[152:153], v[184:185], v[158:159] op_sel_hi:[1,0]
	v_pk_fma_f32 v[152:153], v[152:153], v[88:89], v[120:121]
	v_cvt_pk_bf16_f32 v163, v152, v153
	global_store_dwordx2 v169, v[162:163], s[14:15] offset:512
	v_pk_mul_f32 v[146:147], v[194:195], v[158:159] op_sel_hi:[1,0]
	v_pk_fma_f32 v[146:147], v[146:147], v[90:91], v[122:123]
	v_cvt_pk_bf16_f32 v164, v146, v147
	v_pk_mul_f32 v[148:149], v[196:197], v[158:159] op_sel_hi:[1,0]
	v_pk_fma_f32 v[148:149], v[148:149], v[92:93], v[124:125]
	v_cvt_pk_bf16_f32 v165, v148, v149
	global_store_dwordx2 v169, v[164:165], s[14:15] offset:1024
	v_pk_mul_f32 v[150:151], v[198:199], v[158:159] op_sel_hi:[1,0]
	v_pk_fma_f32 v[150:151], v[150:151], v[94:95], v[126:127]
	v_cvt_pk_bf16_f32 v166, v150, v151
	v_pk_mul_f32 v[152:153], v[200:201], v[158:159] op_sel_hi:[1,0]
	v_pk_fma_f32 v[152:153], v[152:153], v[96:97], v[128:129]
	v_cvt_pk_bf16_f32 v167, v152, v153
	global_store_dwordx2 v169, v[166:167], s[14:15] offset:1536
	v_pk_mul_f32 v[146:147], v[202:203], v[158:159] op_sel_hi:[1,0]
	v_pk_fma_f32 v[146:147], v[146:147], v[98:99], v[130:131]
	v_cvt_pk_bf16_f32 v160, v146, v147
	v_pk_mul_f32 v[148:149], v[204:205], v[158:159] op_sel_hi:[1,0]
	v_pk_fma_f32 v[148:149], v[148:149], v[100:101], v[132:133]
	v_cvt_pk_bf16_f32 v161, v148, v149
	global_store_dwordx2 v169, v[160:161], s[14:15] offset:2048
	v_pk_mul_f32 v[150:151], v[206:207], v[158:159] op_sel_hi:[1,0]
	v_pk_fma_f32 v[150:151], v[150:151], v[102:103], v[134:135]
	v_cvt_pk_bf16_f32 v162, v150, v151
	v_pk_mul_f32 v[152:153], v[208:209], v[158:159] op_sel_hi:[1,0]
	v_pk_fma_f32 v[152:153], v[152:153], v[104:105], v[136:137]
	v_cvt_pk_bf16_f32 v163, v152, v153
	global_store_dwordx2 v169, v[162:163], s[14:15] offset:2560
	v_pk_mul_f32 v[146:147], v[210:211], v[158:159] op_sel_hi:[1,0]
	v_pk_fma_f32 v[146:147], v[146:147], v[106:107], v[138:139]
	v_cvt_pk_bf16_f32 v164, v146, v147
	v_pk_mul_f32 v[148:149], v[212:213], v[158:159] op_sel_hi:[1,0]
	v_pk_fma_f32 v[148:149], v[148:149], v[108:109], v[140:141]
	v_cvt_pk_bf16_f32 v165, v148, v149
	global_store_dwordx2 v169, v[164:165], s[14:15] offset:3072
	v_pk_mul_f32 v[150:151], v[218:219], v[158:159] op_sel_hi:[1,0]
	v_pk_fma_f32 v[150:151], v[150:151], v[110:111], v[142:143]
	v_cvt_pk_bf16_f32 v166, v150, v151
	v_pk_mul_f32 v[152:153], v[220:221], v[158:159] op_sel_hi:[1,0]
	v_pk_fma_f32 v[152:153], v[152:153], v[112:113], v[144:145]
	v_cvt_pk_bf16_f32 v167, v152, v153
	global_store_dwordx2 v169, v[166:167], s[14:15] offset:3584
	s_add_u32 s0, s0, 2
	s_cmp_lt_u32 s0, 16
	s_cbranch_scc1 .Lrm2_loop
	s_bitcmp1_b32 s5, 0
	s_cbranch_scc1 .Lrm2_done
	s_mov_b32 s4, 4
	s_branch .Lrm2_coef
.Lrm2_ctxrow:
	s_lshr_b32 s8, s5, 1
	s_lshl_b32 s8, s8, 13
	s_add_u32 s8, s8, 0x3d000000
	s_add_u32 s6, s52, s8
	s_addc_u32 s7, s53, 0
	s_sub_u32 s8, s8, 0x3d000000
	global_load_dwordx4 v[0:3], v80, s[6:7] offset:0 nt
	global_load_dwordx4 v[4:7], v80, s[6:7] offset:1024 nt
	global_load_dwordx4 v[8:11], v80, s[6:7] offset:2048 nt
	global_load_dwordx4 v[12:15], v80, s[6:7] offset:3072 nt
	global_load_dwordx4 v[16:19], v168, s[6:7] offset:0 nt
	global_load_dwordx4 v[20:23], v168, s[6:7] offset:1024 nt
	global_load_dwordx4 v[24:27], v168, s[6:7] offset:2048 nt
	global_load_dwordx4 v[28:31], v168, s[6:7] offset:3072 nt
	s_lshr_b32 s8, s5, 1
	s_add_u32 s1, s8, 0x8000
	s_lshl_b32 s8, s8, 13
	s_add_u32 s9, s8, 0x3d000000
	s_add_u32 s10, s52, s9
	s_addc_u32 s11, s53, 0
	s_lshl_b32 s8, s1, 12
	s_add_u32 s9, s8, 0x34c00000
	s_add_u32 s12, s52, s9
	s_addc_u32 s13, s53, 0
	s_add_u32 s9, s8, 0x2c800000
	s_add_u32 s14, s52, s9
	s_addc_u32 s15, s53, 0
	global_load_dwordx2 v[32:33], v169, s[12:13] offset:0 nt
	global_load_dwordx2 v[34:35], v169, s[12:13] offset:512 nt
	global_load_dwordx2 v[36:37], v169, s[12:13] offset:1024 nt
	global_load_dwordx2 v[38:39], v169, s[12:13] offset:1536 nt
	global_load_dwordx2 v[40:41], v169, s[12:13] offset:2048 nt
	global_load_dwordx2 v[42:43], v169, s[12:13] offset:2560 nt
	global_load_dwordx2 v[44:45], v169, s[12:13] offset:3072 nt
	global_load_dwordx2 v[46:47], v169, s[12:13] offset:3584 nt
	s_waitcnt vmcnt(0)
	v_lshlrev_b32_e32 v146, 16, v32
	v_and_b32_e32 v147, 0xffff0000, v32
	v_pk_mul_f32 v[154:155], v[146:147], v[146:147]
	v_lshlrev_b32_e32 v148, 16, v33
	v_and_b32_e32 v149, 0xffff0000, v33
	v_pk_mul_f32 v[156:157], v[148:149], v[148:149]
	v_lshlrev_b32_e32 v150, 16, v34
	v_and_b32_e32 v151, 0xffff0000, v34
	v_pk_fma_f32 v[154:155], v[150:151], v[150:151], v[154:155]
	v_lshlrev_b32_e32 v152, 16, v35
	v_and_b32_e32 v153, 0xffff0000, v35
	v_pk_fma_f32 v[156:157], v[152:153], v[152:153], v[156:157]
	v_lshlrev_b32_e32 v146, 16, v36
	v_and_b32_e32 v147, 0xffff0000, v36
	v_pk_fma_f32 v[154:155], v[146:147], v[146:147], v[154:155]
	v_lshlrev_b32_e32 v148, 16, v37
	v_and_b32_e32 v149, 0xffff0000, v37
	v_pk_fma_f32 v[156:157], v[148:149], v[148:149], v[156:157]
	v_lshlrev_b32_e32 v150, 16, v38
	v_and_b32_e32 v151, 0xffff0000, v38
	v_pk_fma_f32 v[154:155], v[150:151], v[150:151], v[154:155]
	v_lshlrev_b32_e32 v152, 16, v39
	v_and_b32_e32 v153, 0xffff0000, v39
	v_pk_fma_f32 v[156:157], v[152:153], v[152:153], v[156:157]
	v_lshlrev_b32_e32 v146, 16, v40
	v_and_b32_e32 v147, 0xffff0000, v40
	v_pk_fma_f32 v[154:155], v[146:147], v[146:147], v[154:155]
	v_lshlrev_b32_e32 v148, 16, v41
	v_and_b32_e32 v149, 0xffff0000, v41
	v_pk_fma_f32 v[156:157], v[148:149], v[148:149], v[156:157]
	v_lshlrev_b32_e32 v150, 16, v42
	v_and_b32_e32 v151, 0xffff0000, v42
	v_pk_fma_f32 v[154:155], v[150:151], v[150:151], v[154:155]
	v_lshlrev_b32_e32 v152, 16, v43
	v_and_b32_e32 v153, 0xffff0000, v43
	v_pk_fma_f32 v[156:157], v[152:153], v[152:153], v[156:157]
	v_lshlrev_b32_e32 v146, 16, v44
	v_and_b32_e32 v147, 0xffff0000, v44
	v_pk_fma_f32 v[154:155], v[146:147], v[146:147], v[154:155]
	v_lshlrev_b32_e32 v148, 16, v45
	v_and_b32_e32 v149, 0xffff0000, v45
	v_pk_fma_f32 v[156:157], v[148:149], v[148:149], v[156:157]
	v_lshlrev_b32_e32 v150, 16, v46
	v_and_b32_e32 v151, 0xffff0000, v46
	v_pk_fma_f32 v[154:155], v[150:151], v[150:151], v[154:155]
	v_lshlrev_b32_e32 v152, 16, v47
	v_and_b32_e32 v153, 0xffff0000, v47
	v_pk_fma_f32 v[156:157], v[152:153], v[152:153], v[156:157]
	v_pk_add_f32 v[154:155], v[154:155], v[156:157]
	s_nop 0
	v_add_f32_e32 v173, v154, v155
	s_nop 1
	v_add_f32_dpp v173, v173, v173 quad_perm:[1,0,3,2] row_mask:0xf bank_mask:0xf
	s_nop 1
	v_add_f32_dpp v173, v173, v173 quad_perm:[2,3,0,1] row_mask:0xf bank_mask:0xf
	s_nop 1
	v_add_f32_dpp v173, v173, v173 row_half_mirror row_mask:0xf bank_mask:0xf
	s_nop 1
	v_add_f32_dpp v173, v173, v173 row_mirror row_mask:0xf bank_mask:0xf
	s_nop 1
	v_add_f32_dpp v173, v173, v173 row_bcast:15 row_mask:0xa bank_mask:0xf
	s_nop 1
	v_add_f32_dpp v173, v173, v173 row_bcast:31 row_mask:0xc bank_mask:0xf
	s_nop 1
	v_readlane_b32 s8, v173, 63
	s_nop 3
	v_mov_b32_e32 v158, s8
	v_fma_f32 v158, v158, v171, v172
	v_rsq_f32_e32 v158, v158
	s_nop 1
	v_lshlrev_b32_e32 v146, 16, v32
	v_and_b32_e32 v147, 0xffff0000, v32
	v_pk_mul_f32 v[146:147], v[146:147], v[158:159] op_sel_hi:[1,0]
	v_pk_fma_f32 v[0:1], v[48:49], v[146:147], v[0:1]
	v_lshlrev_b32_e32 v148, 16, v33
	v_and_b32_e32 v149, 0xffff0000, v33
	v_pk_mul_f32 v[148:149], v[148:149], v[158:159] op_sel_hi:[1,0]
	v_pk_fma_f32 v[2:3], v[50:51], v[148:149], v[2:3]
	v_lshlrev_b32_e32 v150, 16, v34
	v_and_b32_e32 v151, 0xffff0000, v34
	v_pk_mul_f32 v[150:151], v[150:151], v[158:159] op_sel_hi:[1,0]
	v_pk_fma_f32 v[4:5], v[52:53], v[150:151], v[4:5]
	v_lshlrev_b32_e32 v152, 16, v35
	v_and_b32_e32 v153, 0xffff0000, v35
	v_pk_mul_f32 v[152:153], v[152:153], v[158:159] op_sel_hi:[1,0]
	v_pk_fma_f32 v[6:7], v[54:55], v[152:153], v[6:7]
	v_lshlrev_b32_e32 v146, 16, v36
	v_and_b32_e32 v147, 0xffff0000, v36
	v_pk_mul_f32 v[146:147], v[146:147], v[158:159] op_sel_hi:[1,0]
	v_pk_fma_f32 v[8:9], v[56:57], v[146:147], v[8:9]
	v_lshlrev_b32_e32 v148, 16, v37
	v_and_b32_e32 v149, 0xffff0000, v37
	v_pk_mul_f32 v[148:149], v[148:149], v[158:159] op_sel_hi:[1,0]
	v_pk_fma_f32 v[10:11], v[58:59], v[148:149], v[10:11]
	v_lshlrev_b32_e32 v150, 16, v38
	v_and_b32_e32 v151, 0xffff0000, v38
	v_pk_mul_f32 v[150:151], v[150:151], v[158:159] op_sel_hi:[1,0]
	v_pk_fma_f32 v[12:13], v[60:61], v[150:151], v[12:13]
	v_lshlrev_b32_e32 v152, 16, v39
	v_and_b32_e32 v153, 0xffff0000, v39
	v_pk_mul_f32 v[152:153], v[152:153], v[158:159] op_sel_hi:[1,0]
	v_pk_fma_f32 v[14:15], v[62:63], v[152:153], v[14:15]
	v_lshlrev_b32_e32 v146, 16, v40
	v_and_b32_e32 v147, 0xffff0000, v40
	v_pk_mul_f32 v[146:147], v[146:147], v[158:159] op_sel_hi:[1,0]
	v_pk_fma_f32 v[16:17], v[64:65], v[146:147], v[16:17]
	v_lshlrev_b32_e32 v148, 16, v41
	v_and_b32_e32 v149, 0xffff0000, v41
	v_pk_mul_f32 v[148:149], v[148:149], v[158:159] op_sel_hi:[1,0]
	v_pk_fma_f32 v[18:19], v[66:67], v[148:149], v[18:19]
	v_lshlrev_b32_e32 v150, 16, v42
	v_and_b32_e32 v151, 0xffff0000, v42
	v_pk_mul_f32 v[150:151], v[150:151], v[158:159] op_sel_hi:[1,0]
	v_pk_fma_f32 v[20:21], v[68:69], v[150:151], v[20:21]
	v_lshlrev_b32_e32 v152, 16, v43
	v_and_b32_e32 v153, 0xffff0000, v43
	v_pk_mul_f32 v[152:153], v[152:153], v[158:159] op_sel_hi:[1,0]
	v_pk_fma_f32 v[22:23], v[70:71], v[152:153], v[22:23]
	v_lshlrev_b32_e32 v146, 16, v44
	v_and_b32_e32 v147, 0xffff0000, v44
	v_pk_mul_f32 v[146:147], v[146:147], v[158:159] op_sel_hi:[1,0]
	v_pk_fma_f32 v[24:25], v[72:73], v[146:147], v[24:25]
	v_lshlrev_b32_e32 v148, 16, v45
	v_and_b32_e32 v149, 0xffff0000, v45
	v_pk_mul_f32 v[148:149], v[148:149], v[158:159] op_sel_hi:[1,0]
	v_pk_fma_f32 v[26:27], v[74:75], v[148:149], v[26:27]
	v_lshlrev_b32_e32 v150, 16, v46
	v_and_b32_e32 v151, 0xffff0000, v46
	v_pk_mul_f32 v[150:151], v[150:151], v[158:159] op_sel_hi:[1,0]
	v_pk_fma_f32 v[28:29], v[76:77], v[150:151], v[28:29]
	v_lshlrev_b32_e32 v152, 16, v47
	v_and_b32_e32 v153, 0xffff0000, v47
	v_pk_mul_f32 v[152:153], v[152:153], v[158:159] op_sel_hi:[1,0]
	v_pk_fma_f32 v[30:31], v[78:79], v[152:153], v[30:31]
	s_nop 0
	global_store_dwordx4 v80, v[0:3], s[10:11] offset:0 nt
	global_store_dwordx4 v80, v[4:7], s[10:11] offset:1024 nt
	global_store_dwordx4 v80, v[8:11], s[10:11] offset:2048 nt
	global_store_dwordx4 v80, v[12:15], s[10:11] offset:3072 nt
	global_store_dwordx4 v168, v[16:19], s[10:11] offset:0 nt
	global_store_dwordx4 v168, v[20:23], s[10:11] offset:1024 nt
	global_store_dwordx4 v168, v[24:27], s[10:11] offset:2048 nt
	global_store_dwordx4 v168, v[28:31], s[10:11] offset:3072 nt
	v_pk_mul_f32 v[154:155], v[0:1], v[0:1]
	v_pk_mul_f32 v[156:157], v[2:3], v[2:3]
	v_pk_fma_f32 v[154:155], v[4:5], v[4:5], v[154:155]
	v_pk_fma_f32 v[156:157], v[6:7], v[6:7], v[156:157]
	v_pk_fma_f32 v[154:155], v[8:9], v[8:9], v[154:155]
	v_pk_fma_f32 v[156:157], v[10:11], v[10:11], v[156:157]
	v_pk_fma_f32 v[154:155], v[12:13], v[12:13], v[154:155]
	v_pk_fma_f32 v[156:157], v[14:15], v[14:15], v[156:157]
	v_pk_fma_f32 v[154:155], v[16:17], v[16:17], v[154:155]
	v_pk_fma_f32 v[156:157], v[18:19], v[18:19], v[156:157]
	v_pk_fma_f32 v[154:155], v[20:21], v[20:21], v[154:155]
	v_pk_fma_f32 v[156:157], v[22:23], v[22:23], v[156:157]
	v_pk_fma_f32 v[154:155], v[24:25], v[24:25], v[154:155]
	v_pk_fma_f32 v[156:157], v[26:27], v[26:27], v[156:157]
	v_pk_fma_f32 v[154:155], v[28:29], v[28:29], v[154:155]
	v_pk_fma_f32 v[156:157], v[30:31], v[30:31], v[156:157]
	v_pk_add_f32 v[154:155], v[154:155], v[156:157]
	s_nop 0
	v_add_f32_e32 v173, v154, v155
	s_nop 1
	v_add_f32_dpp v173, v173, v173 quad_perm:[1,0,3,2] row_mask:0xf bank_mask:0xf
	s_nop 1
	v_add_f32_dpp v173, v173, v173 quad_perm:[2,3,0,1] row_mask:0xf bank_mask:0xf
	s_nop 1
	v_add_f32_dpp v173, v173, v173 row_half_mirror row_mask:0xf bank_mask:0xf
	s_nop 1
	v_add_f32_dpp v173, v173, v173 row_mirror row_mask:0xf bank_mask:0xf
	s_nop 1
	v_add_f32_dpp v173, v173, v173 row_bcast:15 row_mask:0xa bank_mask:0xf
	s_nop 1
	v_add_f32_dpp v173, v173, v173 row_bcast:31 row_mask:0xc bank_mask:0xf
	s_nop 1
	v_readlane_b32 s8, v173, 63
	s_nop 3
	v_mov_b32_e32 v158, s8
	v_fma_f32 v158, v158, v171, v172
	v_rsq_f32_e32 v158, v158
	s_nop 1
	v_pk_mul_f32 v[146:147], v[0:1], v[158:159] op_sel_hi:[1,0]
	v_pk_fma_f32 v[146:147], v[146:147], v[82:83], v[114:115]
	v_cvt_pk_bf16_f32 v160, v146, v147
	v_pk_mul_f32 v[148:149], v[2:3], v[158:159] op_sel_hi:[1,0]
	v_pk_fma_f32 v[148:149], v[148:149], v[84:85], v[116:117]
	v_cvt_pk_bf16_f32 v161, v148, v149
	global_store_dwordx2 v169, v[160:161], s[14:15] offset:0
	v_pk_mul_f32 v[150:151], v[4:5], v[158:159] op_sel_hi:[1,0]
	v_pk_fma_f32 v[150:151], v[150:151], v[86:87], v[118:119]
	v_cvt_pk_bf16_f32 v162, v150, v151
	v_pk_mul_f32 v[152:153], v[6:7], v[158:159] op_sel_hi:[1,0]
	v_pk_fma_f32 v[152:153], v[152:153], v[88:89], v[120:121]
	v_cvt_pk_bf16_f32 v163, v152, v153
	global_store_dwordx2 v169, v[162:163], s[14:15] offset:512
	v_pk_mul_f32 v[146:147], v[8:9], v[158:159] op_sel_hi:[1,0]
	v_pk_fma_f32 v[146:147], v[146:147], v[90:91], v[122:123]
	v_cvt_pk_bf16_f32 v164, v146, v147
	v_pk_mul_f32 v[148:149], v[10:11], v[158:159] op_sel_hi:[1,0]
	v_pk_fma_f32 v[148:149], v[148:149], v[92:93], v[124:125]
	v_cvt_pk_bf16_f32 v165, v148, v149
	global_store_dwordx2 v169, v[164:165], s[14:15] offset:1024
	v_pk_mul_f32 v[150:151], v[12:13], v[158:159] op_sel_hi:[1,0]
	v_pk_fma_f32 v[150:151], v[150:151], v[94:95], v[126:127]
	v_cvt_pk_bf16_f32 v166, v150, v151
	v_pk_mul_f32 v[152:153], v[14:15], v[158:159] op_sel_hi:[1,0]
	v_pk_fma_f32 v[152:153], v[152:153], v[96:97], v[128:129]
	v_cvt_pk_bf16_f32 v167, v152, v153
	global_store_dwordx2 v169, v[166:167], s[14:15] offset:1536
	v_pk_mul_f32 v[146:147], v[16:17], v[158:159] op_sel_hi:[1,0]
	v_pk_fma_f32 v[146:147], v[146:147], v[98:99], v[130:131]
	v_cvt_pk_bf16_f32 v160, v146, v147
	v_pk_mul_f32 v[148:149], v[18:19], v[158:159] op_sel_hi:[1,0]
	v_pk_fma_f32 v[148:149], v[148:149], v[100:101], v[132:133]
	v_cvt_pk_bf16_f32 v161, v148, v149
	global_store_dwordx2 v169, v[160:161], s[14:15] offset:2048
	v_pk_mul_f32 v[150:151], v[20:21], v[158:159] op_sel_hi:[1,0]
	v_pk_fma_f32 v[150:151], v[150:151], v[102:103], v[134:135]
	v_cvt_pk_bf16_f32 v162, v150, v151
	v_pk_mul_f32 v[152:153], v[22:23], v[158:159] op_sel_hi:[1,0]
	v_pk_fma_f32 v[152:153], v[152:153], v[104:105], v[136:137]
	v_cvt_pk_bf16_f32 v163, v152, v153
	global_store_dwordx2 v169, v[162:163], s[14:15] offset:2560
	v_pk_mul_f32 v[146:147], v[24:25], v[158:159] op_sel_hi:[1,0]
	v_pk_fma_f32 v[146:147], v[146:147], v[106:107], v[138:139]
	v_cvt_pk_bf16_f32 v164, v146, v147
	v_pk_mul_f32 v[148:149], v[26:27], v[158:159] op_sel_hi:[1,0]
	v_pk_fma_f32 v[148:149], v[148:149], v[108:109], v[140:141]
	v_cvt_pk_bf16_f32 v165, v148, v149
	global_store_dwordx2 v169, v[164:165], s[14:15] offset:3072
	v_pk_mul_f32 v[150:151], v[28:29], v[158:159] op_sel_hi:[1,0]
	v_pk_fma_f32 v[150:151], v[150:151], v[110:111], v[142:143]
	v_cvt_pk_bf16_f32 v166, v150, v151
	v_pk_mul_f32 v[152:153], v[30:31], v[158:159] op_sel_hi:[1,0]
	v_pk_fma_f32 v[152:153], v[152:153], v[112:113], v[144:145]
	v_cvt_pk_bf16_f32 v167, v152, v153
	global_store_dwordx2 v169, v[166:167], s[14:15] offset:3584

.Lrm2_orig:
	v_lshlrev_b32_e32 v5, 2, v5
	v_and_b32_e32 v6, 0xfc, v5
	v_or_b32_e32 v16, 0x400, v6
	v_or_b32_e32 v20, 0x500, v6
	v_or_b32_e32 v24, 0x600, v6
	v_or_b32_e32 v28, 0x700, v6
	s_mov_b64 s[6:7], 0x2000
	v_lshlrev_b32_e32 v8, 2, v6
	v_mov_b32_e32 v9, v81
	v_or_b32_e32 v10, 0x100, v6
	v_lshlrev_b32_e32 v18, 2, v16
	v_mov_b32_e32 v19, v81
	v_lshlrev_b32_e32 v22, 2, v20
	v_mov_b32_e32 v23, v81
	v_lshlrev_b32_e32 v26, 2, v24
	v_mov_b32_e32 v27, v81
	v_lshlrev_b32_e32 v30, 2, v28
	v_mov_b32_e32 v31, v81
	s_waitcnt vmcnt(0)
	v_lshl_add_u64 v[2:3], v[2:3], 0, s[6:7]
	v_lshl_add_u64 v[84:85], v[0:1], 0, v[8:9]
	v_or_b32_e32 v12, 0x200, v6
	v_lshl_add_u64 v[86:87], v[0:1], 0, v[18:19]
	v_lshl_add_u64 v[88:89], v[0:1], 0, v[22:23]
	v_lshl_add_u64 v[90:91], v[0:1], 0, v[26:27]
	v_lshl_add_u64 v[92:93], v[0:1], 0, v[30:31]
	v_lshlrev_b32_e32 v0, 2, v10
	v_mov_b32_e32 v1, v81
	v_or_b32_e32 v14, 0x300, v6
	v_lshl_add_u64 v[96:97], v[2:3], 0, v[0:1]
	v_lshlrev_b32_e32 v0, 2, v12
	v_lshl_add_u64 v[98:99], v[2:3], 0, v[0:1]
	v_lshlrev_b32_e32 v0, 2, v14
	v_lshl_add_u64 v[100:101], v[2:3], 0, v[0:1]
	v_mbcnt_hi_u32_b32 v0, -1, v190
	v_and_b32_e32 v1, 64, v0
	v_lshl_add_u64 v[94:95], v[2:3], 0, v[8:9]
	v_lshl_add_u64 v[102:103], v[2:3], 0, v[18:19]
	v_lshl_add_u64 v[104:105], v[2:3], 0, v[22:23]
	v_lshl_add_u64 v[106:107], v[2:3], 0, v[26:27]
	v_lshl_add_u64 v[108:109], v[2:3], 0, v[30:31]
	v_add_u32_e32 v1, 64, v1
	v_xor_b32_e32 v2, 32, v0
	v_cmp_lt_i32_e32 vcc, v2, v1
	s_add_u32 s8, s52, 0x3d80a000
	s_addc_u32 s9, s53, 0
	v_cndmask_b32_e32 v2, v0, v2, vcc
	v_lshlrev_b32_e32 v185, 2, v2
	v_xor_b32_e32 v2, 16, v0
	v_cmp_lt_i32_e32 vcc, v2, v1
	v_lshlrev_b32_e32 v80, 1, v6
	s_cmp_lg_u64 s[58:59], 0
	v_cndmask_b32_e32 v2, v0, v2, vcc
	v_lshlrev_b32_e32 v186, 2, v2
	v_xor_b32_e32 v2, 8, v0
	v_cmp_lt_i32_e32 vcc, v2, v1
	v_lshl_add_u64 v[82:83], s[64:65], 0, v[80:81]
	s_mov_b64 s[10:11], 0
	v_cndmask_b32_e32 v2, v0, v2, vcc
	v_lshlrev_b32_e32 v187, 2, v2
	v_xor_b32_e32 v2, 4, v0
	v_cmp_lt_i32_e32 vcc, v2, v1
	s_cselect_b64 s[12:13], -1, 0
	v_lshl_add_u64 v[110:111], s[62:63], 0, v[80:81]
	v_cndmask_b32_e32 v2, v0, v2, vcc
	v_lshlrev_b32_e32 v188, 2, v2
	v_xor_b32_e32 v2, 2, v0
	v_cmp_lt_i32_e32 vcc, v2, v1
	s_lshl_b32 s4, s54, 4
	s_movk_i32 s5, 0x4000
	v_cndmask_b32_e32 v2, v0, v2, vcc
	v_lshlrev_b32_e32 v191, 2, v2
	v_xor_b32_e32 v2, 1, v0
	v_cmp_lt_i32_e32 vcc, v2, v1
	s_movk_i32 s41, 0x3000
	s_mov_b64 s[14:15], 0x1000
	v_cndmask_b32_e32 v0, v0, v2, vcc
	v_lshlrev_b32_e32 v192, 2, v0
	v_lshlrev_b32_e32 v0, 1, v4
	v_lshl_add_u32 v112, s0, 4, v0
	s_movk_i32 s42, 0x1000
	s_mov_b64 s[16:17], 0x1400
	s_mov_b64 s[18:19], 0x1800
	s_mov_b64 s[20:21], 0x1c00
	s_movk_i32 s43, 0x2000
	s_mov_b64 s[22:23], 0x2400
	s_mov_b64 s[24:25], 0x2800
	s_mov_b64 s[26:27], 0x2c00
	s_mov_b64 s[28:29], 0x3000
	s_mov_b64 s[34:35], 0x3400
	s_mov_b64 s[36:37], 0x3800
	s_mov_b64 s[38:39], 0x3c00
	s_mov_b32 s40, 0x3a000000
	s_mov_b32 s44, 0x800000
	v_lshlrev_b32_e32 v114, 2, v16
	v_lshlrev_b32_e32 v116, 2, v20
	v_lshlrev_b32_e32 v118, 2, v24
	v_lshlrev_b32_e32 v120, 2, v28
	v_lshlrev_b32_e32 v80, 2, v6
	v_lshlrev_b32_e32 v122, 2, v10
	v_lshlrev_b32_e32 v124, 2, v12
	v_lshlrev_b32_e32 v126, 2, v14
	s_movk_i32 s45, 0x41ff
	v_mov_b32_e32 v128, 0x358637bd
	s_branch .LBB0_1202

.LBB0_1920:
	s_or_b64 exec, exec, s[0:1]
	v_readlane_b32 s0, v252, 7
	v_mov_b32_e32 v81, 0
	v_readlane_b32 s1, v252, 8
	s_waitcnt lgkmcnt(0)
	s_barrier
	v_mov_b32_e32 v5, v189
	s_nop 1
	global_load_dwordx4 v[0:3], v81, s[0:1]
	s_mov_b32 s0, s33
	v_ashrrev_i32_e32 v4, 6, v5
	s_movk_i32 s1, 0x4000
	v_lshl_add_u32 v137, s0, 3, v4
	v_cmp_gt_i32_e32 vcc, s1, v137
	s_and_saveexec_b64 s[2:3], vcc
	s_cbranch_execz .LBB0_1925
	s_cmpk_lg_i32 s94, 0x800
	s_cbranch_scc1 .Lrm3_orig
	s_waitcnt vmcnt(0) lgkmcnt(0)
	v_and_b32_e32 v170, 63, v189
	v_lshrrev_b32_e32 v173, 6, v189
	v_lshlrev_b32_e32 v80, 4, v170
	v_lshlrev_b32_e32 v169, 3, v170
	v_readfirstlane_b32 s5, v173
	v_add_u32_e32 v168, 0x1000, v80
	v_mov_b32_e32 v170, 0
	v_mov_b32_e32 v171, 0x3a000000
	v_mov_b32_e32 v172, 0x358637bd
	s_lshl_b32 s8, s33, 3
	s_add_u32 s5, s5, s8
	s_add_u32 s8, s52, 0x3e500000
	s_addc_u32 s9, s53, 0
	global_load_dwordx2 v[174:175], v170, s[8:9] offset:56
	global_load_dwordx2 v[176:177], v170, s[8:9] offset:64
	s_waitcnt vmcnt(0)
	v_mov_b32_e32 v173, 0x2000
	v_add_co_u32_e32 v174, vcc, v174, v173
	s_nop 1
	v_addc_co_u32_e32 v175, vcc, 0, v175, vcc
	v_mov_b32_e32 v173, 0x2000
	v_add_co_u32_e32 v176, vcc, v176, v173
	s_nop 1
	v_addc_co_u32_e32 v177, vcc, 0, v177, vcc
	s_mov_b32 s0, 0
	s_lshr_b32 s4, s5, 9
.Lrm3_coef:
	v_readfirstlane_b32 s8, v174
	v_readfirstlane_b32 s9, v175
	s_nop 4
	global_load_dwordx4 v[0:3], v80, s[8:9] offset:0
	global_load_dwordx4 v[4:7], v80, s[8:9] offset:1024
	global_load_dwordx4 v[8:11], v80, s[8:9] offset:2048
	global_load_dwordx4 v[12:15], v80, s[8:9] offset:3072
	global_load_dwordx4 v[16:19], v168, s[8:9] offset:0
	global_load_dwordx4 v[20:23], v168, s[8:9] offset:1024
	global_load_dwordx4 v[24:27], v168, s[8:9] offset:2048
	global_load_dwordx4 v[28:31], v168, s[8:9] offset:3072
	s_mul_i32 s8, s4, 0xc000
	s_add_u32 s8, s8, 0x3d840000
	s_add_u32 s8, s52, s8
	s_addc_u32 s9, s53, 0
	global_load_dwordx4 v[82:85], v80, s[8:9] offset:0
	global_load_dwordx4 v[86:89], v80, s[8:9] offset:1024
	global_load_dwordx4 v[90:93], v80, s[8:9] offset:2048
	global_load_dwordx4 v[94:97], v80, s[8:9] offset:3072
	global_load_dwordx4 v[98:101], v168, s[8:9] offset:0
	global_load_dwordx4 v[102:105], v168, s[8:9] offset:1024
	global_load_dwordx4 v[106:109], v168, s[8:9] offset:2048
	global_load_dwordx4 v[110:113], v168, s[8:9] offset:3072
	s_waitcnt vmcnt(0)
	v_pk_mul_f32 v[48:49], v[82:83], v[0:1]
	v_pk_mul_f32 v[50:51], v[84:85], v[2:3]
	v_pk_mul_f32 v[52:53], v[86:87], v[4:5]
	v_pk_mul_f32 v[54:55], v[88:89], v[6:7]
	v_pk_mul_f32 v[56:57], v[90:91], v[8:9]
	v_pk_mul_f32 v[58:59], v[92:93], v[10:11]
	v_pk_mul_f32 v[60:61], v[94:95], v[12:13]
	v_pk_mul_f32 v[62:63], v[96:97], v[14:15]
	v_pk_mul_f32 v[64:65], v[98:99], v[16:17]
	v_pk_mul_f32 v[66:67], v[100:101], v[18:19]
	v_pk_mul_f32 v[68:69], v[102:103], v[20:21]
	v_pk_mul_f32 v[70:71], v[104:105], v[22:23]
	v_pk_mul_f32 v[72:73], v[106:107], v[24:25]
	v_pk_mul_f32 v[74:75], v[108:109], v[26:27]
	v_pk_mul_f32 v[76:77], v[110:111], v[28:29]
	v_pk_mul_f32 v[78:79], v[112:113], v[30:31]
	v_readfirstlane_b32 s8, v176
	v_readfirstlane_b32 s9, v177
	s_nop 4
	global_load_dwordx4 v[0:3], v80, s[8:9] offset:0
	global_load_dwordx4 v[4:7], v80, s[8:9] offset:1024
	global_load_dwordx4 v[8:11], v80, s[8:9] offset:2048
	global_load_dwordx4 v[12:15], v80, s[8:9] offset:3072
	global_load_dwordx4 v[16:19], v168, s[8:9] offset:0
	global_load_dwordx4 v[20:23], v168, s[8:9] offset:1024
	global_load_dwordx4 v[24:27], v168, s[8:9] offset:2048
	global_load_dwordx4 v[28:31], v168, s[8:9] offset:3072
	s_mul_i32 s8, s4, 0xc000
	s_add_u32 s8, s8, 0x3d844000
	s_add_u32 s8, s52, s8
	s_addc_u32 s9, s53, 0
	global_load_dwordx4 v[114:117], v80, s[8:9] offset:0
	global_load_dwordx4 v[118:121], v80, s[8:9] offset:1024
	global_load_dwordx4 v[122:125], v80, s[8:9] offset:2048
	global_load_dwordx4 v[126:129], v80, s[8:9] offset:3072
	global_load_dwordx4 v[130:133], v168, s[8:9] offset:0
	global_load_dwordx4 v[134:137], v168, s[8:9] offset:1024
	global_load_dwordx4 v[138:141], v168, s[8:9] offset:2048
	global_load_dwordx4 v[142:145], v168, s[8:9] offset:3072
	s_waitcnt vmcnt(0)
	v_pk_add_f32 v[114:115], v[114:115], 1.0 op_sel_hi:[1,0]
	v_pk_add_f32 v[116:117], v[116:117], 1.0 op_sel_hi:[1,0]
	v_pk_add_f32 v[118:119], v[118:119], 1.0 op_sel_hi:[1,0]
	v_pk_add_f32 v[120:121], v[120:121], 1.0 op_sel_hi:[1,0]
	v_pk_add_f32 v[122:123], v[122:123], 1.0 op_sel_hi:[1,0]
	v_pk_add_f32 v[124:125], v[124:125], 1.0 op_sel_hi:[1,0]
	v_pk_add_f32 v[126:127], v[126:127], 1.0 op_sel_hi:[1,0]
	v_pk_add_f32 v[128:129], v[128:129], 1.0 op_sel_hi:[1,0]
	v_pk_add_f32 v[130:131], v[130:131], 1.0 op_sel_hi:[1,0]
	v_pk_add_f32 v[132:133], v[132:133], 1.0 op_sel_hi:[1,0]
	v_pk_add_f32 v[134:135], v[134:135], 1.0 op_sel_hi:[1,0]
	v_pk_add_f32 v[136:137], v[136:137], 1.0 op_sel_hi:[1,0]
	v_pk_add_f32 v[138:139], v[138:139], 1.0 op_sel_hi:[1,0]
	v_pk_add_f32 v[140:141], v[140:141], 1.0 op_sel_hi:[1,0]
	v_pk_add_f32 v[142:143], v[142:143], 1.0 op_sel_hi:[1,0]
	v_pk_add_f32 v[144:145], v[144:145], 1.0 op_sel_hi:[1,0]
	v_pk_mul_f32 v[82:83], v[0:1], v[114:115]
	v_pk_mul_f32 v[84:85], v[2:3], v[116:117]
	v_pk_mul_f32 v[86:87], v[4:5], v[118:119]
	v_pk_mul_f32 v[88:89], v[6:7], v[120:121]
	v_pk_mul_f32 v[90:91], v[8:9], v[122:123]
	v_pk_mul_f32 v[92:93], v[10:11], v[124:125]
	v_pk_mul_f32 v[94:95], v[12:13], v[126:127]
	v_pk_mul_f32 v[96:97], v[14:15], v[128:129]
	v_pk_mul_f32 v[98:99], v[16:17], v[130:131]
	v_pk_mul_f32 v[100:101], v[18:19], v[132:133]
	v_pk_mul_f32 v[102:103], v[20:21], v[134:135]
	v_pk_mul_f32 v[104:105], v[22:23], v[136:137]
	v_pk_mul_f32 v[106:107], v[24:25], v[138:139]
	v_pk_mul_f32 v[108:109], v[26:27], v[140:141]
	v_pk_mul_f32 v[110:111], v[28:29], v[142:143]
	v_pk_mul_f32 v[112:113], v[30:31], v[144:145]
	s_mul_i32 s8, s4, 0xc000
	s_add_u32 s8, s8, 0x3d842000
	s_add_u32 s8, s52, s8
	s_addc_u32 s9, s53, 0
	global_load_dwordx4 v[114:117], v80, s[8:9] offset:0
	global_load_dwordx4 v[118:121], v80, s[8:9] offset:1024
	global_load_dwordx4 v[122:125], v80, s[8:9] offset:2048
	global_load_dwordx4 v[126:129], v80, s[8:9] offset:3072
	global_load_dwordx4 v[130:133], v168, s[8:9] offset:0
	global_load_dwordx4 v[134:137], v168, s[8:9] offset:1024
	global_load_dwordx4 v[138:141], v168, s[8:9] offset:2048
	global_load_dwordx4 v[142:145], v168, s[8:9] offset:3072
	s_cmp_lt_u32 s0, 16
	s_cbranch_scc0 .Lrm3_ctxrow
	s_lshr_b32 s1, s5, 9
	s_lshl_b32 s1, s1, 13
	s_and_b32 s8, s5, 0x1ff
	s_add_u32 s1, s1, s8
	s_add_u32 s8, s0, 0
	s_lshl_b32 s8, s8, 9
	s_add_u32 s1, s1, s8
	s_lshl_b32 s8, s1, 13
	s_add_u32 s6, s58, s8
	s_addc_u32 s7, s59, 0
	global_load_dwordx4 v[0:3], v80, s[6:7] offset:0 nt
	global_load_dwordx4 v[4:7], v80, s[6:7] offset:1024 nt
	global_load_dwordx4 v[8:11], v80, s[6:7] offset:2048 nt
	global_load_dwordx4 v[12:15], v80, s[6:7] offset:3072 nt
	global_load_dwordx4 v[16:19], v168, s[6:7] offset:0 nt
	global_load_dwordx4 v[20:23], v168, s[6:7] offset:1024 nt
	global_load_dwordx4 v[24:27], v168, s[6:7] offset:2048 nt
	global_load_dwordx4 v[28:31], v168, s[6:7] offset:3072 nt
.Lrm3_loop:
	s_lshr_b32 s1, s5, 9
	s_lshl_b32 s1, s1, 13
	s_and_b32 s8, s5, 0x1ff
	s_add_u32 s1, s1, s8
	s_add_u32 s8, s0, 0
	s_lshl_b32 s8, s8, 9
	s_add_u32 s1, s1, s8
	s_lshl_b32 s8, s1, 13
	s_add_u32 s10, s58, s8
	s_addc_u32 s11, s59, 0
	s_lshl_b32 s8, s1, 12
	s_add_u32 s9, s8, 0xb800000
	s_add_u32 s12, s52, s9
	s_addc_u32 s13, s53, 0
	s_add_u32 s9, s8, 0x2c800000
	s_add_u32 s14, s52, s9
	s_addc_u32 s15, s53, 0
	global_load_dwordx2 v[32:33], v169, s[12:13] offset:0 nt
	global_load_dwordx2 v[34:35], v169, s[12:13] offset:512 nt
	global_load_dwordx2 v[36:37], v169, s[12:13] offset:1024 nt
	global_load_dwordx2 v[38:39], v169, s[12:13] offset:1536 nt
	global_load_dwordx2 v[40:41], v169, s[12:13] offset:2048 nt
	global_load_dwordx2 v[42:43], v169, s[12:13] offset:2560 nt
	global_load_dwordx2 v[44:45], v169, s[12:13] offset:3072 nt
	global_load_dwordx2 v[46:47], v169, s[12:13] offset:3584 nt
	s_lshr_b32 s1, s5, 9
	s_lshl_b32 s1, s1, 13
	s_and_b32 s8, s5, 0x1ff
	s_add_u32 s1, s1, s8
	s_add_u32 s8, s0, 1
	s_lshl_b32 s8, s8, 9
	s_add_u32 s1, s1, s8
	s_lshl_b32 s8, s1, 13
	s_add_u32 s6, s58, s8
	s_addc_u32 s7, s59, 0
	global_load_dwordx4 v[178:181], v80, s[6:7] offset:0 nt
	global_load_dwordx4 v[182:185], v80, s[6:7] offset:1024 nt
	global_load_dwordx4 v[192:195], v80, s[6:7] offset:2048 nt
	global_load_dwordx4 v[198:201], v80, s[6:7] offset:3072 nt
	global_load_dwordx4 v[202:205], v168, s[6:7] offset:0 nt
	global_load_dwordx4 v[206:209], v168, s[6:7] offset:1024 nt
	global_load_dwordx4 v[210:213], v168, s[6:7] offset:2048 nt
	global_load_dwordx4 v[214:217], v168, s[6:7] offset:3072 nt
	s_waitcnt vmcnt(8)
	v_lshlrev_b32_e32 v146, 16, v32
	v_and_b32_e32 v147, 0xffff0000, v32
	v_pk_mul_f32 v[154:155], v[146:147], v[146:147]
	v_lshlrev_b32_e32 v148, 16, v33
	v_and_b32_e32 v149, 0xffff0000, v33
	v_pk_mul_f32 v[156:157], v[148:149], v[148:149]
	v_lshlrev_b32_e32 v150, 16, v34
	v_and_b32_e32 v151, 0xffff0000, v34
	v_pk_fma_f32 v[154:155], v[150:151], v[150:151], v[154:155]
	v_lshlrev_b32_e32 v152, 16, v35
	v_and_b32_e32 v153, 0xffff0000, v35
	v_pk_fma_f32 v[156:157], v[152:153], v[152:153], v[156:157]
	v_lshlrev_b32_e32 v146, 16, v36
	v_and_b32_e32 v147, 0xffff0000, v36
	v_pk_fma_f32 v[154:155], v[146:147], v[146:147], v[154:155]
	v_lshlrev_b32_e32 v148, 16, v37
	v_and_b32_e32 v149, 0xffff0000, v37
	v_pk_fma_f32 v[156:157], v[148:149], v[148:149], v[156:157]
	v_lshlrev_b32_e32 v150, 16, v38
	v_and_b32_e32 v151, 0xffff0000, v38
	v_pk_fma_f32 v[154:155], v[150:151], v[150:151], v[154:155]
	v_lshlrev_b32_e32 v152, 16, v39
	v_and_b32_e32 v153, 0xffff0000, v39
	v_pk_fma_f32 v[156:157], v[152:153], v[152:153], v[156:157]
	v_lshlrev_b32_e32 v146, 16, v40
	v_and_b32_e32 v147, 0xffff0000, v40
	v_pk_fma_f32 v[154:155], v[146:147], v[146:147], v[154:155]
	v_lshlrev_b32_e32 v148, 16, v41
	v_and_b32_e32 v149, 0xffff0000, v41
	v_pk_fma_f32 v[156:157], v[148:149], v[148:149], v[156:157]
	v_lshlrev_b32_e32 v150, 16, v42
	v_and_b32_e32 v151, 0xffff0000, v42
	v_pk_fma_f32 v[154:155], v[150:151], v[150:151], v[154:155]
	v_lshlrev_b32_e32 v152, 16, v43
	v_and_b32_e32 v153, 0xffff0000, v43
	v_pk_fma_f32 v[156:157], v[152:153], v[152:153], v[156:157]
	v_lshlrev_b32_e32 v146, 16, v44
	v_and_b32_e32 v147, 0xffff0000, v44
	v_pk_fma_f32 v[154:155], v[146:147], v[146:147], v[154:155]
	v_lshlrev_b32_e32 v148, 16, v45
	v_and_b32_e32 v149, 0xffff0000, v45
	v_pk_fma_f32 v[156:157], v[148:149], v[148:149], v[156:157]
	v_lshlrev_b32_e32 v150, 16, v46
	v_and_b32_e32 v151, 0xffff0000, v46
	v_pk_fma_f32 v[154:155], v[150:151], v[150:151], v[154:155]
	v_lshlrev_b32_e32 v152, 16, v47
	v_and_b32_e32 v153, 0xffff0000, v47
	v_pk_fma_f32 v[156:157], v[152:153], v[152:153], v[156:157]
	v_pk_add_f32 v[154:155], v[154:155], v[156:157]
	s_nop 0
	v_add_f32_e32 v173, v154, v155
	s_nop 1
	v_add_f32_dpp v173, v173, v173 quad_perm:[1,0,3,2] row_mask:0xf bank_mask:0xf
	s_nop 1
	v_add_f32_dpp v173, v173, v173 quad_perm:[2,3,0,1] row_mask:0xf bank_mask:0xf
	s_nop 1
	v_add_f32_dpp v173, v173, v173 row_half_mirror row_mask:0xf bank_mask:0xf
	s_nop 1
	v_add_f32_dpp v173, v173, v173 row_mirror row_mask:0xf bank_mask:0xf
	s_nop 1
	v_add_f32_dpp v173, v173, v173 row_bcast:15 row_mask:0xa bank_mask:0xf
	s_nop 1
	v_add_f32_dpp v173, v173, v173 row_bcast:31 row_mask:0xc bank_mask:0xf
	s_nop 1
	v_readlane_b32 s8, v173, 63
	s_nop 3
	v_mov_b32_e32 v158, s8
	v_fma_f32 v158, v158, v171, v172
	v_rsq_f32_e32 v158, v158
	s_nop 1
	v_lshlrev_b32_e32 v146, 16, v32
	v_and_b32_e32 v147, 0xffff0000, v32
	v_pk_mul_f32 v[146:147], v[146:147], v[158:159] op_sel_hi:[1,0]
	v_pk_fma_f32 v[0:1], v[48:49], v[146:147], v[0:1]
	v_lshlrev_b32_e32 v148, 16, v33
	v_and_b32_e32 v149, 0xffff0000, v33
	v_pk_mul_f32 v[148:149], v[148:149], v[158:159] op_sel_hi:[1,0]
	v_pk_fma_f32 v[2:3], v[50:51], v[148:149], v[2:3]
	v_lshlrev_b32_e32 v150, 16, v34
	v_and_b32_e32 v151, 0xffff0000, v34
	v_pk_mul_f32 v[150:151], v[150:151], v[158:159] op_sel_hi:[1,0]
	v_pk_fma_f32 v[4:5], v[52:53], v[150:151], v[4:5]
	v_lshlrev_b32_e32 v152, 16, v35
	v_and_b32_e32 v153, 0xffff0000, v35
	v_pk_mul_f32 v[152:153], v[152:153], v[158:159] op_sel_hi:[1,0]
	v_pk_fma_f32 v[6:7], v[54:55], v[152:153], v[6:7]
	v_lshlrev_b32_e32 v146, 16, v36
	v_and_b32_e32 v147, 0xffff0000, v36
	v_pk_mul_f32 v[146:147], v[146:147], v[158:159] op_sel_hi:[1,0]
	v_pk_fma_f32 v[8:9], v[56:57], v[146:147], v[8:9]
	v_lshlrev_b32_e32 v148, 16, v37
	v_and_b32_e32 v149, 0xffff0000, v37
	v_pk_mul_f32 v[148:149], v[148:149], v[158:159] op_sel_hi:[1,0]
	v_pk_fma_f32 v[10:11], v[58:59], v[148:149], v[10:11]
	v_lshlrev_b32_e32 v150, 16, v38
	v_and_b32_e32 v151, 0xffff0000, v38
	v_pk_mul_f32 v[150:151], v[150:151], v[158:159] op_sel_hi:[1,0]
	v_pk_fma_f32 v[12:13], v[60:61], v[150:151], v[12:13]
	v_lshlrev_b32_e32 v152, 16, v39
	v_and_b32_e32 v153, 0xffff0000, v39
	v_pk_mul_f32 v[152:153], v[152:153], v[158:159] op_sel_hi:[1,0]
	v_pk_fma_f32 v[14:15], v[62:63], v[152:153], v[14:15]
	v_lshlrev_b32_e32 v146, 16, v40
	v_and_b32_e32 v147, 0xffff0000, v40
	v_pk_mul_f32 v[146:147], v[146:147], v[158:159] op_sel_hi:[1,0]
	v_pk_fma_f32 v[16:17], v[64:65], v[146:147], v[16:17]
	v_lshlrev_b32_e32 v148, 16, v41
	v_and_b32_e32 v149, 0xffff0000, v41
	v_pk_mul_f32 v[148:149], v[148:149], v[158:159] op_sel_hi:[1,0]
	v_pk_fma_f32 v[18:19], v[66:67], v[148:149], v[18:19]
	v_lshlrev_b32_e32 v150, 16, v42
	v_and_b32_e32 v151, 0xffff0000, v42
	v_pk_mul_f32 v[150:151], v[150:151], v[158:159] op_sel_hi:[1,0]
	v_pk_fma_f32 v[20:21], v[68:69], v[150:151], v[20:21]
	v_lshlrev_b32_e32 v152, 16, v43
	v_and_b32_e32 v153, 0xffff0000, v43
	v_pk_mul_f32 v[152:153], v[152:153], v[158:159] op_sel_hi:[1,0]
	v_pk_fma_f32 v[22:23], v[70:71], v[152:153], v[22:23]
	v_lshlrev_b32_e32 v146, 16, v44
	v_and_b32_e32 v147, 0xffff0000, v44
	v_pk_mul_f32 v[146:147], v[146:147], v[158:159] op_sel_hi:[1,0]
	v_pk_fma_f32 v[24:25], v[72:73], v[146:147], v[24:25]
	v_lshlrev_b32_e32 v148, 16, v45
	v_and_b32_e32 v149, 0xffff0000, v45
	v_pk_mul_f32 v[148:149], v[148:149], v[158:159] op_sel_hi:[1,0]
	v_pk_fma_f32 v[26:27], v[74:75], v[148:149], v[26:27]
	v_lshlrev_b32_e32 v150, 16, v46
	v_and_b32_e32 v151, 0xffff0000, v46
	v_pk_mul_f32 v[150:151], v[150:151], v[158:159] op_sel_hi:[1,0]
	v_pk_fma_f32 v[28:29], v[76:77], v[150:151], v[28:29]
	v_lshlrev_b32_e32 v152, 16, v47
	v_and_b32_e32 v153, 0xffff0000, v47
	v_pk_mul_f32 v[152:153], v[152:153], v[158:159] op_sel_hi:[1,0]
	v_pk_fma_f32 v[30:31], v[78:79], v[152:153], v[30:31]
	s_nop 0
	global_store_dwordx4 v80, v[0:3], s[10:11] offset:0 nt
	global_store_dwordx4 v80, v[4:7], s[10:11] offset:1024 nt
	global_store_dwordx4 v80, v[8:11], s[10:11] offset:2048 nt
	global_store_dwordx4 v80, v[12:15], s[10:11] offset:3072 nt
	global_store_dwordx4 v168, v[16:19], s[10:11] offset:0 nt
	global_store_dwordx4 v168, v[20:23], s[10:11] offset:1024 nt
	global_store_dwordx4 v168, v[24:27], s[10:11] offset:2048 nt
	global_store_dwordx4 v168, v[28:31], s[10:11] offset:3072 nt
	v_pk_mul_f32 v[154:155], v[0:1], v[0:1]
	v_pk_mul_f32 v[156:157], v[2:3], v[2:3]
	v_pk_fma_f32 v[154:155], v[4:5], v[4:5], v[154:155]
	v_pk_fma_f32 v[156:157], v[6:7], v[6:7], v[156:157]
	v_pk_fma_f32 v[154:155], v[8:9], v[8:9], v[154:155]
	v_pk_fma_f32 v[156:157], v[10:11], v[10:11], v[156:157]
	v_pk_fma_f32 v[154:155], v[12:13], v[12:13], v[154:155]
	v_pk_fma_f32 v[156:157], v[14:15], v[14:15], v[156:157]
	v_pk_fma_f32 v[154:155], v[16:17], v[16:17], v[154:155]
	v_pk_fma_f32 v[156:157], v[18:19], v[18:19], v[156:157]
	v_pk_fma_f32 v[154:155], v[20:21], v[20:21], v[154:155]
	v_pk_fma_f32 v[156:157], v[22:23], v[22:23], v[156:157]
	v_pk_fma_f32 v[154:155], v[24:25], v[24:25], v[154:155]
	v_pk_fma_f32 v[156:157], v[26:27], v[26:27], v[156:157]
	v_pk_fma_f32 v[154:155], v[28:29], v[28:29], v[154:155]
	v_pk_fma_f32 v[156:157], v[30:31], v[30:31], v[156:157]
	v_pk_add_f32 v[154:155], v[154:155], v[156:157]
	s_nop 0
	v_add_f32_e32 v173, v154, v155
	s_nop 1
	v_add_f32_dpp v173, v173, v173 quad_perm:[1,0,3,2] row_mask:0xf bank_mask:0xf
	s_nop 1
	v_add_f32_dpp v173, v173, v173 quad_perm:[2,3,0,1] row_mask:0xf bank_mask:0xf
	s_nop 1
	v_add_f32_dpp v173, v173, v173 row_half_mirror row_mask:0xf bank_mask:0xf
	s_nop 1
	v_add_f32_dpp v173, v173, v173 row_mirror row_mask:0xf bank_mask:0xf
	s_nop 1
	v_add_f32_dpp v173, v173, v173 row_bcast:15 row_mask:0xa bank_mask:0xf
	s_nop 1
	v_add_f32_dpp v173, v173, v173 row_bcast:31 row_mask:0xc bank_mask:0xf
	s_nop 1
	v_readlane_b32 s8, v173, 63
	s_nop 3
	v_mov_b32_e32 v158, s8
	v_fma_f32 v158, v158, v171, v172
	v_rsq_f32_e32 v158, v158
	s_nop 1
	v_pk_mul_f32 v[146:147], v[0:1], v[158:159] op_sel_hi:[1,0]
	v_pk_fma_f32 v[146:147], v[146:147], v[82:83], v[114:115]
	v_cvt_pk_bf16_f32 v160, v146, v147
	v_pk_mul_f32 v[148:149], v[2:3], v[158:159] op_sel_hi:[1,0]
	v_pk_fma_f32 v[148:149], v[148:149], v[84:85], v[116:117]
	v_cvt_pk_bf16_f32 v161, v148, v149
	global_store_dwordx2 v169, v[160:161], s[14:15] offset:0
	v_pk_mul_f32 v[150:151], v[4:5], v[158:159] op_sel_hi:[1,0]
	v_pk_fma_f32 v[150:151], v[150:151], v[86:87], v[118:119]
	v_cvt_pk_bf16_f32 v162, v150, v151
	v_pk_mul_f32 v[152:153], v[6:7], v[158:159] op_sel_hi:[1,0]
	v_pk_fma_f32 v[152:153], v[152:153], v[88:89], v[120:121]
	v_cvt_pk_bf16_f32 v163, v152, v153
	global_store_dwordx2 v169, v[162:163], s[14:15] offset:512
	v_pk_mul_f32 v[146:147], v[8:9], v[158:159] op_sel_hi:[1,0]
	v_pk_fma_f32 v[146:147], v[146:147], v[90:91], v[122:123]
	v_cvt_pk_bf16_f32 v164, v146, v147
	v_pk_mul_f32 v[148:149], v[10:11], v[158:159] op_sel_hi:[1,0]
	v_pk_fma_f32 v[148:149], v[148:149], v[92:93], v[124:125]
	v_cvt_pk_bf16_f32 v165, v148, v149
	global_store_dwordx2 v169, v[164:165], s[14:15] offset:1024
	v_pk_mul_f32 v[150:151], v[12:13], v[158:159] op_sel_hi:[1,0]
	v_pk_fma_f32 v[150:151], v[150:151], v[94:95], v[126:127]
	v_cvt_pk_bf16_f32 v166, v150, v151
	v_pk_mul_f32 v[152:153], v[14:15], v[158:159] op_sel_hi:[1,0]
	v_pk_fma_f32 v[152:153], v[152:153], v[96:97], v[128:129]
	v_cvt_pk_bf16_f32 v167, v152, v153
	global_store_dwordx2 v169, v[166:167], s[14:15] offset:1536
	v_pk_mul_f32 v[146:147], v[16:17], v[158:159] op_sel_hi:[1,0]
	v_pk_fma_f32 v[146:147], v[146:147], v[98:99], v[130:131]
	v_cvt_pk_bf16_f32 v160, v146, v147
	v_pk_mul_f32 v[148:149], v[18:19], v[158:159] op_sel_hi:[1,0]
	v_pk_fma_f32 v[148:149], v[148:149], v[100:101], v[132:133]
	v_cvt_pk_bf16_f32 v161, v148, v149
	global_store_dwordx2 v169, v[160:161], s[14:15] offset:2048
	v_pk_mul_f32 v[150:151], v[20:21], v[158:159] op_sel_hi:[1,0]
	v_pk_fma_f32 v[150:151], v[150:151], v[102:103], v[134:135]
	v_cvt_pk_bf16_f32 v162, v150, v151
	v_pk_mul_f32 v[152:153], v[22:23], v[158:159] op_sel_hi:[1,0]
	v_pk_fma_f32 v[152:153], v[152:153], v[104:105], v[136:137]
	v_cvt_pk_bf16_f32 v163, v152, v153
	global_store_dwordx2 v169, v[162:163], s[14:15] offset:2560
	v_pk_mul_f32 v[146:147], v[24:25], v[158:159] op_sel_hi:[1,0]
	v_pk_fma_f32 v[146:147], v[146:147], v[106:107], v[138:139]
	v_cvt_pk_bf16_f32 v164, v146, v147
	v_pk_mul_f32 v[148:149], v[26:27], v[158:159] op_sel_hi:[1,0]
	v_pk_fma_f32 v[148:149], v[148:149], v[108:109], v[140:141]
	v_cvt_pk_bf16_f32 v165, v148, v149
	global_store_dwordx2 v169, v[164:165], s[14:15] offset:3072
	v_pk_mul_f32 v[150:151], v[28:29], v[158:159] op_sel_hi:[1,0]
	v_pk_fma_f32 v[150:151], v[150:151], v[110:111], v[142:143]
	v_cvt_pk_bf16_f32 v166, v150, v151
	v_pk_mul_f32 v[152:153], v[30:31], v[158:159] op_sel_hi:[1,0]
	v_pk_fma_f32 v[152:153], v[152:153], v[112:113], v[144:145]
	v_cvt_pk_bf16_f32 v167, v152, v153
	global_store_dwordx2 v169, v[166:167], s[14:15] offset:3584
	s_lshr_b32 s1, s5, 9
	s_lshl_b32 s1, s1, 13
	s_and_b32 s8, s5, 0x1ff
	s_add_u32 s1, s1, s8
	s_add_u32 s8, s0, 1
	s_lshl_b32 s8, s8, 9
	s_add_u32 s1, s1, s8
	s_lshl_b32 s8, s1, 13
	s_add_u32 s10, s58, s8
	s_addc_u32 s11, s59, 0
	s_lshl_b32 s8, s1, 12
	s_add_u32 s9, s8, 0xb800000
	s_add_u32 s12, s52, s9
	s_addc_u32 s13, s53, 0
	s_add_u32 s9, s8, 0x2c800000
	s_add_u32 s14, s52, s9
	s_addc_u32 s15, s53, 0
	global_load_dwordx2 v[32:33], v169, s[12:13] offset:0 nt
	global_load_dwordx2 v[34:35], v169, s[12:13] offset:512 nt
	global_load_dwordx2 v[36:37], v169, s[12:13] offset:1024 nt
	global_load_dwordx2 v[38:39], v169, s[12:13] offset:1536 nt
	global_load_dwordx2 v[40:41], v169, s[12:13] offset:2048 nt
	global_load_dwordx2 v[42:43], v169, s[12:13] offset:2560 nt
	global_load_dwordx2 v[44:45], v169, s[12:13] offset:3072 nt
	global_load_dwordx2 v[46:47], v169, s[12:13] offset:3584 nt
	s_cmp_lt_u32 s0, 14
	s_cbranch_scc0 .Lrm3_nopf_o
	s_lshr_b32 s1, s5, 9
	s_lshl_b32 s1, s1, 13
	s_and_b32 s8, s5, 0x1ff
	s_add_u32 s1, s1, s8
	s_add_u32 s8, s0, 2
	s_lshl_b32 s8, s8, 9
	s_add_u32 s1, s1, s8
	s_lshl_b32 s8, s1, 13
	s_add_u32 s6, s58, s8
	s_addc_u32 s7, s59, 0
	global_load_dwordx4 v[0:3], v80, s[6:7] offset:0 nt
	global_load_dwordx4 v[4:7], v80, s[6:7] offset:1024 nt
	global_load_dwordx4 v[8:11], v80, s[6:7] offset:2048 nt
	global_load_dwordx4 v[12:15], v80, s[6:7] offset:3072 nt
	global_load_dwordx4 v[16:19], v168, s[6:7] offset:0 nt
	global_load_dwordx4 v[20:23], v168, s[6:7] offset:1024 nt
	global_load_dwordx4 v[24:27], v168, s[6:7] offset:2048 nt
	global_load_dwordx4 v[28:31], v168, s[6:7] offset:3072 nt
	s_waitcnt vmcnt(8)
	s_branch .Lrm3_pfd_o

.Lrm3_pfd_o:
	v_lshlrev_b32_e32 v146, 16, v32
	v_and_b32_e32 v147, 0xffff0000, v32
	v_pk_mul_f32 v[154:155], v[146:147], v[146:147]
	v_lshlrev_b32_e32 v148, 16, v33
	v_and_b32_e32 v149, 0xffff0000, v33
	v_pk_mul_f32 v[156:157], v[148:149], v[148:149]
	v_lshlrev_b32_e32 v150, 16, v34
	v_and_b32_e32 v151, 0xffff0000, v34
	v_pk_fma_f32 v[154:155], v[150:151], v[150:151], v[154:155]
	v_lshlrev_b32_e32 v152, 16, v35
	v_and_b32_e32 v153, 0xffff0000, v35
	v_pk_fma_f32 v[156:157], v[152:153], v[152:153], v[156:157]
	v_lshlrev_b32_e32 v146, 16, v36
	v_and_b32_e32 v147, 0xffff0000, v36
	v_pk_fma_f32 v[154:155], v[146:147], v[146:147], v[154:155]
	v_lshlrev_b32_e32 v148, 16, v37
	v_and_b32_e32 v149, 0xffff0000, v37
	v_pk_fma_f32 v[156:157], v[148:149], v[148:149], v[156:157]
	v_lshlrev_b32_e32 v150, 16, v38
	v_and_b32_e32 v151, 0xffff0000, v38
	v_pk_fma_f32 v[154:155], v[150:151], v[150:151], v[154:155]
	v_lshlrev_b32_e32 v152, 16, v39
	v_and_b32_e32 v153, 0xffff0000, v39
	v_pk_fma_f32 v[156:157], v[152:153], v[152:153], v[156:157]
	v_lshlrev_b32_e32 v146, 16, v40
	v_and_b32_e32 v147, 0xffff0000, v40
	v_pk_fma_f32 v[154:155], v[146:147], v[146:147], v[154:155]
	v_lshlrev_b32_e32 v148, 16, v41
	v_and_b32_e32 v149, 0xffff0000, v41
	v_pk_fma_f32 v[156:157], v[148:149], v[148:149], v[156:157]
	v_lshlrev_b32_e32 v150, 16, v42
	v_and_b32_e32 v151, 0xffff0000, v42
	v_pk_fma_f32 v[154:155], v[150:151], v[150:151], v[154:155]
	v_lshlrev_b32_e32 v152, 16, v43
	v_and_b32_e32 v153, 0xffff0000, v43
	v_pk_fma_f32 v[156:157], v[152:153], v[152:153], v[156:157]
	v_lshlrev_b32_e32 v146, 16, v44
	v_and_b32_e32 v147, 0xffff0000, v44
	v_pk_fma_f32 v[154:155], v[146:147], v[146:147], v[154:155]
	v_lshlrev_b32_e32 v148, 16, v45
	v_and_b32_e32 v149, 0xffff0000, v45
	v_pk_fma_f32 v[156:157], v[148:149], v[148:149], v[156:157]
	v_lshlrev_b32_e32 v150, 16, v46
	v_and_b32_e32 v151, 0xffff0000, v46
	v_pk_fma_f32 v[154:155], v[150:151], v[150:151], v[154:155]
	v_lshlrev_b32_e32 v152, 16, v47
	v_and_b32_e32 v153, 0xffff0000, v47
	v_pk_fma_f32 v[156:157], v[152:153], v[152:153], v[156:157]
	v_pk_add_f32 v[154:155], v[154:155], v[156:157]
	s_nop 0
	v_add_f32_e32 v173, v154, v155
	s_nop 1
	v_add_f32_dpp v173, v173, v173 quad_perm:[1,0,3,2] row_mask:0xf bank_mask:0xf
	s_nop 1
	v_add_f32_dpp v173, v173, v173 quad_perm:[2,3,0,1] row_mask:0xf bank_mask:0xf
	s_nop 1
	v_add_f32_dpp v173, v173, v173 row_half_mirror row_mask:0xf bank_mask:0xf
	s_nop 1
	v_add_f32_dpp v173, v173, v173 row_mirror row_mask:0xf bank_mask:0xf
	s_nop 1
	v_add_f32_dpp v173, v173, v173 row_bcast:15 row_mask:0xa bank_mask:0xf
	s_nop 1
	v_add_f32_dpp v173, v173, v173 row_bcast:31 row_mask:0xc bank_mask:0xf
	s_nop 1
	v_readlane_b32 s8, v173, 63
	s_nop 3
	v_mov_b32_e32 v158, s8
	v_fma_f32 v158, v158, v171, v172
	v_rsq_f32_e32 v158, v158
	s_nop 1
	v_lshlrev_b32_e32 v146, 16, v32
	v_and_b32_e32 v147, 0xffff0000, v32
	v_pk_mul_f32 v[146:147], v[146:147], v[158:159] op_sel_hi:[1,0]
	v_pk_fma_f32 v[178:179], v[48:49], v[146:147], v[178:179]
	v_lshlrev_b32_e32 v148, 16, v33
	v_and_b32_e32 v149, 0xffff0000, v33
	v_pk_mul_f32 v[148:149], v[148:149], v[158:159] op_sel_hi:[1,0]
	v_pk_fma_f32 v[180:181], v[50:51], v[148:149], v[180:181]
	v_lshlrev_b32_e32 v150, 16, v34
	v_and_b32_e32 v151, 0xffff0000, v34
	v_pk_mul_f32 v[150:151], v[150:151], v[158:159] op_sel_hi:[1,0]
	v_pk_fma_f32 v[182:183], v[52:53], v[150:151], v[182:183]
	v_lshlrev_b32_e32 v152, 16, v35
	v_and_b32_e32 v153, 0xffff0000, v35
	v_pk_mul_f32 v[152:153], v[152:153], v[158:159] op_sel_hi:[1,0]
	v_pk_fma_f32 v[184:185], v[54:55], v[152:153], v[184:185]
	v_lshlrev_b32_e32 v146, 16, v36
	v_and_b32_e32 v147, 0xffff0000, v36
	v_pk_mul_f32 v[146:147], v[146:147], v[158:159] op_sel_hi:[1,0]
	v_pk_fma_f32 v[192:193], v[56:57], v[146:147], v[192:193]
	v_lshlrev_b32_e32 v148, 16, v37
	v_and_b32_e32 v149, 0xffff0000, v37
	v_pk_mul_f32 v[148:149], v[148:149], v[158:159] op_sel_hi:[1,0]
	v_pk_fma_f32 v[194:195], v[58:59], v[148:149], v[194:195]
	v_lshlrev_b32_e32 v150, 16, v38
	v_and_b32_e32 v151, 0xffff0000, v38
	v_pk_mul_f32 v[150:151], v[150:151], v[158:159] op_sel_hi:[1,0]
	v_pk_fma_f32 v[198:199], v[60:61], v[150:151], v[198:199]
	v_lshlrev_b32_e32 v152, 16, v39
	v_and_b32_e32 v153, 0xffff0000, v39
	v_pk_mul_f32 v[152:153], v[152:153], v[158:159] op_sel_hi:[1,0]
	v_pk_fma_f32 v[200:201], v[62:63], v[152:153], v[200:201]
	v_lshlrev_b32_e32 v146, 16, v40
	v_and_b32_e32 v147, 0xffff0000, v40
	v_pk_mul_f32 v[146:147], v[146:147], v[158:159] op_sel_hi:[1,0]
	v_pk_fma_f32 v[202:203], v[64:65], v[146:147], v[202:203]
	v_lshlrev_b32_e32 v148, 16, v41
	v_and_b32_e32 v149, 0xffff0000, v41
	v_pk_mul_f32 v[148:149], v[148:149], v[158:159] op_sel_hi:[1,0]
	v_pk_fma_f32 v[204:205], v[66:67], v[148:149], v[204:205]
	v_lshlrev_b32_e32 v150, 16, v42
	v_and_b32_e32 v151, 0xffff0000, v42
	v_pk_mul_f32 v[150:151], v[150:151], v[158:159] op_sel_hi:[1,0]
	v_pk_fma_f32 v[206:207], v[68:69], v[150:151], v[206:207]
	v_lshlrev_b32_e32 v152, 16, v43
	v_and_b32_e32 v153, 0xffff0000, v43
	v_pk_mul_f32 v[152:153], v[152:153], v[158:159] op_sel_hi:[1,0]
	v_pk_fma_f32 v[208:209], v[70:71], v[152:153], v[208:209]
	v_lshlrev_b32_e32 v146, 16, v44
	v_and_b32_e32 v147, 0xffff0000, v44
	v_pk_mul_f32 v[146:147], v[146:147], v[158:159] op_sel_hi:[1,0]
	v_pk_fma_f32 v[210:211], v[72:73], v[146:147], v[210:211]
	v_lshlrev_b32_e32 v148, 16, v45
	v_and_b32_e32 v149, 0xffff0000, v45
	v_pk_mul_f32 v[148:149], v[148:149], v[158:159] op_sel_hi:[1,0]
	v_pk_fma_f32 v[212:213], v[74:75], v[148:149], v[212:213]
	v_lshlrev_b32_e32 v150, 16, v46
	v_and_b32_e32 v151, 0xffff0000, v46
	v_pk_mul_f32 v[150:151], v[150:151], v[158:159] op_sel_hi:[1,0]
	v_pk_fma_f32 v[214:215], v[76:77], v[150:151], v[214:215]
	v_lshlrev_b32_e32 v152, 16, v47
	v_and_b32_e32 v153, 0xffff0000, v47
	v_pk_mul_f32 v[152:153], v[152:153], v[158:159] op_sel_hi:[1,0]
	v_pk_fma_f32 v[216:217], v[78:79], v[152:153], v[216:217]
	s_nop 0
	global_store_dwordx4 v80, v[178:181], s[10:11] offset:0 nt
	global_store_dwordx4 v80, v[182:185], s[10:11] offset:1024 nt
	global_store_dwordx4 v80, v[192:195], s[10:11] offset:2048 nt
	global_store_dwordx4 v80, v[198:201], s[10:11] offset:3072 nt
	global_store_dwordx4 v168, v[202:205], s[10:11] offset:0 nt
	global_store_dwordx4 v168, v[206:209], s[10:11] offset:1024 nt
	global_store_dwordx4 v168, v[210:213], s[10:11] offset:2048 nt
	global_store_dwordx4 v168, v[214:217], s[10:11] offset:3072 nt
	v_pk_mul_f32 v[154:155], v[178:179], v[178:179]
	v_pk_mul_f32 v[156:157], v[180:181], v[180:181]
	v_pk_fma_f32 v[154:155], v[182:183], v[182:183], v[154:155]
	v_pk_fma_f32 v[156:157], v[184:185], v[184:185], v[156:157]
	v_pk_fma_f32 v[154:155], v[192:193], v[192:193], v[154:155]
	v_pk_fma_f32 v[156:157], v[194:195], v[194:195], v[156:157]
	v_pk_fma_f32 v[154:155], v[198:199], v[198:199], v[154:155]
	v_pk_fma_f32 v[156:157], v[200:201], v[200:201], v[156:157]
	v_pk_fma_f32 v[154:155], v[202:203], v[202:203], v[154:155]
	v_pk_fma_f32 v[156:157], v[204:205], v[204:205], v[156:157]
	v_pk_fma_f32 v[154:155], v[206:207], v[206:207], v[154:155]
	v_pk_fma_f32 v[156:157], v[208:209], v[208:209], v[156:157]
	v_pk_fma_f32 v[154:155], v[210:211], v[210:211], v[154:155]
	v_pk_fma_f32 v[156:157], v[212:213], v[212:213], v[156:157]
	v_pk_fma_f32 v[154:155], v[214:215], v[214:215], v[154:155]
	v_pk_fma_f32 v[156:157], v[216:217], v[216:217], v[156:157]
	v_pk_add_f32 v[154:155], v[154:155], v[156:157]
	s_nop 0
	v_add_f32_e32 v173, v154, v155
	s_nop 1
	v_add_f32_dpp v173, v173, v173 quad_perm:[1,0,3,2] row_mask:0xf bank_mask:0xf
	s_nop 1
	v_add_f32_dpp v173, v173, v173 quad_perm:[2,3,0,1] row_mask:0xf bank_mask:0xf
	s_nop 1
	v_add_f32_dpp v173, v173, v173 row_half_mirror row_mask:0xf bank_mask:0xf
	s_nop 1
	v_add_f32_dpp v173, v173, v173 row_mirror row_mask:0xf bank_mask:0xf
	s_nop 1
	v_add_f32_dpp v173, v173, v173 row_bcast:15 row_mask:0xa bank_mask:0xf
	s_nop 1
	v_add_f32_dpp v173, v173, v173 row_bcast:31 row_mask:0xc bank_mask:0xf
	s_nop 1
	v_readlane_b32 s8, v173, 63
	s_nop 3
	v_mov_b32_e32 v158, s8
	v_fma_f32 v158, v158, v171, v172
	v_rsq_f32_e32 v158, v158
	s_nop 1
	v_pk_mul_f32 v[146:147], v[178:179], v[158:159] op_sel_hi:[1,0]
	v_pk_fma_f32 v[146:147], v[146:147], v[82:83], v[114:115]
	v_cvt_pk_bf16_f32 v160, v146, v147
	v_pk_mul_f32 v[148:149], v[180:181], v[158:159] op_sel_hi:[1,0]
	v_pk_fma_f32 v[148:149], v[148:149], v[84:85], v[116:117]
	v_cvt_pk_bf16_f32 v161, v148, v149
	global_store_dwordx2 v169, v[160:161], s[14:15] offset:0
	v_pk_mul_f32 v[150:151], v[182:183], v[158:159] op_sel_hi:[1,0]
	v_pk_fma_f32 v[150:151], v[150:151], v[86:87], v[118:119]
	v_cvt_pk_bf16_f32 v162, v150, v151
	v_pk_mul_f32 v[152:153], v[184:185], v[158:159] op_sel_hi:[1,0]
	v_pk_fma_f32 v[152:153], v[152:153], v[88:89], v[120:121]
	v_cvt_pk_bf16_f32 v163, v152, v153
	global_store_dwordx2 v169, v[162:163], s[14:15] offset:512
	v_pk_mul_f32 v[146:147], v[192:193], v[158:159] op_sel_hi:[1,0]
	v_pk_fma_f32 v[146:147], v[146:147], v[90:91], v[122:123]
	v_cvt_pk_bf16_f32 v164, v146, v147
	v_pk_mul_f32 v[148:149], v[194:195], v[158:159] op_sel_hi:[1,0]
	v_pk_fma_f32 v[148:149], v[148:149], v[92:93], v[124:125]
	v_cvt_pk_bf16_f32 v165, v148, v149
	global_store_dwordx2 v169, v[164:165], s[14:15] offset:1024
	v_pk_mul_f32 v[150:151], v[198:199], v[158:159] op_sel_hi:[1,0]
	v_pk_fma_f32 v[150:151], v[150:151], v[94:95], v[126:127]
	v_cvt_pk_bf16_f32 v166, v150, v151
	v_pk_mul_f32 v[152:153], v[200:201], v[158:159] op_sel_hi:[1,0]
	v_pk_fma_f32 v[152:153], v[152:153], v[96:97], v[128:129]
	v_cvt_pk_bf16_f32 v167, v152, v153
	global_store_dwordx2 v169, v[166:167], s[14:15] offset:1536
	v_pk_mul_f32 v[146:147], v[202:203], v[158:159] op_sel_hi:[1,0]
	v_pk_fma_f32 v[146:147], v[146:147], v[98:99], v[130:131]
	v_cvt_pk_bf16_f32 v160, v146, v147
	v_pk_mul_f32 v[148:149], v[204:205], v[158:159] op_sel_hi:[1,0]
	v_pk_fma_f32 v[148:149], v[148:149], v[100:101], v[132:133]
	v_cvt_pk_bf16_f32 v161, v148, v149
	global_store_dwordx2 v169, v[160:161], s[14:15] offset:2048
	v_pk_mul_f32 v[150:151], v[206:207], v[158:159] op_sel_hi:[1,0]
	v_pk_fma_f32 v[150:151], v[150:151], v[102:103], v[134:135]
	v_cvt_pk_bf16_f32 v162, v150, v151
	v_pk_mul_f32 v[152:153], v[208:209], v[158:159] op_sel_hi:[1,0]
	v_pk_fma_f32 v[152:153], v[152:153], v[104:105], v[136:137]
	v_cvt_pk_bf16_f32 v163, v152, v153
	global_store_dwordx2 v169, v[162:163], s[14:15] offset:2560
	v_pk_mul_f32 v[146:147], v[210:211], v[158:159] op_sel_hi:[1,0]
	v_pk_fma_f32 v[146:147], v[146:147], v[106:107], v[138:139]
	v_cvt_pk_bf16_f32 v164, v146, v147
	v_pk_mul_f32 v[148:149], v[212:213], v[158:159] op_sel_hi:[1,0]
	v_pk_fma_f32 v[148:149], v[148:149], v[108:109], v[140:141]
	v_cvt_pk_bf16_f32 v165, v148, v149
	global_store_dwordx2 v169, v[164:165], s[14:15] offset:3072
	v_pk_mul_f32 v[150:151], v[214:215], v[158:159] op_sel_hi:[1,0]
	v_pk_fma_f32 v[150:151], v[150:151], v[110:111], v[142:143]
	v_cvt_pk_bf16_f32 v166, v150, v151
	v_pk_mul_f32 v[152:153], v[216:217], v[158:159] op_sel_hi:[1,0]
	v_pk_fma_f32 v[152:153], v[152:153], v[112:113], v[144:145]
	v_cvt_pk_bf16_f32 v167, v152, v153
	global_store_dwordx2 v169, v[166:167], s[14:15] offset:3584
	s_add_u32 s0, s0, 2
	s_cmp_lt_u32 s0, 16
	s_cbranch_scc1 .Lrm3_loop
	s_branch .Lrm3_done
.Lrm3_ctxrow:
.Lrm3_done:
	s_branch .LBB0_1925
.Lrm3_orig:
	v_lshlrev_b32_e32 v5, 2, v5
	v_and_b32_e32 v6, 0xfc, v5
	s_mov_b64 s[6:7], 0x2000
	v_or_b32_e32 v10, 0x100, v6
	v_or_b32_e32 v14, 0x200, v6
	v_or_b32_e32 v18, 0x300, v6
	v_or_b32_e32 v22, 0x400, v6
	v_or_b32_e32 v26, 0x500, v6
	v_or_b32_e32 v30, 0x600, v6
	v_or_b32_e32 v34, 0x700, v6
	s_waitcnt vmcnt(0)
	v_lshl_add_u64 v[0:1], v[0:1], 0, s[6:7]
	v_lshlrev_b32_e32 v8, 2, v6
	v_mov_b32_e32 v9, v81
	v_lshlrev_b32_e32 v12, 2, v10
	v_mov_b32_e32 v13, v81
	v_lshlrev_b32_e32 v16, 2, v14
	v_mov_b32_e32 v17, v81
	v_lshlrev_b32_e32 v20, 2, v18
	v_mov_b32_e32 v21, v81
	v_lshlrev_b32_e32 v24, 2, v22
	v_mov_b32_e32 v25, v81
	v_lshlrev_b32_e32 v28, 2, v26
	v_mov_b32_e32 v29, v81
	v_lshlrev_b32_e32 v32, 2, v30
	v_mov_b32_e32 v33, v81
	v_lshlrev_b32_e32 v36, 2, v34
	v_mov_b32_e32 v37, v81
	v_lshl_add_u64 v[84:85], v[0:1], 0, v[8:9]
	v_lshl_add_u64 v[86:87], v[0:1], 0, v[12:13]
	v_lshl_add_u64 v[88:89], v[0:1], 0, v[16:17]
	v_lshl_add_u64 v[90:91], v[0:1], 0, v[20:21]
	v_lshl_add_u64 v[92:93], v[0:1], 0, v[24:25]
	v_lshl_add_u64 v[94:95], v[0:1], 0, v[28:29]
	v_lshl_add_u64 v[96:97], v[0:1], 0, v[32:33]
	v_lshl_add_u64 v[98:99], v[0:1], 0, v[36:37]
	v_mbcnt_hi_u32_b32 v0, -1, v190
	v_lshl_add_u64 v[2:3], v[2:3], 0, s[6:7]
	v_and_b32_e32 v1, 64, v0
	v_lshl_add_u64 v[100:101], v[2:3], 0, v[8:9]
	v_lshl_add_u64 v[102:103], v[2:3], 0, v[12:13]
	v_lshl_add_u64 v[104:105], v[2:3], 0, v[16:17]
	v_lshl_add_u64 v[106:107], v[2:3], 0, v[20:21]
	v_lshl_add_u64 v[108:109], v[2:3], 0, v[24:25]
	v_lshl_add_u64 v[110:111], v[2:3], 0, v[28:29]
	v_lshl_add_u64 v[112:113], v[2:3], 0, v[32:33]
	v_lshl_add_u64 v[114:115], v[2:3], 0, v[36:37]
	v_add_u32_e32 v1, 64, v1
	v_xor_b32_e32 v2, 32, v0
	v_cmp_lt_i32_e32 vcc, v2, v1
	s_add_u32 s8, s52, 0x3d840000
	s_addc_u32 s9, s53, 0
	v_cndmask_b32_e32 v2, v0, v2, vcc
	v_lshlrev_b32_e32 v191, 2, v2
	v_xor_b32_e32 v2, 16, v0
	v_cmp_lt_i32_e32 vcc, v2, v1
	v_lshlrev_b32_e32 v80, 1, v6
	s_cmp_lg_u64 s[58:59], 0
	v_cndmask_b32_e32 v2, v0, v2, vcc
	v_lshlrev_b32_e32 v192, 2, v2
	v_xor_b32_e32 v2, 8, v0
	v_cmp_lt_i32_e32 vcc, v2, v1
	v_lshl_add_u64 v[82:83], s[60:61], 0, v[80:81]
	s_mov_b64 s[10:11], 0
	v_cndmask_b32_e32 v2, v0, v2, vcc
	v_lshlrev_b32_e32 v193, 2, v2
	v_xor_b32_e32 v2, 4, v0
	v_cmp_lt_i32_e32 vcc, v2, v1
	s_cselect_b64 s[12:13], -1, 0
	v_lshl_add_u64 v[116:117], s[58:59], 0, v[8:9]
	v_cndmask_b32_e32 v2, v0, v2, vcc
	v_lshlrev_b32_e32 v194, 2, v2
	v_xor_b32_e32 v2, 2, v0
	v_cmp_lt_i32_e32 vcc, v2, v1
	v_lshl_add_u64 v[118:119], s[62:63], 0, v[80:81]
	s_lshl_b32 s4, s54, 4
	v_cndmask_b32_e32 v2, v0, v2, vcc
	v_lshlrev_b32_e32 v195, 2, v2
	v_xor_b32_e32 v2, 1, v0
	v_cmp_lt_i32_e32 vcc, v2, v1
	s_movk_i32 s5, 0x3000
	s_mov_b64 s[14:15], 0x1000
	v_cndmask_b32_e32 v0, v0, v2, vcc
	v_lshlrev_b32_e32 v196, 2, v0
	v_lshlrev_b32_e32 v0, 1, v4
	v_lshl_add_u32 v120, s0, 4, v0
	s_mov_b64 s[16:17], 0x1400
	s_mov_b64 s[18:19], 0x1800
	s_mov_b64 s[20:21], 0x1c00
	s_mov_b64 s[22:23], 0x2400
	s_mov_b64 s[24:25], 0x2800
	s_mov_b64 s[26:27], 0x2c00
	s_mov_b64 s[28:29], 0x3000
	s_mov_b64 s[30:31], 0x3400
	s_mov_b64 s[34:35], 0x3800
	s_mov_b64 s[36:37], 0x3c00
	s_mov_b32 s38, 0x3a000000
	s_mov_b32 s39, 0x800000
	v_lshlrev_b32_e32 v80, 2, v6
	v_lshlrev_b32_e32 v122, 2, v22
	v_lshlrev_b32_e32 v124, 2, v26
	v_lshlrev_b32_e32 v126, 2, v30
	v_lshlrev_b32_e32 v128, 2, v34
	s_mov_b64 s[40:41], 0x6000
	s_mov_b64 s[42:43], 0x8000
	v_lshlrev_b32_e32 v130, 2, v10
	v_lshlrev_b32_e32 v132, 2, v14
	v_lshlrev_b32_e32 v134, 2, v18
	s_movk_i32 s44, 0x3fff
	v_mov_b32_e32 v136, 0x358637bd
	s_branch .LBB0_1923

.LBB0_2141:
	s_or_b64 exec, exec, s[0:1]
	v_readlane_b32 s0, v252, 9
	v_mov_b32_e32 v5, 0
	v_readlane_b32 s1, v252, 10
	s_waitcnt lgkmcnt(0)
	s_barrier
	s_nop 2
	global_load_dwordx2 v[0:1], v5, s[0:1]
	s_movk_i32 s0, 0x4000
	v_ashrrev_i32_e32 v2, 6, v189
	v_lshl_add_u32 v37, s33, 3, v2
	v_cmp_gt_i32_e32 vcc, s0, v37
	s_and_saveexec_b64 s[0:1], vcc
	s_cbranch_execz .LBB0_2146
	s_cmpk_lg_i32 s94, 0x800
	s_cbranch_scc1 .Lrm4_orig
	s_waitcnt vmcnt(0) lgkmcnt(0)
	v_and_b32_e32 v142, 63, v189
	v_lshrrev_b32_e32 v145, 6, v189
	v_lshlrev_b32_e32 v4, 4, v142
	v_lshlrev_b32_e32 v141, 3, v142
	v_readfirstlane_b32 s3, v145
	v_add_u32_e32 v140, 0x1000, v4
	v_mov_b32_e32 v142, 0
	v_mov_b32_e32 v143, 0x3a000000
	v_mov_b32_e32 v144, 0x358637bd
	s_lshl_b32 s6, s33, 3
	s_add_u32 s3, s3, s6
	s_add_u32 s6, s52, 0x3e500000
	s_addc_u32 s7, s53, 0
	global_load_dwordx2 v[146:147], v142, s[6:7] offset:72
	s_waitcnt vmcnt(0)
	v_mov_b32_e32 v145, 0x2000
	v_add_co_u32_e32 v146, vcc, v146, v145
	s_nop 1
	v_addc_co_u32_e32 v147, vcc, 0, v147, vcc
	s_mov_b32 s0, 0
	s_lshr_b32 s2, s3, 9
.Lrm4_coef:
	v_readfirstlane_b32 s6, v146
	v_readfirstlane_b32 s7, v147
	s_nop 4
	global_load_dwordx4 v[0:3], v4, s[6:7] offset:0
	global_load_dwordx4 v[6:9], v4, s[6:7] offset:1024
	global_load_dwordx4 v[10:13], v4, s[6:7] offset:2048
	global_load_dwordx4 v[14:17], v4, s[6:7] offset:3072
	global_load_dwordx4 v[18:21], v140, s[6:7] offset:0
	global_load_dwordx4 v[22:25], v140, s[6:7] offset:1024
	global_load_dwordx4 v[26:29], v140, s[6:7] offset:2048
	global_load_dwordx4 v[30:33], v140, s[6:7] offset:3072
	s_mul_i32 s6, s2, 0xc000
	s_add_u32 s6, s6, 0x3d846000
	s_add_u32 s6, s52, s6
	s_addc_u32 s7, s53, 0
	global_load_dwordx4 v[82:85], v4, s[6:7] offset:0
	global_load_dwordx4 v[86:89], v4, s[6:7] offset:1024
	global_load_dwordx4 v[90:93], v4, s[6:7] offset:2048
	global_load_dwordx4 v[94:97], v4, s[6:7] offset:3072
	global_load_dwordx4 v[98:101], v140, s[6:7] offset:0
	global_load_dwordx4 v[102:105], v140, s[6:7] offset:1024
	global_load_dwordx4 v[106:109], v140, s[6:7] offset:2048
	global_load_dwordx4 v[110:113], v140, s[6:7] offset:3072
	s_waitcnt vmcnt(0)
	v_pk_mul_f32 v[50:51], v[82:83], v[0:1]
	v_pk_mul_f32 v[52:53], v[84:85], v[2:3]
	v_pk_mul_f32 v[54:55], v[86:87], v[6:7]
	v_pk_mul_f32 v[56:57], v[88:89], v[8:9]
	v_pk_mul_f32 v[58:59], v[90:91], v[10:11]
	v_pk_mul_f32 v[60:61], v[92:93], v[12:13]
	v_pk_mul_f32 v[62:63], v[94:95], v[14:15]
	v_pk_mul_f32 v[64:65], v[96:97], v[16:17]
	v_pk_mul_f32 v[66:67], v[98:99], v[18:19]
	v_pk_mul_f32 v[68:69], v[100:101], v[20:21]
	v_pk_mul_f32 v[70:71], v[102:103], v[22:23]
	v_pk_mul_f32 v[72:73], v[104:105], v[24:25]
	v_pk_mul_f32 v[74:75], v[106:107], v[26:27]
	v_pk_mul_f32 v[76:77], v[108:109], v[28:29]
	v_pk_mul_f32 v[78:79], v[110:111], v[30:31]
	v_pk_mul_f32 v[80:81], v[112:113], v[32:33]
	s_cmp_lt_u32 s0, 16
	s_cbranch_scc0 .Lrm4_ctxrow
	s_lshr_b32 s1, s3, 9
	s_lshl_b32 s1, s1, 13
	s_and_b32 s6, s3, 0x1ff
	s_add_u32 s1, s1, s6
	s_add_u32 s6, s0, 0
	s_lshl_b32 s6, s6, 9
	s_add_u32 s1, s1, s6
	s_lshl_b32 s6, s1, 13
	s_add_u32 s4, s58, s6
	s_addc_u32 s5, s59, 0
	global_load_dwordx4 v[0:3], v4, s[4:5] offset:0 nt
	global_load_dwordx4 v[6:9], v4, s[4:5] offset:1024 nt
	global_load_dwordx4 v[10:13], v4, s[4:5] offset:2048 nt
	global_load_dwordx4 v[14:17], v4, s[4:5] offset:3072 nt
	global_load_dwordx4 v[18:21], v140, s[4:5] offset:0 nt
	global_load_dwordx4 v[22:25], v140, s[4:5] offset:1024 nt
	global_load_dwordx4 v[26:29], v140, s[4:5] offset:2048 nt
	global_load_dwordx4 v[30:33], v140, s[4:5] offset:3072 nt
.Lrm4_loop:
	s_lshr_b32 s1, s3, 9
	s_lshl_b32 s1, s1, 13
	s_and_b32 s6, s3, 0x1ff
	s_add_u32 s1, s1, s6
	s_add_u32 s6, s0, 0
	s_lshl_b32 s6, s6, 9
	s_add_u32 s1, s1, s6
	s_lshl_b32 s6, s1, 13
	s_add_u32 s8, s58, s6
	s_addc_u32 s9, s59, 0
	s_lshl_b32 s6, s1, 12
	s_add_u32 s7, s6, 0x34c00000
	s_add_u32 s10, s52, s7
	s_addc_u32 s11, s53, 0
	global_load_dwordx2 v[34:35], v141, s[10:11] offset:0 nt
	global_load_dwordx2 v[36:37], v141, s[10:11] offset:512 nt
	global_load_dwordx2 v[38:39], v141, s[10:11] offset:1024 nt
	global_load_dwordx2 v[40:41], v141, s[10:11] offset:1536 nt
	global_load_dwordx2 v[42:43], v141, s[10:11] offset:2048 nt
	global_load_dwordx2 v[44:45], v141, s[10:11] offset:2560 nt
	global_load_dwordx2 v[46:47], v141, s[10:11] offset:3072 nt
	global_load_dwordx2 v[48:49], v141, s[10:11] offset:3584 nt
	s_lshr_b32 s1, s3, 9
	s_lshl_b32 s1, s1, 13
	s_and_b32 s6, s3, 0x1ff
	s_add_u32 s1, s1, s6
	s_add_u32 s6, s0, 1
	s_lshl_b32 s6, s6, 9
	s_add_u32 s1, s1, s6
	s_lshl_b32 s6, s1, 13
	s_add_u32 s4, s58, s6
	s_addc_u32 s5, s59, 0
	global_load_dwordx4 v[148:151], v4, s[4:5] offset:0 nt
	global_load_dwordx4 v[152:155], v4, s[4:5] offset:1024 nt
	global_load_dwordx4 v[156:159], v4, s[4:5] offset:2048 nt
	global_load_dwordx4 v[160:163], v4, s[4:5] offset:3072 nt
	global_load_dwordx4 v[174:177], v140, s[4:5] offset:0 nt
	global_load_dwordx4 v[178:181], v140, s[4:5] offset:1024 nt
	global_load_dwordx4 v[182:185], v140, s[4:5] offset:2048 nt
	global_load_dwordx4 v[192:195], v140, s[4:5] offset:3072 nt
	s_waitcnt vmcnt(8)
	v_lshlrev_b32_e32 v114, 16, v34
	v_and_b32_e32 v115, 0xffff0000, v34
	v_pk_mul_f32 v[126:127], v[114:115], v[114:115]
	v_lshlrev_b32_e32 v116, 16, v35
	v_and_b32_e32 v117, 0xffff0000, v35
	v_pk_mul_f32 v[128:129], v[116:117], v[116:117]
	v_lshlrev_b32_e32 v118, 16, v36
	v_and_b32_e32 v119, 0xffff0000, v36
	v_pk_fma_f32 v[126:127], v[118:119], v[118:119], v[126:127]
	v_lshlrev_b32_e32 v120, 16, v37
	v_and_b32_e32 v121, 0xffff0000, v37
	v_pk_fma_f32 v[128:129], v[120:121], v[120:121], v[128:129]
	v_lshlrev_b32_e32 v114, 16, v38
	v_and_b32_e32 v115, 0xffff0000, v38
	v_pk_fma_f32 v[126:127], v[114:115], v[114:115], v[126:127]
	v_lshlrev_b32_e32 v116, 16, v39
	v_and_b32_e32 v117, 0xffff0000, v39
	v_pk_fma_f32 v[128:129], v[116:117], v[116:117], v[128:129]
	v_lshlrev_b32_e32 v118, 16, v40
	v_and_b32_e32 v119, 0xffff0000, v40
	v_pk_fma_f32 v[126:127], v[118:119], v[118:119], v[126:127]
	v_lshlrev_b32_e32 v120, 16, v41
	v_and_b32_e32 v121, 0xffff0000, v41
	v_pk_fma_f32 v[128:129], v[120:121], v[120:121], v[128:129]
	v_lshlrev_b32_e32 v114, 16, v42
	v_and_b32_e32 v115, 0xffff0000, v42
	v_pk_fma_f32 v[126:127], v[114:115], v[114:115], v[126:127]
	v_lshlrev_b32_e32 v116, 16, v43
	v_and_b32_e32 v117, 0xffff0000, v43
	v_pk_fma_f32 v[128:129], v[116:117], v[116:117], v[128:129]
	v_lshlrev_b32_e32 v118, 16, v44
	v_and_b32_e32 v119, 0xffff0000, v44
	v_pk_fma_f32 v[126:127], v[118:119], v[118:119], v[126:127]
	v_lshlrev_b32_e32 v120, 16, v45
	v_and_b32_e32 v121, 0xffff0000, v45
	v_pk_fma_f32 v[128:129], v[120:121], v[120:121], v[128:129]
	v_lshlrev_b32_e32 v114, 16, v46
	v_and_b32_e32 v115, 0xffff0000, v46
	v_pk_fma_f32 v[126:127], v[114:115], v[114:115], v[126:127]
	v_lshlrev_b32_e32 v116, 16, v47
	v_and_b32_e32 v117, 0xffff0000, v47
	v_pk_fma_f32 v[128:129], v[116:117], v[116:117], v[128:129]
	v_lshlrev_b32_e32 v118, 16, v48
	v_and_b32_e32 v119, 0xffff0000, v48
	v_pk_fma_f32 v[126:127], v[118:119], v[118:119], v[126:127]
	v_lshlrev_b32_e32 v120, 16, v49
	v_and_b32_e32 v121, 0xffff0000, v49
	v_pk_fma_f32 v[128:129], v[120:121], v[120:121], v[128:129]
	v_pk_add_f32 v[126:127], v[126:127], v[128:129]
	s_nop 0
	v_add_f32_e32 v145, v126, v127
	s_nop 1
	v_add_f32_dpp v145, v145, v145 quad_perm:[1,0,3,2] row_mask:0xf bank_mask:0xf
	s_nop 1
	v_add_f32_dpp v145, v145, v145 quad_perm:[2,3,0,1] row_mask:0xf bank_mask:0xf
	s_nop 1
	v_add_f32_dpp v145, v145, v145 row_half_mirror row_mask:0xf bank_mask:0xf
	s_nop 1
	v_add_f32_dpp v145, v145, v145 row_mirror row_mask:0xf bank_mask:0xf
	s_nop 1
	v_add_f32_dpp v145, v145, v145 row_bcast:15 row_mask:0xa bank_mask:0xf
	s_nop 1
	v_add_f32_dpp v145, v145, v145 row_bcast:31 row_mask:0xc bank_mask:0xf
	s_nop 1
	v_readlane_b32 s6, v145, 63
	s_nop 3
	v_mov_b32_e32 v130, s6
	v_fma_f32 v130, v130, v143, v144
	v_rsq_f32_e32 v130, v130
	s_nop 1
	v_lshlrev_b32_e32 v114, 16, v34
	v_and_b32_e32 v115, 0xffff0000, v34
	v_pk_mul_f32 v[114:115], v[114:115], v[130:131] op_sel_hi:[1,0]
	v_pk_fma_f32 v[0:1], v[50:51], v[114:115], v[0:1]
	v_lshlrev_b32_e32 v116, 16, v35
	v_and_b32_e32 v117, 0xffff0000, v35
	v_pk_mul_f32 v[116:117], v[116:117], v[130:131] op_sel_hi:[1,0]
	v_pk_fma_f32 v[2:3], v[52:53], v[116:117], v[2:3]
	v_lshlrev_b32_e32 v118, 16, v36
	v_and_b32_e32 v119, 0xffff0000, v36
	v_pk_mul_f32 v[118:119], v[118:119], v[130:131] op_sel_hi:[1,0]
	v_pk_fma_f32 v[6:7], v[54:55], v[118:119], v[6:7]
	v_lshlrev_b32_e32 v120, 16, v37
	v_and_b32_e32 v121, 0xffff0000, v37
	v_pk_mul_f32 v[120:121], v[120:121], v[130:131] op_sel_hi:[1,0]
	v_pk_fma_f32 v[8:9], v[56:57], v[120:121], v[8:9]
	v_lshlrev_b32_e32 v114, 16, v38
	v_and_b32_e32 v115, 0xffff0000, v38
	v_pk_mul_f32 v[114:115], v[114:115], v[130:131] op_sel_hi:[1,0]
	v_pk_fma_f32 v[10:11], v[58:59], v[114:115], v[10:11]
	v_lshlrev_b32_e32 v116, 16, v39
	v_and_b32_e32 v117, 0xffff0000, v39
	v_pk_mul_f32 v[116:117], v[116:117], v[130:131] op_sel_hi:[1,0]
	v_pk_fma_f32 v[12:13], v[60:61], v[116:117], v[12:13]
	v_lshlrev_b32_e32 v118, 16, v40
	v_and_b32_e32 v119, 0xffff0000, v40
	v_pk_mul_f32 v[118:119], v[118:119], v[130:131] op_sel_hi:[1,0]
	v_pk_fma_f32 v[14:15], v[62:63], v[118:119], v[14:15]
	v_lshlrev_b32_e32 v120, 16, v41
	v_and_b32_e32 v121, 0xffff0000, v41
	v_pk_mul_f32 v[120:121], v[120:121], v[130:131] op_sel_hi:[1,0]
	v_pk_fma_f32 v[16:17], v[64:65], v[120:121], v[16:17]
	v_lshlrev_b32_e32 v114, 16, v42
	v_and_b32_e32 v115, 0xffff0000, v42
	v_pk_mul_f32 v[114:115], v[114:115], v[130:131] op_sel_hi:[1,0]
	v_pk_fma_f32 v[18:19], v[66:67], v[114:115], v[18:19]
	v_lshlrev_b32_e32 v116, 16, v43
	v_and_b32_e32 v117, 0xffff0000, v43
	v_pk_mul_f32 v[116:117], v[116:117], v[130:131] op_sel_hi:[1,0]
	v_pk_fma_f32 v[20:21], v[68:69], v[116:117], v[20:21]
	v_lshlrev_b32_e32 v118, 16, v44
	v_and_b32_e32 v119, 0xffff0000, v44
	v_pk_mul_f32 v[118:119], v[118:119], v[130:131] op_sel_hi:[1,0]
	v_pk_fma_f32 v[22:23], v[70:71], v[118:119], v[22:23]
	v_lshlrev_b32_e32 v120, 16, v45
	v_and_b32_e32 v121, 0xffff0000, v45
	v_pk_mul_f32 v[120:121], v[120:121], v[130:131] op_sel_hi:[1,0]
	v_pk_fma_f32 v[24:25], v[72:73], v[120:121], v[24:25]
	v_lshlrev_b32_e32 v114, 16, v46
	v_and_b32_e32 v115, 0xffff0000, v46
	v_pk_mul_f32 v[114:115], v[114:115], v[130:131] op_sel_hi:[1,0]
	v_pk_fma_f32 v[26:27], v[74:75], v[114:115], v[26:27]
	v_lshlrev_b32_e32 v116, 16, v47
	v_and_b32_e32 v117, 0xffff0000, v47
	v_pk_mul_f32 v[116:117], v[116:117], v[130:131] op_sel_hi:[1,0]
	v_pk_fma_f32 v[28:29], v[76:77], v[116:117], v[28:29]
	v_lshlrev_b32_e32 v118, 16, v48
	v_and_b32_e32 v119, 0xffff0000, v48
	v_pk_mul_f32 v[118:119], v[118:119], v[130:131] op_sel_hi:[1,0]
	v_pk_fma_f32 v[30:31], v[78:79], v[118:119], v[30:31]
	v_lshlrev_b32_e32 v120, 16, v49
	v_and_b32_e32 v121, 0xffff0000, v49
	v_pk_mul_f32 v[120:121], v[120:121], v[130:131] op_sel_hi:[1,0]
	v_pk_fma_f32 v[32:33], v[80:81], v[120:121], v[32:33]
	s_nop 0
	global_store_dwordx4 v4, v[0:3], s[8:9] offset:0 nt
	global_store_dwordx4 v4, v[6:9], s[8:9] offset:1024 nt
	global_store_dwordx4 v4, v[10:13], s[8:9] offset:2048 nt
	global_store_dwordx4 v4, v[14:17], s[8:9] offset:3072 nt
	global_store_dwordx4 v140, v[18:21], s[8:9] offset:0 nt
	global_store_dwordx4 v140, v[22:25], s[8:9] offset:1024 nt
	global_store_dwordx4 v140, v[26:29], s[8:9] offset:2048 nt
	global_store_dwordx4 v140, v[30:33], s[8:9] offset:3072 nt
	s_lshr_b32 s1, s3, 9
	s_lshl_b32 s1, s1, 13
	s_and_b32 s6, s3, 0x1ff
	s_add_u32 s1, s1, s6
	s_add_u32 s6, s0, 1
	s_lshl_b32 s6, s6, 9
	s_add_u32 s1, s1, s6
	s_lshl_b32 s6, s1, 13
	s_add_u32 s8, s58, s6
	s_addc_u32 s9, s59, 0
	s_lshl_b32 s6, s1, 12
	s_add_u32 s7, s6, 0x34c00000
	s_add_u32 s10, s52, s7
	s_addc_u32 s11, s53, 0
	global_load_dwordx2 v[34:35], v141, s[10:11] offset:0 nt
	global_load_dwordx2 v[36:37], v141, s[10:11] offset:512 nt
	global_load_dwordx2 v[38:39], v141, s[10:11] offset:1024 nt
	global_load_dwordx2 v[40:41], v141, s[10:11] offset:1536 nt
	global_load_dwordx2 v[42:43], v141, s[10:11] offset:2048 nt
	global_load_dwordx2 v[44:45], v141, s[10:11] offset:2560 nt
	global_load_dwordx2 v[46:47], v141, s[10:11] offset:3072 nt
	global_load_dwordx2 v[48:49], v141, s[10:11] offset:3584 nt
	s_cmp_lt_u32 s0, 14
	s_cbranch_scc0 .Lrm4_nopf_o
	s_lshr_b32 s1, s3, 9
	s_lshl_b32 s1, s1, 13
	s_and_b32 s6, s3, 0x1ff
	s_add_u32 s1, s1, s6
	s_add_u32 s6, s0, 2
	s_lshl_b32 s6, s6, 9
	s_add_u32 s1, s1, s6
	s_lshl_b32 s6, s1, 13
	s_add_u32 s4, s58, s6
	s_addc_u32 s5, s59, 0
	global_load_dwordx4 v[0:3], v4, s[4:5] offset:0 nt
	global_load_dwordx4 v[6:9], v4, s[4:5] offset:1024 nt
	global_load_dwordx4 v[10:13], v4, s[4:5] offset:2048 nt
	global_load_dwordx4 v[14:17], v4, s[4:5] offset:3072 nt
	global_load_dwordx4 v[18:21], v140, s[4:5] offset:0 nt
	global_load_dwordx4 v[22:25], v140, s[4:5] offset:1024 nt
	global_load_dwordx4 v[26:29], v140, s[4:5] offset:2048 nt
	global_load_dwordx4 v[30:33], v140, s[4:5] offset:3072 nt
	s_waitcnt vmcnt(8)
	s_branch .Lrm4_pfd_o

.Lrm4_pfd_o:
	v_lshlrev_b32_e32 v114, 16, v34
	v_and_b32_e32 v115, 0xffff0000, v34
	v_pk_mul_f32 v[126:127], v[114:115], v[114:115]
	v_lshlrev_b32_e32 v116, 16, v35
	v_and_b32_e32 v117, 0xffff0000, v35
	v_pk_mul_f32 v[128:129], v[116:117], v[116:117]
	v_lshlrev_b32_e32 v118, 16, v36
	v_and_b32_e32 v119, 0xffff0000, v36
	v_pk_fma_f32 v[126:127], v[118:119], v[118:119], v[126:127]
	v_lshlrev_b32_e32 v120, 16, v37
	v_and_b32_e32 v121, 0xffff0000, v37
	v_pk_fma_f32 v[128:129], v[120:121], v[120:121], v[128:129]
	v_lshlrev_b32_e32 v114, 16, v38
	v_and_b32_e32 v115, 0xffff0000, v38
	v_pk_fma_f32 v[126:127], v[114:115], v[114:115], v[126:127]
	v_lshlrev_b32_e32 v116, 16, v39
	v_and_b32_e32 v117, 0xffff0000, v39
	v_pk_fma_f32 v[128:129], v[116:117], v[116:117], v[128:129]
	v_lshlrev_b32_e32 v118, 16, v40
	v_and_b32_e32 v119, 0xffff0000, v40
	v_pk_fma_f32 v[126:127], v[118:119], v[118:119], v[126:127]
	v_lshlrev_b32_e32 v120, 16, v41
	v_and_b32_e32 v121, 0xffff0000, v41
	v_pk_fma_f32 v[128:129], v[120:121], v[120:121], v[128:129]
	v_lshlrev_b32_e32 v114, 16, v42
	v_and_b32_e32 v115, 0xffff0000, v42
	v_pk_fma_f32 v[126:127], v[114:115], v[114:115], v[126:127]
	v_lshlrev_b32_e32 v116, 16, v43
	v_and_b32_e32 v117, 0xffff0000, v43
	v_pk_fma_f32 v[128:129], v[116:117], v[116:117], v[128:129]
	v_lshlrev_b32_e32 v118, 16, v44
	v_and_b32_e32 v119, 0xffff0000, v44
	v_pk_fma_f32 v[126:127], v[118:119], v[118:119], v[126:127]
	v_lshlrev_b32_e32 v120, 16, v45
	v_and_b32_e32 v121, 0xffff0000, v45
	v_pk_fma_f32 v[128:129], v[120:121], v[120:121], v[128:129]
	v_lshlrev_b32_e32 v114, 16, v46
	v_and_b32_e32 v115, 0xffff0000, v46
	v_pk_fma_f32 v[126:127], v[114:115], v[114:115], v[126:127]
	v_lshlrev_b32_e32 v116, 16, v47
	v_and_b32_e32 v117, 0xffff0000, v47
	v_pk_fma_f32 v[128:129], v[116:117], v[116:117], v[128:129]
	v_lshlrev_b32_e32 v118, 16, v48
	v_and_b32_e32 v119, 0xffff0000, v48
	v_pk_fma_f32 v[126:127], v[118:119], v[118:119], v[126:127]
	v_lshlrev_b32_e32 v120, 16, v49
	v_and_b32_e32 v121, 0xffff0000, v49
	v_pk_fma_f32 v[128:129], v[120:121], v[120:121], v[128:129]
	v_pk_add_f32 v[126:127], v[126:127], v[128:129]
	s_nop 0
	v_add_f32_e32 v145, v126, v127
	s_nop 1
	v_add_f32_dpp v145, v145, v145 quad_perm:[1,0,3,2] row_mask:0xf bank_mask:0xf
	s_nop 1
	v_add_f32_dpp v145, v145, v145 quad_perm:[2,3,0,1] row_mask:0xf bank_mask:0xf
	s_nop 1
	v_add_f32_dpp v145, v145, v145 row_half_mirror row_mask:0xf bank_mask:0xf
	s_nop 1
	v_add_f32_dpp v145, v145, v145 row_mirror row_mask:0xf bank_mask:0xf
	s_nop 1
	v_add_f32_dpp v145, v145, v145 row_bcast:15 row_mask:0xa bank_mask:0xf
	s_nop 1
	v_add_f32_dpp v145, v145, v145 row_bcast:31 row_mask:0xc bank_mask:0xf
	s_nop 1
	v_readlane_b32 s6, v145, 63
	s_nop 3
	v_mov_b32_e32 v130, s6
	v_fma_f32 v130, v130, v143, v144
	v_rsq_f32_e32 v130, v130
	s_nop 1
	v_lshlrev_b32_e32 v114, 16, v34
	v_and_b32_e32 v115, 0xffff0000, v34
	v_pk_mul_f32 v[114:115], v[114:115], v[130:131] op_sel_hi:[1,0]
	v_pk_fma_f32 v[148:149], v[50:51], v[114:115], v[148:149]
	v_lshlrev_b32_e32 v116, 16, v35
	v_and_b32_e32 v117, 0xffff0000, v35
	v_pk_mul_f32 v[116:117], v[116:117], v[130:131] op_sel_hi:[1,0]
	v_pk_fma_f32 v[150:151], v[52:53], v[116:117], v[150:151]
	v_lshlrev_b32_e32 v118, 16, v36
	v_and_b32_e32 v119, 0xffff0000, v36
	v_pk_mul_f32 v[118:119], v[118:119], v[130:131] op_sel_hi:[1,0]
	v_pk_fma_f32 v[152:153], v[54:55], v[118:119], v[152:153]
	v_lshlrev_b32_e32 v120, 16, v37
	v_and_b32_e32 v121, 0xffff0000, v37
	v_pk_mul_f32 v[120:121], v[120:121], v[130:131] op_sel_hi:[1,0]
	v_pk_fma_f32 v[154:155], v[56:57], v[120:121], v[154:155]
	v_lshlrev_b32_e32 v114, 16, v38
	v_and_b32_e32 v115, 0xffff0000, v38
	v_pk_mul_f32 v[114:115], v[114:115], v[130:131] op_sel_hi:[1,0]
	v_pk_fma_f32 v[156:157], v[58:59], v[114:115], v[156:157]
	v_lshlrev_b32_e32 v116, 16, v39
	v_and_b32_e32 v117, 0xffff0000, v39
	v_pk_mul_f32 v[116:117], v[116:117], v[130:131] op_sel_hi:[1,0]
	v_pk_fma_f32 v[158:159], v[60:61], v[116:117], v[158:159]
	v_lshlrev_b32_e32 v118, 16, v40
	v_and_b32_e32 v119, 0xffff0000, v40
	v_pk_mul_f32 v[118:119], v[118:119], v[130:131] op_sel_hi:[1,0]
	v_pk_fma_f32 v[160:161], v[62:63], v[118:119], v[160:161]
	v_lshlrev_b32_e32 v120, 16, v41
	v_and_b32_e32 v121, 0xffff0000, v41
	v_pk_mul_f32 v[120:121], v[120:121], v[130:131] op_sel_hi:[1,0]
	v_pk_fma_f32 v[162:163], v[64:65], v[120:121], v[162:163]
	v_lshlrev_b32_e32 v114, 16, v42
	v_and_b32_e32 v115, 0xffff0000, v42
	v_pk_mul_f32 v[114:115], v[114:115], v[130:131] op_sel_hi:[1,0]
	v_pk_fma_f32 v[174:175], v[66:67], v[114:115], v[174:175]
	v_lshlrev_b32_e32 v116, 16, v43
	v_and_b32_e32 v117, 0xffff0000, v43
	v_pk_mul_f32 v[116:117], v[116:117], v[130:131] op_sel_hi:[1,0]
	v_pk_fma_f32 v[176:177], v[68:69], v[116:117], v[176:177]
	v_lshlrev_b32_e32 v118, 16, v44
	v_and_b32_e32 v119, 0xffff0000, v44
	v_pk_mul_f32 v[118:119], v[118:119], v[130:131] op_sel_hi:[1,0]
	v_pk_fma_f32 v[178:179], v[70:71], v[118:119], v[178:179]
	v_lshlrev_b32_e32 v120, 16, v45
	v_and_b32_e32 v121, 0xffff0000, v45
	v_pk_mul_f32 v[120:121], v[120:121], v[130:131] op_sel_hi:[1,0]
	v_pk_fma_f32 v[180:181], v[72:73], v[120:121], v[180:181]
	v_lshlrev_b32_e32 v114, 16, v46
	v_and_b32_e32 v115, 0xffff0000, v46
	v_pk_mul_f32 v[114:115], v[114:115], v[130:131] op_sel_hi:[1,0]
	v_pk_fma_f32 v[182:183], v[74:75], v[114:115], v[182:183]
	v_lshlrev_b32_e32 v116, 16, v47
	v_and_b32_e32 v117, 0xffff0000, v47
	v_pk_mul_f32 v[116:117], v[116:117], v[130:131] op_sel_hi:[1,0]
	v_pk_fma_f32 v[184:185], v[76:77], v[116:117], v[184:185]
	v_lshlrev_b32_e32 v118, 16, v48
	v_and_b32_e32 v119, 0xffff0000, v48
	v_pk_mul_f32 v[118:119], v[118:119], v[130:131] op_sel_hi:[1,0]
	v_pk_fma_f32 v[192:193], v[78:79], v[118:119], v[192:193]
	v_lshlrev_b32_e32 v120, 16, v49
	v_and_b32_e32 v121, 0xffff0000, v49
	v_pk_mul_f32 v[120:121], v[120:121], v[130:131] op_sel_hi:[1,0]
	v_pk_fma_f32 v[194:195], v[80:81], v[120:121], v[194:195]
	s_nop 0
	global_store_dwordx4 v4, v[148:151], s[8:9] offset:0 nt
	global_store_dwordx4 v4, v[152:155], s[8:9] offset:1024 nt
	global_store_dwordx4 v4, v[156:159], s[8:9] offset:2048 nt
	global_store_dwordx4 v4, v[160:163], s[8:9] offset:3072 nt
	global_store_dwordx4 v140, v[174:177], s[8:9] offset:0 nt
	global_store_dwordx4 v140, v[178:181], s[8:9] offset:1024 nt
	global_store_dwordx4 v140, v[182:185], s[8:9] offset:2048 nt
	global_store_dwordx4 v140, v[192:195], s[8:9] offset:3072 nt
	s_add_u32 s0, s0, 2
	s_cmp_lt_u32 s0, 16
	s_cbranch_scc1 .Lrm4_loop
	s_branch .Lrm4_done

.Lrm4_orig:
	v_lshlrev_b32_e32 v3, 2, v189
	v_and_b32_e32 v34, 0xfc, v3
	v_lshlrev_b32_e32 v4, 1, v34
	s_mov_b64 s[0:1], 0x2000
	v_lshl_add_u64 v[6:7], s[64:65], 0, v[4:5]
	v_lshlrev_b32_e32 v4, 2, v34
	v_or_b32_e32 v32, 0x400, v34
	v_or_b32_e32 v30, 0x500, v34
	v_or_b32_e32 v28, 0x600, v34
	v_or_b32_e32 v36, 0x700, v34
	s_waitcnt vmcnt(0)
	v_lshl_add_u64 v[0:1], v[0:1], 0, s[0:1]
	v_or_b32_e32 v10, 0x400, v4
	v_mov_b32_e32 v11, v5
	v_or_b32_e32 v12, 0x800, v4
	v_mov_b32_e32 v13, v5
	v_or_b32_e32 v14, 0xc00, v4
	v_mov_b32_e32 v15, v5
	v_lshlrev_b32_e32 v16, 2, v32
	v_mov_b32_e32 v17, v5
	v_lshlrev_b32_e32 v18, 2, v30
	v_mov_b32_e32 v19, v5
	v_lshlrev_b32_e32 v20, 2, v28
	v_mov_b32_e32 v21, v5
	v_lshlrev_b32_e32 v22, 2, v36
	v_mov_b32_e32 v23, v5
	v_lshl_add_u64 v[8:9], v[0:1], 0, v[4:5]
	v_lshl_add_u64 v[10:11], v[0:1], 0, v[10:11]
	v_lshl_add_u64 v[12:13], v[0:1], 0, v[12:13]
	v_lshl_add_u64 v[14:15], v[0:1], 0, v[14:15]
	v_lshl_add_u64 v[16:17], v[0:1], 0, v[16:17]
	v_lshl_add_u64 v[18:19], v[0:1], 0, v[18:19]
	v_lshl_add_u64 v[20:21], v[0:1], 0, v[20:21]
	v_lshl_add_u64 v[22:23], v[0:1], 0, v[22:23]
	v_mbcnt_hi_u32_b32 v0, -1, v190
	v_and_b32_e32 v1, 64, v0
	v_add_u32_e32 v1, 64, v1
	v_xor_b32_e32 v3, 32, v0
	v_cmp_lt_i32_e32 vcc, v3, v1
	s_add_u32 s4, s52, 0x3d846000
	s_addc_u32 s5, s53, 0
	v_cndmask_b32_e32 v3, v0, v3, vcc
	v_lshlrev_b32_e32 v108, 2, v3
	v_xor_b32_e32 v3, 16, v0
	v_cmp_lt_i32_e32 vcc, v3, v1
	s_cmp_lg_u64 s[58:59], 0
	s_cselect_b64 s[0:1], -1, 0
	v_cndmask_b32_e32 v3, v0, v3, vcc
	v_lshlrev_b32_e32 v109, 2, v3
	v_xor_b32_e32 v3, 8, v0
	v_cmp_lt_i32_e32 vcc, v3, v1
	s_mov_b64 s[6:7], 0
	v_lshl_add_u64 v[24:25], s[58:59], 0, v[4:5]
	v_cndmask_b32_e32 v3, v0, v3, vcc
	v_lshlrev_b32_e32 v110, 2, v3
	v_xor_b32_e32 v3, 4, v0
	v_cmp_lt_i32_e32 vcc, v3, v1
	s_lshl_b32 s9, s54, 4
	v_lshlrev_b32_e32 v4, 2, v36
	v_cndmask_b32_e32 v3, v0, v3, vcc
	v_lshlrev_b32_e32 v111, 2, v3
	v_xor_b32_e32 v3, 2, v0
	v_cmp_lt_i32_e32 vcc, v3, v1
	s_movk_i32 s10, 0x1000
	s_mov_b32 s8, 0x3a000000
	v_cndmask_b32_e32 v3, v0, v3, vcc
	v_lshlrev_b32_e32 v112, 2, v3
	v_xor_b32_e32 v3, 1, v0
	v_cmp_lt_i32_e32 vcc, v3, v1
	s_mov_b32 s11, 0x800000
	v_lshlrev_b32_e32 v28, 2, v28
	v_cndmask_b32_e32 v0, v0, v3, vcc
	v_lshlrev_b32_e32 v113, 2, v0
	v_lshlrev_b32_e32 v0, 1, v2
	v_lshl_add_u32 v26, s33, 4, v0
	v_cndmask_b32_e64 v0, 0, 1, s[0:1]
	v_lshlrev_b32_e32 v30, 2, v30
	v_lshlrev_b32_e32 v32, 2, v32
	s_movk_i32 s12, 0x2000
	v_lshlrev_b32_e32 v34, 2, v34
	s_movk_i32 s13, 0x3fff
	v_cmp_ne_u32_e64 s[0:1], 1, v0
	v_mov_b32_e32 v36, 0x358637bd
	s_branch .LBB0_2144
